# nt (streaming) hint on epilogue 16B stores whose data is still in the accumulator registers (f32 residual stream / bf16 in place) + S5 + LRU edits
# baseline (speedup 1.0000x reference)
; __device__ __forceinline__ float ssq4(const f32x4 o) { return (o[0] * o[0] + o[1] * o[1]) + (o[2] * o[2] + o[3] * o[3]); }
;     __device__ __forceinline__ void operator()(f32x4 (&acc)[2][2][4][2], const Unit& u, int wr, int wc, int fr, int fq) const {
;     ...
;         f32x4 cur[2][4], nxt[2][4];
; #pragma unroll
;         for (int q = 0; q < 2; ++q)
; #pragma unroll
;             for (int c = 0; c < 4; ++c) cur[q][c] = *(const f32x4*)(base + (size_t)EPI_ROW(q) * D + col0 + (c >> 1) * HALF + (c & 1) * 4);
; #pragma unroll
;         for (int k = 0; k < 4; ++k) {
;             if (k < 3) {
; #pragma unroll
;                 for (int q = 0; q < 2; ++q)
; #pragma unroll
;                     for (int c = 0; c < 4; ++c) nxt[q][c] = *(const f32x4*)(base + (size_t)EPI_ROW(2 * k + 2 + q) * D + col0 + (c >> 1) * HALF + (c & 1) * 4);
;             }
;             asm volatile("" ::: "memory");
; #pragma unroll
;             for (int q = 0; q < 2; ++q) { const int r = 2 * k + q, ai = r >> 2, m = r & 3; const size_t off = (size_t)EPI_ROW(r) * D + col0; float sr = 0.f;
; #pragma unroll
;                 for (int bj = 0; bj < 2; ++bj) { const f32x4 o0 = cur[q][2 * bj] + acc[ai][bj][m][0], o1 = cur[q][2 * bj + 1] + acc[ai][bj][m][1];
;                     *(f32x4*)(out + off + bj * HALF) = o0; *(f32x4*)(out + off + bj * HALF + 4) = o1;
;                     u32x4 w; w.x = cvt_pk_bf16(o0[0], o0[1]); w.y = cvt_pk_bf16(o0[2], o0[3]); w.z = cvt_pk_bf16(o1[0], o1[1]); w.w = cvt_pk_bf16(o1[2], o1[3]); *(u32x4*)(hb + off + bj * HALF) = w; sr += ssq4(o0) + ssq4(o1); }
;                 s[ai][m] = sr; }
.LBB0_1013:
	v_mov_b32_e32 v185, v246
	s_lshl_b32 s1, s6, 8
	s_or_b32 s1, s1, s42
	v_bfe_u32 v184, v185, 4, 2
	v_lshl_or_b32 v200, v184, 3, s1
	s_lshl_b32 s1, s24, 8
	v_and_b32_e32 v183, 15, v185
	s_add_i32 s3, s1, s35
	v_or_b32_e32 v202, s3, v183
	v_readlane_b32 s14, v255, 40
	v_ashrrev_i32_e32 v203, 31, v202
	v_ashrrev_i32_e32 v201, 31, v200
	v_readlane_b32 s15, v255, 41
	v_lshlrev_b64 v[130:131], 13, v[202:203]
	v_or_b32_e32 v178, 16, v202
	v_lshl_add_u64 v[204:205], v[200:201], 2, s[14:15]
	v_lshl_add_u64 v[130:131], v[204:205], 0, v[130:131]
	global_load_dwordx4 v[210:213], v[130:131], off offset:16
	global_load_dwordx4 v[214:217], v[130:131], off
	global_load_dwordx4 v[218:221], v[130:131], off offset:528
	global_load_dwordx4 v[222:225], v[130:131], off offset:512
	v_ashrrev_i32_e32 v179, 31, v178
	v_lshlrev_b64 v[130:131], 13, v[178:179]
	v_lshl_add_u64 v[130:131], v[204:205], 0, v[130:131]
	global_load_dwordx4 v[170:173], v[130:131], off offset:16
	global_load_dwordx4 v[174:177], v[130:131], off
	global_load_dwordx4 v[162:165], v[130:131], off offset:528
	global_load_dwordx4 v[166:169], v[130:131], off offset:512
	v_or_b32_e32 v208, 32, v202
	v_ashrrev_i32_e32 v209, 31, v208
	v_lshlrev_b64 v[130:131], 13, v[208:209]
	v_lshl_add_u64 v[130:131], v[204:205], 0, v[130:131]
	v_or_b32_e32 v206, 48, v202
	global_load_dwordx4 v[154:157], v[130:131], off offset:16
	global_load_dwordx4 v[158:161], v[130:131], off
	global_load_dwordx4 v[138:141], v[130:131], off offset:528
	global_load_dwordx4 v[142:145], v[130:131], off offset:512
	v_ashrrev_i32_e32 v207, 31, v206
	v_lshlrev_b64 v[130:131], 13, v[206:207]
	v_lshl_add_u64 v[134:135], v[204:205], 0, v[130:131]
	global_load_dwordx4 v[146:149], v[134:135], off offset:16
	global_load_dwordx4 v[150:153], v[134:135], off
	global_load_dwordx4 v[130:133], v[134:135], off offset:528
	s_nop 0
	global_load_dwordx4 v[134:137], v[134:135], off offset:512
	v_lshlrev_b64 v[226:227], 11, v[202:203]
	v_lshl_add_u64 v[226:227], v[226:227], 0, v[200:201]
	v_lshlrev_b64 v[208:209], 11, v[208:209]
	v_lshl_add_u64 v[208:209], v[208:209], 0, v[200:201]
	v_cmp_eq_u32_e32 vcc, 0, v184
	s_waitcnt vmcnt(0)
	v_pk_add_f32 v[122:123], v[122:123], v[210:211]
	v_pk_add_f32 v[128:129], v[128:129], v[216:217]
	v_pk_add_f32 v[126:127], v[126:127], v[214:215]
	v_lshl_add_u64 v[214:215], v[226:227], 2, s[36:37]
	v_pk_add_f32 v[124:125], v[124:125], v[212:213]
	global_store_dwordx4 v[214:215], v[126:129], off nt
	global_store_dwordx4 v[214:215], v[122:125], off offset:16 nt
	v_cvt_pk_bf16_f32 v210, v126, v127
	v_cvt_pk_bf16_f32 v212, v122, v123
	v_mul_f32_e32 v127, v127, v127
	v_mul_f32_e32 v123, v123, v123
	v_fmac_f32_e32 v127, v126, v126
	v_mul_f32_e32 v126, v129, v129
	v_fmac_f32_e32 v123, v122, v122
	v_mul_f32_e32 v122, v125, v125
	v_fmac_f32_e32 v126, v128, v128
	v_fmac_f32_e32 v122, v124, v124
	v_cvt_pk_bf16_f32 v211, v128, v129
	v_cvt_pk_bf16_f32 v213, v124, v125
	v_lshl_add_u64 v[216:217], v[226:227], 1, s[54:55]
	v_add_f32_e32 v126, v127, v126
	v_add_f32_e32 v122, v123, v122
	v_pk_add_f32 v[120:121], v[120:121], v[224:225]
	v_pk_add_f32 v[118:119], v[118:119], v[222:223]
	v_pk_add_f32 v[114:115], v[114:115], v[218:219]
	global_store_dwordx4 v[216:217], v[210:213], off
	v_add_f32_e32 v126, v126, v122
	v_pk_add_f32 v[116:117], v[116:117], v[220:221]
	global_store_dwordx4 v[214:215], v[118:121], off offset:512 nt
	global_store_dwordx4 v[214:215], v[114:117], off offset:528 nt
	v_cvt_pk_bf16_f32 v122, v118, v119
	v_cvt_pk_bf16_f32 v124, v114, v115
	v_mul_f32_e32 v119, v119, v119
	v_mul_f32_e32 v115, v115, v115
	v_fmac_f32_e32 v119, v118, v118
	v_mul_f32_e32 v118, v121, v121
	v_fmac_f32_e32 v115, v114, v114
	v_mul_f32_e32 v114, v117, v117
	v_fmac_f32_e32 v118, v120, v120
	v_fmac_f32_e32 v114, v116, v116
	v_add_f32_e32 v118, v119, v118
	v_add_f32_e32 v114, v115, v114
	v_add_f32_e32 v114, v118, v114
	v_add_f32_e32 v187, v126, v114
	v_lshlrev_b64 v[114:115], 11, v[178:179]
	v_lshl_add_u64 v[118:119], v[114:115], 0, v[200:201]
	v_pk_add_f32 v[112:113], v[112:113], v[176:177]
	v_pk_add_f32 v[110:111], v[110:111], v[174:175]
	v_pk_add_f32 v[108:109], v[108:109], v[172:173]
	v_pk_add_f32 v[106:107], v[106:107], v[170:171]
	v_cvt_pk_bf16_f32 v123, v120, v121
	v_cvt_pk_bf16_f32 v125, v116, v117
	v_lshl_add_u64 v[120:121], v[118:119], 2, s[36:37]
	v_cvt_pk_bf16_f32 v114, v110, v111
	v_cvt_pk_bf16_f32 v115, v112, v113
	v_cvt_pk_bf16_f32 v116, v106, v107
	v_cvt_pk_bf16_f32 v117, v108, v109
	v_lshl_add_u64 v[118:119], v[118:119], 1, s[54:55]
	v_pk_add_f32 v[104:105], v[104:105], v[168:169]
	v_pk_add_f32 v[102:103], v[102:103], v[166:167]
	v_pk_add_f32 v[100:101], v[100:101], v[164:165]
	v_pk_add_f32 v[98:99], v[98:99], v[162:163]
	v_add_u32_e32 v210, 0x80, v202
	global_store_dwordx4 v[216:217], v[122:125], off offset:256 nt
	global_store_dwordx4 v[120:121], v[110:113], off nt
	global_store_dwordx4 v[120:121], v[106:109], off offset:16 nt
	global_store_dwordx4 v[118:119], v[114:117], off nt
	v_ashrrev_i32_e32 v211, 31, v210
	global_store_dwordx4 v[120:121], v[102:105], off offset:512 nt
	global_store_dwordx4 v[120:121], v[98:101], off offset:528 nt
	v_cvt_pk_bf16_f32 v114, v102, v103
	v_cvt_pk_bf16_f32 v115, v104, v105
	v_cvt_pk_bf16_f32 v116, v98, v99
	v_cvt_pk_bf16_f32 v117, v100, v101
	global_store_dwordx4 v[118:119], v[114:117], off offset:256 nt
	v_add_u32_e32 v170, 0x90, v202
	v_ashrrev_i32_e32 v171, 31, v170
	v_lshlrev_b64 v[114:115], 13, v[210:211]
	v_lshl_add_u64 v[114:115], v[204:205], 0, v[114:115]
	global_load_dwordx4 v[172:175], v[114:115], off offset:16
	global_load_dwordx4 v[176:179], v[114:115], off
; __device__ __forceinline__ float ssq4(const f32x4 o) { return (o[0] * o[0] + o[1] * o[1]) + (o[2] * o[2] + o[3] * o[3]); }
;     __device__ __forceinline__ void operator()(f32x4 (&acc)[2][2][4][2], const Unit& u, int wr, int wc, int fr, int fq) const {
;     ...
;         for (int k = 0; k < 4; ++k) {
;             if (k < 3) {
; #pragma unroll
;                 for (int q = 0; q < 2; ++q)
; #pragma unroll
;                     for (int c = 0; c < 4; ++c) nxt[q][c] = *(const f32x4*)(base + (size_t)EPI_ROW(2 * k + 2 + q) * D + col0 + (c >> 1) * HALF + (c & 1) * 4);
;             }
;             asm volatile("" ::: "memory");
; #pragma unroll
;             for (int q = 0; q < 2; ++q) { const int r = 2 * k + q, ai = r >> 2, m = r & 3; const size_t off = (size_t)EPI_ROW(r) * D + col0; float sr = 0.f;
; #pragma unroll
;                 for (int bj = 0; bj < 2; ++bj) { const f32x4 o0 = cur[q][2 * bj] + acc[ai][bj][m][0], o1 = cur[q][2 * bj + 1] + acc[ai][bj][m][1];
;                     *(f32x4*)(out + off + bj * HALF) = o0; *(f32x4*)(out + off + bj * HALF + 4) = o1;
;                     u32x4 w; w.x = cvt_pk_bf16(o0[0], o0[1]); w.y = cvt_pk_bf16(o0[2], o0[3]); w.z = cvt_pk_bf16(o1[0], o1[1]); w.w = cvt_pk_bf16(o1[2], o1[3]); *(u32x4*)(hb + off + bj * HALF) = w; sr += ssq4(o0) + ssq4(o1); }
;                 s[ai][m] = sr; }
	global_load_dwordx4 v[162:165], v[114:115], off offset:528
	global_load_dwordx4 v[166:169], v[114:115], off offset:512
	v_lshlrev_b64 v[114:115], 13, v[170:171]
	v_pk_add_f32 v[96:97], v[96:97], v[160:161]
	v_pk_add_f32 v[94:95], v[94:95], v[158:159]
	v_pk_add_f32 v[92:93], v[92:93], v[156:157]
	v_pk_add_f32 v[90:91], v[90:91], v[154:155]
	v_pk_add_f32 v[88:89], v[88:89], v[144:145]
	v_pk_add_f32 v[86:87], v[86:87], v[142:143]
	v_pk_add_f32 v[80:81], v[80:81], v[140:141]
	v_pk_add_f32 v[78:79], v[78:79], v[138:139]
	v_lshl_add_u64 v[118:119], v[204:205], 0, v[114:115]
	v_lshl_add_u64 v[158:159], v[208:209], 2, s[36:37]
	v_cvt_pk_bf16_f32 v154, v94, v95
	v_cvt_pk_bf16_f32 v155, v96, v97
	v_cvt_pk_bf16_f32 v156, v90, v91
	v_cvt_pk_bf16_f32 v157, v92, v93
	v_lshl_add_u64 v[160:161], v[208:209], 1, s[54:55]
	v_cvt_pk_bf16_f32 v138, v86, v87
	v_cvt_pk_bf16_f32 v139, v88, v89
	v_cvt_pk_bf16_f32 v140, v78, v79
	v_cvt_pk_bf16_f32 v141, v80, v81
	global_load_dwordx4 v[122:125], v[118:119], off offset:16
	global_load_dwordx4 v[126:129], v[118:119], off
	global_load_dwordx4 v[114:117], v[118:119], off offset:528
	s_nop 0
	global_load_dwordx4 v[118:121], v[118:119], off offset:512
	global_store_dwordx4 v[158:159], v[94:97], off nt
	global_store_dwordx4 v[158:159], v[90:93], off offset:16 nt
	global_store_dwordx4 v[160:161], v[154:157], off
	global_store_dwordx4 v[158:159], v[86:89], off offset:512 nt
	global_store_dwordx4 v[158:159], v[78:81], off offset:528 nt
	global_store_dwordx4 v[160:161], v[138:141], off offset:256
	v_pk_add_f32 v[84:85], v[84:85], v[152:153]
	v_pk_add_f32 v[82:83], v[82:83], v[150:151]
	v_lshlrev_b64 v[138:139], 11, v[206:207]
	v_lshl_add_u64 v[142:143], v[138:139], 0, v[200:201]
	v_pk_add_f32 v[76:77], v[76:77], v[148:149]
	v_pk_add_f32 v[74:75], v[74:75], v[146:147]
	v_pk_add_f32 v[72:73], v[72:73], v[136:137]
	v_pk_add_f32 v[70:71], v[70:71], v[134:135]
	v_pk_add_f32 v[68:69], v[68:69], v[132:133]
	v_pk_add_f32 v[66:67], v[66:67], v[130:131]
	v_add_u32_e32 v206, 0xa0, v202
	v_lshl_add_u64 v[144:145], v[142:143], 2, s[36:37]
	v_cvt_pk_bf16_f32 v138, v82, v83
	v_cvt_pk_bf16_f32 v139, v84, v85
	v_cvt_pk_bf16_f32 v140, v74, v75
	v_cvt_pk_bf16_f32 v141, v76, v77
	v_lshl_add_u64 v[142:143], v[142:143], 1, s[54:55]
	v_cvt_pk_bf16_f32 v130, v70, v71
	v_cvt_pk_bf16_f32 v131, v72, v73
	v_cvt_pk_bf16_f32 v132, v66, v67
	v_cvt_pk_bf16_f32 v133, v68, v69
	v_ashrrev_i32_e32 v207, 31, v206
	global_store_dwordx4 v[144:145], v[82:85], off nt
	global_store_dwordx4 v[144:145], v[74:77], off offset:16 nt
	global_store_dwordx4 v[142:143], v[138:141], off
	global_store_dwordx4 v[144:145], v[70:73], off offset:512 nt
	global_store_dwordx4 v[144:145], v[66:69], off offset:528 nt
	global_store_dwordx4 v[142:143], v[130:133], off offset:256
	v_add_u32_e32 v202, 0xb0, v202
	v_ashrrev_i32_e32 v203, 31, v202
	v_lshlrev_b64 v[130:131], 13, v[206:207]
	v_lshl_add_u64 v[142:143], v[204:205], 0, v[130:131]
	global_load_dwordx4 v[130:133], v[142:143], off offset:16
	global_load_dwordx4 v[134:137], v[142:143], off
	global_load_dwordx4 v[138:141], v[142:143], off offset:528
	s_nop 0
	global_load_dwordx4 v[142:145], v[142:143], off offset:512
	v_lshlrev_b64 v[146:147], 13, v[202:203]
	v_lshl_add_u64 v[158:159], v[204:205], 0, v[146:147]
	global_load_dwordx4 v[146:149], v[158:159], off offset:16
	global_load_dwordx4 v[150:153], v[158:159], off
	global_load_dwordx4 v[154:157], v[158:159], off offset:528
	s_nop 0
	global_load_dwordx4 v[158:161], v[158:159], off offset:512
	v_lshlrev_b64 v[204:205], 11, v[210:211]
	v_lshl_add_u64 v[204:205], v[204:205], 0, v[200:201]
	s_waitcnt vmcnt(27)
	v_pk_add_f32 v[60:61], v[60:61], v[174:175]
	s_waitcnt vmcnt(26)
	v_pk_add_f32 v[64:65], v[64:65], v[178:179]
	v_pk_add_f32 v[62:63], v[62:63], v[176:177]
	v_pk_add_f32 v[58:59], v[58:59], v[172:173]
	s_waitcnt vmcnt(24)
	v_pk_add_f32 v[56:57], v[56:57], v[168:169]
	v_pk_add_f32 v[54:55], v[54:55], v[166:167]
	v_pk_add_f32 v[48:49], v[48:49], v[164:165]
	v_pk_add_f32 v[46:47], v[46:47], v[162:163]
	v_lshl_add_u64 v[176:177], v[204:205], 2, s[36:37]
	v_cvt_pk_bf16_f32 v172, v62, v63
	v_cvt_pk_bf16_f32 v173, v64, v65
	v_cvt_pk_bf16_f32 v174, v58, v59
	v_cvt_pk_bf16_f32 v175, v60, v61
	v_lshl_add_u64 v[178:179], v[204:205], 1, s[54:55]
	v_cvt_pk_bf16_f32 v162, v54, v55
	v_cvt_pk_bf16_f32 v163, v56, v57
	v_cvt_pk_bf16_f32 v164, v46, v47
	v_cvt_pk_bf16_f32 v165, v48, v49
	global_store_dwordx4 v[176:177], v[62:65], off nt
	global_store_dwordx4 v[176:177], v[58:61], off offset:16 nt
	global_store_dwordx4 v[178:179], v[172:175], off
	global_store_dwordx4 v[176:177], v[54:57], off offset:512 nt
	global_store_dwordx4 v[176:177], v[46:49], off offset:528 nt
	global_store_dwordx4 v[178:179], v[162:165], off offset:256
	s_waitcnt vmcnt(28)
; __device__ __forceinline__ float shx(float v, int o, int lane) { return __builtin_bit_cast(float, __builtin_amdgcn_ds_bpermute((lane ^ o) << 2, __builtin_bit_cast(int, v))); }
; __device__ __forceinline__ float ssq4(const f32x4 o) { return (o[0] * o[0] + o[1] * o[1]) + (o[2] * o[2] + o[3] * o[3]); }
; template <bool SIXTEEN> __device__ __forceinline__ void tile_ssq(const float (&s)[2][4], const Unit& u, int wr, int wc, int fr, int fq, float* ssq, LAS float* ptab) {
;     ...
;         for (int m = 0; m < 4; ++m) { float v = s[ai][m]; v += shx(v, 16, lane); v += shx(v, 32, lane); if (fq == 0) ptab[(ai * HALF + wr * 64 + m * 16 + fr) * 4 + wc] = v; }
;     __device__ __forceinline__ void operator()(f32x4 (&acc)[2][2][4][2], const Unit& u, int wr, int wc, int fr, int fq) const {
;     ...
;             for (int q = 0; q < 2; ++q) { const int r = 2 * k + q, ai = r >> 2, m = r & 3; const size_t off = (size_t)EPI_ROW(r) * D + col0; float sr = 0.f;
; #pragma unroll
;                 for (int bj = 0; bj < 2; ++bj) { const f32x4 o0 = cur[q][2 * bj] + acc[ai][bj][m][0], o1 = cur[q][2 * bj + 1] + acc[ai][bj][m][1];
;                     *(f32x4*)(out + off + bj * HALF) = o0; *(f32x4*)(out + off + bj * HALF + 4) = o1;
;                     u32x4 w; w.x = cvt_pk_bf16(o0[0], o0[1]); w.y = cvt_pk_bf16(o0[2], o0[3]); w.z = cvt_pk_bf16(o1[0], o1[1]); w.w = cvt_pk_bf16(o1[2], o1[3]); *(u32x4*)(hb + off + bj * HALF) = w; sr += ssq4(o0) + ssq4(o1); }
;                 s[ai][m] = sr; }
	v_pk_add_f32 v[52:53], v[52:53], v[128:129]
	v_pk_add_f32 v[50:51], v[50:51], v[126:127]
	v_lshlrev_b64 v[162:163], 11, v[170:171]
	v_lshl_add_u64 v[162:163], v[162:163], 0, v[200:201]
	v_pk_add_f32 v[44:45], v[44:45], v[124:125]
	v_pk_add_f32 v[42:43], v[42:43], v[122:123]
	s_waitcnt vmcnt(26)
	v_pk_add_f32 v[40:41], v[40:41], v[120:121]
	v_pk_add_f32 v[38:39], v[38:39], v[118:119]
	v_pk_add_f32 v[36:37], v[36:37], v[116:117]
	v_pk_add_f32 v[34:35], v[34:35], v[114:115]
	v_lshl_add_u64 v[126:127], v[162:163], 2, s[36:37]
	v_cvt_pk_bf16_f32 v122, v50, v51
	v_cvt_pk_bf16_f32 v123, v52, v53
	v_cvt_pk_bf16_f32 v124, v42, v43
	v_cvt_pk_bf16_f32 v125, v44, v45
	v_lshl_add_u64 v[128:129], v[162:163], 1, s[54:55]
	v_cvt_pk_bf16_f32 v114, v38, v39
	v_cvt_pk_bf16_f32 v115, v40, v41
	v_cvt_pk_bf16_f32 v116, v34, v35
	v_cvt_pk_bf16_f32 v117, v36, v37
	global_store_dwordx4 v[126:127], v[50:53], off nt
	global_store_dwordx4 v[126:127], v[42:45], off offset:16 nt
	global_store_dwordx4 v[128:129], v[122:125], off nt
	global_store_dwordx4 v[126:127], v[38:41], off offset:512 nt
	global_store_dwordx4 v[126:127], v[34:37], off offset:528 nt
	global_store_dwordx4 v[128:129], v[114:117], off offset:256 nt
	s_waitcnt vmcnt(19)
	v_pk_add_f32 v[28:29], v[28:29], v[132:133]
	v_lshlrev_b64 v[114:115], 11, v[206:207]
	v_lshl_add_u64 v[118:119], v[114:115], 0, v[200:201]
	s_waitcnt vmcnt(18)
	v_pk_add_f32 v[32:33], v[32:33], v[136:137]
	v_pk_add_f32 v[30:31], v[30:31], v[134:135]
	v_pk_add_f32 v[26:27], v[26:27], v[130:131]
	v_lshl_add_u64 v[120:121], v[118:119], 2, s[36:37]
	v_cvt_pk_bf16_f32 v114, v30, v31
	v_cvt_pk_bf16_f32 v115, v32, v33
	v_cvt_pk_bf16_f32 v116, v26, v27
	v_cvt_pk_bf16_f32 v117, v28, v29
	v_lshl_add_u64 v[118:119], v[118:119], 1, s[54:55]
	s_waitcnt vmcnt(16)
	v_pk_add_f32 v[24:25], v[24:25], v[144:145]
	v_pk_add_f32 v[22:23], v[22:23], v[142:143]
	v_pk_add_f32 v[16:17], v[16:17], v[140:141]
	v_pk_add_f32 v[14:15], v[14:15], v[138:139]
	global_store_dwordx4 v[120:121], v[30:33], off nt
	global_store_dwordx4 v[120:121], v[26:29], off offset:16 nt
	global_store_dwordx4 v[118:119], v[114:117], off nt
	global_store_dwordx4 v[120:121], v[22:25], off offset:512 nt
	global_store_dwordx4 v[120:121], v[14:17], off offset:528 nt
	v_cvt_pk_bf16_f32 v114, v22, v23
	v_cvt_pk_bf16_f32 v115, v24, v25
	v_cvt_pk_bf16_f32 v116, v14, v15
	v_cvt_pk_bf16_f32 v117, v16, v17
	global_store_dwordx4 v[118:119], v[114:117], off offset:256 nt
	s_waitcnt vmcnt(20)
	v_pk_add_f32 v[20:21], v[20:21], v[152:153]
	v_pk_add_f32 v[18:19], v[18:19], v[150:151]
	v_lshlrev_b64 v[114:115], 11, v[202:203]
	v_lshl_add_u64 v[118:119], v[114:115], 0, v[200:201]
	v_pk_add_f32 v[12:13], v[12:13], v[148:149]
	v_pk_add_f32 v[10:11], v[10:11], v[146:147]
	v_lshl_add_u64 v[120:121], v[118:119], 2, s[36:37]
	v_cvt_pk_bf16_f32 v114, v18, v19
	v_cvt_pk_bf16_f32 v115, v20, v21
	v_cvt_pk_bf16_f32 v116, v10, v11
	v_cvt_pk_bf16_f32 v117, v12, v13
	v_lshl_add_u64 v[118:119], v[118:119], 1, s[54:55]
	s_waitcnt vmcnt(18)
	v_pk_add_f32 v[8:9], v[8:9], v[160:161]
	v_pk_add_f32 v[6:7], v[6:7], v[158:159]
	v_pk_add_f32 v[4:5], v[4:5], v[156:157]
	v_pk_add_f32 v[2:3], v[2:3], v[154:155]
	global_store_dwordx4 v[120:121], v[18:21], off nt
	global_store_dwordx4 v[120:121], v[10:13], off offset:16 nt
	global_store_dwordx4 v[118:119], v[114:117], off nt
	global_store_dwordx4 v[120:121], v[6:9], off offset:512 nt
	global_store_dwordx4 v[120:121], v[2:5], off offset:528 nt
	v_cvt_pk_bf16_f32 v114, v6, v7
	v_cvt_pk_bf16_f32 v115, v8, v9
	v_cvt_pk_bf16_f32 v116, v2, v3
	v_cvt_pk_bf16_f32 v117, v4, v5
	global_store_dwordx4 v[118:119], v[114:117], off offset:256 nt
	s_nop 1
	v_and_b32_e32 v114, 63, v185
	v_lshlrev_b32_e32 v115, 2, v114
	v_xor_b32_e32 v116, 64, v115
	ds_bpermute_b32 v117, v116, v187
	v_xor_b32_e32 v115, 0x80, v115
	s_waitcnt lgkmcnt(0)
	v_add_f32_e32 v118, v187, v117
	ds_bpermute_b32 v119, v115, v118
	v_lshl_add_u32 v117, v183, 4, s86
	s_and_saveexec_b64 s[14:15], vcc
	s_cbranch_execz .LBB0_1015
	s_waitcnt lgkmcnt(0)
	v_add_f32_e32 v118, v118, v119
	ds_write_b32 v117, v118

;     __device__ __forceinline__ void operator()(f32x4 (&acc)[2][2][4][2], const Unit& u, int wr, int wc, int fr, int fq) const {
;         const int row0 = u.pm * BM + wr * 64 + fr; const int col0 = u.pn * BM + wc * 32 + 8 * fq;
;         float rsv[8]; if (ssq) rows_rstd(ssq, row0, fr, fq, rsv);
; #pragma unroll
;         for (int ai = 0; ai < 2; ++ai)
; #pragma unroll
;             for (int m = 0; m < 4; ++m) { const int row = row0 + ai * HALF + m * 16; bf16_t* rowp = O + (size_t)row * ldc + col0;
;                 const float rs = ssq ? rsv[ai * 4 + m] : 1.0f;
; #pragma unroll
;                 for (int bj = 0; bj < 2; ++bj) { f32x4 v0 = acc[ai][bj][m][0] * rs, v1 = acc[ai][bj][m][1] * rs;
;                     if (ACT == 2) {
; #pragma unroll
;                         for (int j = 0; j < 4; ++j) { float a = v0[j] > 0.f ? v0[j] : 0.f; v0[j] = a * a; float b = v1[j] > 0.f ? v1[j] : 0.f; v1[j] = b * b; } }
;                     u32x4 w; w.x = cvt_pk_bf16(v0[0], v0[1]); w.y = cvt_pk_bf16(v0[2], v0[3]); w.z = cvt_pk_bf16(v1[0], v1[1]); w.w = cvt_pk_bf16(v1[2], v1[3]);
;                     *(u32x4*)(rowp + bj * HALF) = w; } }
.LBB0_1112:
	s_lshl_b32 s3, s64, 8
	v_lshl_or_b32 v130, v163, 3, s3
	v_or_b32_e32 v130, s75, v130
	v_ashrrev_i32_e32 v131, 31, v130
	v_lshlrev_b64 v[134:135], 12, v[158:159]
	v_lshl_add_u64 v[134:135], s[58:59], 0, v[134:135]
	v_lshlrev_b64 v[136:137], 1, v[130:131]
	v_lshl_add_u64 v[130:131], v[134:135], 0, v[136:137]
	v_cndmask_b32_e64 v134, v166, 1.0, s[92:93]
	v_pk_mul_f32 v[128:129], v[128:129], v[134:135] op_sel_hi:[1,0]
	v_pk_mul_f32 v[126:127], v[126:127], v[134:135] op_sel_hi:[1,0]
	v_pk_mul_f32 v[140:141], v[124:125], v[134:135] op_sel_hi:[1,0]
	v_pk_mul_f32 v[124:125], v[122:123], v[134:135] op_sel_hi:[1,0]
	v_cvt_pk_bf16_f32 v122, v126, v127
	v_cvt_pk_bf16_f32 v123, v128, v129
	v_cvt_pk_bf16_f32 v124, v124, v125
	v_cvt_pk_bf16_f32 v125, v140, v141
	global_store_dwordx4 v[130:131], v[122:125], off nt
	v_pk_mul_f32 v[120:121], v[120:121], v[134:135] op_sel_hi:[1,0]
	v_pk_mul_f32 v[118:119], v[118:119], v[134:135] op_sel_hi:[1,0]
	v_pk_mul_f32 v[122:123], v[112:113], v[134:135] op_sel_hi:[1,0]
	v_pk_mul_f32 v[112:113], v[110:111], v[134:135] op_sel_hi:[1,0]
	v_cvt_pk_bf16_f32 v110, v118, v119
	v_cvt_pk_bf16_f32 v111, v120, v121
	v_cvt_pk_bf16_f32 v112, v112, v113
	v_cvt_pk_bf16_f32 v113, v122, v123
	global_store_dwordx4 v[130:131], v[110:113], off offset:256 nt
	s_mov_b32 s3, 0x80000
	s_mov_b64 s[6:7], 0x80000
	v_or_b32_e32 v110, 16, v158
	v_ashrrev_i32_e32 v111, 31, v110
	v_lshlrev_b64 v[110:111], 12, v[110:111]
	v_cndmask_b32_e64 v112, v164, 1.0, s[92:93]
	v_lshl_add_u64 v[110:111], s[58:59], 0, v[110:111]
	v_pk_mul_f32 v[116:117], v[116:117], v[112:113] op_sel_hi:[1,0]
	v_pk_mul_f32 v[114:115], v[114:115], v[112:113] op_sel_hi:[1,0]
	v_pk_mul_f32 v[118:119], v[108:109], v[112:113] op_sel_hi:[1,0]
	v_pk_mul_f32 v[108:109], v[106:107], v[112:113] op_sel_hi:[1,0]
	v_lshl_add_u64 v[110:111], v[110:111], 0, v[136:137]
	v_cvt_pk_bf16_f32 v106, v114, v115
	v_cvt_pk_bf16_f32 v107, v116, v117
	v_cvt_pk_bf16_f32 v108, v108, v109
	v_cvt_pk_bf16_f32 v109, v118, v119
	global_store_dwordx4 v[110:111], v[106:109], off nt
	v_pk_mul_f32 v[104:105], v[104:105], v[112:113] op_sel_hi:[1,0]
	v_pk_mul_f32 v[102:103], v[102:103], v[112:113] op_sel_hi:[1,0]
	v_pk_mul_f32 v[106:107], v[96:97], v[112:113] op_sel_hi:[1,0]
	v_pk_mul_f32 v[96:97], v[94:95], v[112:113] op_sel_hi:[1,0]
	v_cvt_pk_bf16_f32 v94, v102, v103
	v_cvt_pk_bf16_f32 v95, v104, v105
	v_cvt_pk_bf16_f32 v96, v96, v97
	v_cvt_pk_bf16_f32 v97, v106, v107
	global_store_dwordx4 v[110:111], v[94:97], off offset:256 nt
	s_nop 1
	v_or_b32_e32 v94, 32, v158
	v_ashrrev_i32_e32 v95, 31, v94
	v_lshlrev_b64 v[94:95], 12, v[94:95]
	v_cndmask_b32_e64 v96, v168, 1.0, s[92:93]
	v_lshl_add_u64 v[94:95], s[58:59], 0, v[94:95]
	v_pk_mul_f32 v[100:101], v[100:101], v[96:97] op_sel_hi:[1,0]
	v_pk_mul_f32 v[98:99], v[98:99], v[96:97] op_sel_hi:[1,0]
	v_pk_mul_f32 v[102:103], v[92:93], v[96:97] op_sel_hi:[1,0]
	v_pk_mul_f32 v[92:93], v[90:91], v[96:97] op_sel_hi:[1,0]
	v_lshl_add_u64 v[94:95], v[94:95], 0, v[136:137]
	v_cvt_pk_bf16_f32 v90, v98, v99
	v_cvt_pk_bf16_f32 v91, v100, v101
	v_cvt_pk_bf16_f32 v92, v92, v93
	v_cvt_pk_bf16_f32 v93, v102, v103
	global_store_dwordx4 v[94:95], v[90:93], off nt
	v_pk_mul_f32 v[88:89], v[88:89], v[96:97] op_sel_hi:[1,0]
	v_pk_mul_f32 v[86:87], v[86:87], v[96:97] op_sel_hi:[1,0]
	v_pk_mul_f32 v[90:91], v[80:81], v[96:97] op_sel_hi:[1,0]
	v_pk_mul_f32 v[80:81], v[78:79], v[96:97] op_sel_hi:[1,0]
	v_cvt_pk_bf16_f32 v78, v86, v87
	v_cvt_pk_bf16_f32 v79, v88, v89
	v_cvt_pk_bf16_f32 v80, v80, v81
	v_cvt_pk_bf16_f32 v81, v90, v91
	global_store_dwordx4 v[94:95], v[78:81], off offset:256 nt
	s_nop 1
	v_or_b32_e32 v78, 48, v158
	v_ashrrev_i32_e32 v79, 31, v78
	v_lshlrev_b64 v[78:79], 12, v[78:79]
	v_cndmask_b32_e64 v80, v167, 1.0, s[92:93]
	v_lshl_add_u64 v[78:79], s[58:59], 0, v[78:79]
	v_pk_mul_f32 v[84:85], v[84:85], v[80:81] op_sel_hi:[1,0]
	v_pk_mul_f32 v[82:83], v[82:83], v[80:81] op_sel_hi:[1,0]
	v_pk_mul_f32 v[86:87], v[76:77], v[80:81] op_sel_hi:[1,0]
	v_pk_mul_f32 v[76:77], v[74:75], v[80:81] op_sel_hi:[1,0]
	v_lshl_add_u64 v[78:79], v[78:79], 0, v[136:137]
	v_cvt_pk_bf16_f32 v74, v82, v83
	v_cvt_pk_bf16_f32 v75, v84, v85
	v_cvt_pk_bf16_f32 v76, v76, v77
	v_cvt_pk_bf16_f32 v77, v86, v87
	global_store_dwordx4 v[78:79], v[74:77], off nt
	v_pk_mul_f32 v[72:73], v[72:73], v[80:81] op_sel_hi:[1,0]
	v_pk_mul_f32 v[70:71], v[70:71], v[80:81] op_sel_hi:[1,0]
	v_pk_mul_f32 v[74:75], v[68:69], v[80:81] op_sel_hi:[1,0]
	v_pk_mul_f32 v[68:69], v[66:67], v[80:81] op_sel_hi:[1,0]
	v_cvt_pk_bf16_f32 v66, v70, v71
;     __device__ __forceinline__ void operator()(f32x4 (&acc)[2][2][4][2], const Unit& u, int wr, int wc, int fr, int fq) const {
;     ...
;             for (int m = 0; m < 4; ++m) { const int row = row0 + ai * HALF + m * 16; bf16_t* rowp = O + (size_t)row * ldc + col0;
;                 const float rs = ssq ? rsv[ai * 4 + m] : 1.0f;
; #pragma unroll
;                 for (int bj = 0; bj < 2; ++bj) { f32x4 v0 = acc[ai][bj][m][0] * rs, v1 = acc[ai][bj][m][1] * rs;
;                     if (ACT == 2) {
; #pragma unroll
;                         for (int j = 0; j < 4; ++j) { float a = v0[j] > 0.f ? v0[j] : 0.f; v0[j] = a * a; float b = v1[j] > 0.f ? v1[j] : 0.f; v1[j] = b * b; } }
;                     u32x4 w; w.x = cvt_pk_bf16(v0[0], v0[1]); w.y = cvt_pk_bf16(v0[2], v0[3]); w.z = cvt_pk_bf16(v1[0], v1[1]); w.w = cvt_pk_bf16(v1[2], v1[3]);
;                     *(u32x4*)(rowp + bj * HALF) = w; } }
	v_cvt_pk_bf16_f32 v67, v72, v73
	v_cvt_pk_bf16_f32 v68, v68, v69
	v_cvt_pk_bf16_f32 v69, v74, v75
	global_store_dwordx4 v[78:79], v[66:69], off offset:256 nt
	s_nop 1
	v_cndmask_b32_e64 v68, v139, 1.0, s[92:93]
	v_pk_mul_f32 v[62:63], v[62:63], v[68:69] op_sel_hi:[1,0]
	v_pk_mul_f32 v[64:65], v[64:65], v[68:69] op_sel_hi:[1,0]
	v_pk_mul_f32 v[70:71], v[60:61], v[68:69] op_sel_hi:[1,0]
	v_pk_mul_f32 v[60:61], v[58:59], v[68:69] op_sel_hi:[1,0]
	v_cvt_pk_bf16_f32 v58, v62, v63
	v_add_co_u32_e32 v62, vcc, s3, v130
	v_cvt_pk_bf16_f32 v59, v64, v65
	v_cvt_pk_bf16_f32 v60, v60, v61
	v_cvt_pk_bf16_f32 v61, v70, v71
	v_addc_co_u32_e32 v63, vcc, 0, v131, vcc
	global_store_dwordx4 v[62:63], v[58:61], off nt
	v_pk_mul_f32 v[52:53], v[52:53], v[68:69] op_sel_hi:[1,0]
	v_pk_mul_f32 v[50:51], v[50:51], v[68:69] op_sel_hi:[1,0]
	v_pk_mul_f32 v[58:59], v[44:45], v[68:69] op_sel_hi:[1,0]
	v_pk_mul_f32 v[44:45], v[42:43], v[68:69] op_sel_hi:[1,0]
	v_lshl_add_u64 v[66:67], v[130:131], 0, s[6:7]
	v_cvt_pk_bf16_f32 v42, v50, v51
	v_cvt_pk_bf16_f32 v43, v52, v53
	v_cvt_pk_bf16_f32 v44, v44, v45
	v_cvt_pk_bf16_f32 v45, v58, v59
	v_cndmask_b32_e64 v52, v138, 1.0, s[92:93]
	global_store_dwordx4 v[66:67], v[42:45], off offset:256 nt
	v_pk_mul_f32 v[46:47], v[46:47], v[52:53] op_sel_hi:[1,0]
	s_mov_b32 s3, 0x90000
	v_pk_mul_f32 v[44:45], v[56:57], v[52:53] op_sel_hi:[1,0]
	v_pk_mul_f32 v[42:43], v[54:55], v[52:53] op_sel_hi:[1,0]
	v_pk_mul_f32 v[48:49], v[48:49], v[52:53] op_sel_hi:[1,0]
	v_cvt_pk_bf16_f32 v42, v42, v43
	v_cvt_pk_bf16_f32 v43, v44, v45
	v_cvt_pk_bf16_f32 v44, v46, v47
	v_add_co_u32_e32 v46, vcc, s3, v130
	v_cvt_pk_bf16_f32 v45, v48, v49
	s_nop 0
	v_addc_co_u32_e32 v47, vcc, 0, v131, vcc
	s_mov_b64 s[6:7], 0x90000
	global_store_dwordx4 v[46:47], v[42:45], off nt
	v_pk_mul_f32 v[36:37], v[36:37], v[52:53] op_sel_hi:[1,0]
	v_pk_mul_f32 v[34:35], v[34:35], v[52:53] op_sel_hi:[1,0]
	v_pk_mul_f32 v[42:43], v[28:29], v[52:53] op_sel_hi:[1,0]
	v_pk_mul_f32 v[28:29], v[26:27], v[52:53] op_sel_hi:[1,0]
	v_lshl_add_u64 v[50:51], v[130:131], 0, s[6:7]
	v_cvt_pk_bf16_f32 v26, v34, v35
	v_cvt_pk_bf16_f32 v27, v36, v37
	v_cvt_pk_bf16_f32 v28, v28, v29
	v_cvt_pk_bf16_f32 v29, v42, v43
	v_cndmask_b32_e64 v36, v133, 1.0, s[92:93]
	global_store_dwordx4 v[50:51], v[26:29], off offset:256 nt
	v_pk_mul_f32 v[30:31], v[30:31], v[36:37] op_sel_hi:[1,0]
	s_mov_b32 s3, 0xa0000
	v_pk_mul_f32 v[28:29], v[40:41], v[36:37] op_sel_hi:[1,0]
	v_pk_mul_f32 v[26:27], v[38:39], v[36:37] op_sel_hi:[1,0]
	v_pk_mul_f32 v[32:33], v[32:33], v[36:37] op_sel_hi:[1,0]
	v_cvt_pk_bf16_f32 v26, v26, v27
	v_cvt_pk_bf16_f32 v27, v28, v29
	v_cvt_pk_bf16_f32 v28, v30, v31
	v_add_co_u32_e32 v30, vcc, s3, v130
	v_cvt_pk_bf16_f32 v29, v32, v33
	s_nop 0
	v_addc_co_u32_e32 v31, vcc, 0, v131, vcc
	s_mov_b64 s[6:7], 0xa0000
	global_store_dwordx4 v[30:31], v[26:29], off nt
	v_pk_mul_f32 v[20:21], v[20:21], v[36:37] op_sel_hi:[1,0]
	v_pk_mul_f32 v[18:19], v[18:19], v[36:37] op_sel_hi:[1,0]
	v_pk_mul_f32 v[26:27], v[12:13], v[36:37] op_sel_hi:[1,0]
	v_pk_mul_f32 v[12:13], v[10:11], v[36:37] op_sel_hi:[1,0]
	v_lshl_add_u64 v[34:35], v[130:131], 0, s[6:7]
	v_cvt_pk_bf16_f32 v10, v18, v19
	v_cvt_pk_bf16_f32 v11, v20, v21
	v_cvt_pk_bf16_f32 v12, v12, v13
	v_cvt_pk_bf16_f32 v13, v26, v27
	v_cndmask_b32_e64 v20, v132, 1.0, s[92:93]
	global_store_dwordx4 v[34:35], v[10:13], off offset:256 nt
	v_pk_mul_f32 v[14:15], v[14:15], v[20:21] op_sel_hi:[1,0]
	s_mov_b32 s3, 0xb0000
	v_pk_mul_f32 v[12:13], v[24:25], v[20:21] op_sel_hi:[1,0]
	v_pk_mul_f32 v[10:11], v[22:23], v[20:21] op_sel_hi:[1,0]
	v_pk_mul_f32 v[16:17], v[16:17], v[20:21] op_sel_hi:[1,0]
	v_cvt_pk_bf16_f32 v10, v10, v11
	v_cvt_pk_bf16_f32 v11, v12, v13
	v_cvt_pk_bf16_f32 v12, v14, v15
	v_add_co_u32_e32 v14, vcc, s3, v130
	v_cvt_pk_bf16_f32 v13, v16, v17
	s_nop 0
	v_addc_co_u32_e32 v15, vcc, 0, v131, vcc
	s_mov_b64 s[6:7], 0xb0000
	global_store_dwordx4 v[14:15], v[10:13], off nt
	v_pk_mul_f32 v[8:9], v[8:9], v[20:21] op_sel_hi:[1,0]
	v_pk_mul_f32 v[6:7], v[6:7], v[20:21] op_sel_hi:[1,0]
	v_pk_mul_f32 v[10:11], v[4:5], v[20:21] op_sel_hi:[1,0]
	v_pk_mul_f32 v[4:5], v[2:3], v[20:21] op_sel_hi:[1,0]
	v_lshl_add_u64 v[18:19], v[130:131], 0, s[6:7]
	v_cvt_pk_bf16_f32 v2, v6, v7
	v_cvt_pk_bf16_f32 v3, v8, v9
	v_cvt_pk_bf16_f32 v4, v4, v5
	v_cvt_pk_bf16_f32 v5, v10, v11
	s_andn2_b64 vcc, exec, s[4:5]
	s_mov_b64 s[4:5], -1
	global_store_dwordx4 v[18:19], v[2:5], off offset:256 nt
	s_cbranch_vccnz .LBB0_1099
	s_andn2_b64 vcc, exec, s[8:9]
	s_cbranch_vccnz .LBB0_1098
	s_barrier
	s_branch .LBB0_1098

; __device__ __forceinline__ float sigmoidf_(float x) { return __builtin_amdgcn_rcpf(1.0f + __expf(-x)); }
; __device__ __forceinline__ float ssq4(const f32x4 o) { return (o[0] * o[0] + o[1] * o[1]) + (o[2] * o[2] + o[3] * o[3]); }
;     __device__ __forceinline__ void operator()(f32x4 (&acc)[2][2][4][2], const Unit& u, int wr, int wc, int fr, int fq) const {
;         const int ch0 = u.pn * HALF + wc * 32 + 4 * fq;
;         float s[2][4];
;         f32x4 cur[4][2], nxt[4][2];
; #pragma unroll
;         for (int q = 0; q < 4; ++q)
; #pragma unroll
;             for (int n = 0; n < 2; ++n) cur[q][n] = *(const f32x4*)(h + (size_t)EPI_ROW(q) * D + ch0 + n * 16);
; #pragma unroll
;         for (int k = 0; k < 2; ++k) {
;             if (k < 1) {
; #pragma unroll
;                 for (int q = 0; q < 4; ++q)
; #pragma unroll
;                     for (int n = 0; n < 2; ++n) nxt[q][n] = *(const f32x4*)(h + (size_t)EPI_ROW(4 + q) * D + ch0 + n * 16);
;             }
;             asm volatile("" ::: "memory");
; #pragma unroll
;             for (int q = 0; q < 4; ++q) { const int r = 4 * k + q, ai = r >> 2, m = r & 3; const size_t off = (size_t)EPI_ROW(r) * D + ch0; float sr = 0.f;
; #pragma unroll
;                 for (int n = 0; n < 2; ++n) { const f32x4 b = cur[q][n]; const f32x4 v = acc[ai][0][m][n], g = acc[ai][1][m][n]; f32x4 o;
; #pragma unroll
;                     for (int j = 0; j < 4; ++j) o[j] = b[j] + v[j] * sigmoidf_(g[j]);
;                     *(f32x4*)(h + off + n * 16) = o; u32x2 w; w.x = cvt_pk_bf16(o[0], o[1]); w.y = cvt_pk_bf16(o[2], o[3]); *(u32x2*)(hb + off + n * 16) = w; sr += ssq4(o); }
.LBB0_1327:
	v_mov_b32_e32 v185, v246
	s_lshl_b32 s3, s6, 7
	s_or_b32 s3, s3, s34
	v_bfe_u32 v184, v185, 4, 2
	s_lshl_b32 s7, s22, 8
	v_and_b32_e32 v183, 15, v185
	v_lshl_or_b32 v176, v184, 2, s3
	s_add_i32 s3, s7, s33
	v_or_b32_e32 v188, s3, v183
	v_ashrrev_i32_e32 v177, 31, v176
	v_ashrrev_i32_e32 v189, 31, v188
	v_lshl_add_u64 v[174:175], v[176:177], 2, s[36:37]
	v_lshlrev_b64 v[130:131], 13, v[188:189]
	v_lshl_add_u64 v[216:217], v[174:175], 0, v[130:131]
	global_load_dwordx4 v[192:195], v[216:217], off
	global_load_dwordx4 v[196:199], v[216:217], off offset:64
	v_mul_f32_e32 v114, 0xbfb8aa3b, v114
	s_addk_i32 s3, 0x80
	v_mul_f32_e32 v115, 0xbfb8aa3b, v115
	v_exp_f32_e32 v138, v114
	v_or_b32_e32 v114, s3, v183
	v_or_b32_e32 v218, 16, v188
	v_mul_f32_e32 v126, 0xbfb8aa3b, v126
	v_mul_f32_e32 v128, 0xbfb8aa3b, v128
	v_exp_f32_e32 v186, v115
	v_ashrrev_i32_e32 v115, 31, v114
	v_ashrrev_i32_e32 v219, 31, v218
	v_exp_f32_e32 v134, v126
	v_exp_f32_e32 v136, v128
	v_or_b32_e32 v126, 16, v114
	v_or_b32_e32 v128, 32, v114
	v_or_b32_e32 v130, 48, v114
	v_lshlrev_b64 v[114:115], 13, v[114:115]
	v_lshlrev_b64 v[132:133], 13, v[218:219]
	v_lshl_add_u64 v[222:223], v[174:175], 0, v[132:133]
	v_lshl_add_u64 v[114:115], v[174:175], 0, v[114:115]
	global_load_dwordx4 v[200:203], v[222:223], off
	global_load_dwordx4 v[154:157], v[114:115], off
	global_load_dwordx4 v[150:153], v[114:115], off offset:64
	global_load_dwordx4 v[204:207], v[222:223], off offset:64
	v_mul_f32_e32 v127, 0xbfb8aa3b, v127
	v_mul_f32_e32 v129, 0xbfb8aa3b, v129
	v_exp_f32_e32 v135, v127
	v_exp_f32_e32 v137, v129
	v_or_b32_e32 v220, 32, v188
	v_or_b32_e32 v190, 48, v188
	v_ashrrev_i32_e32 v221, 31, v220
	v_ashrrev_i32_e32 v127, 31, v126
	v_ashrrev_i32_e32 v129, 31, v128
	v_ashrrev_i32_e32 v131, 31, v130
	v_ashrrev_i32_e32 v191, 31, v190
	v_add_f32_e32 v139, 1.0, v134
	v_add_f32_e32 v140, 1.0, v135
	v_lshlrev_b64 v[134:135], 13, v[220:221]
	v_lshlrev_b64 v[126:127], 13, v[126:127]
	v_lshlrev_b64 v[128:129], 13, v[128:129]
	v_lshlrev_b64 v[130:131], 13, v[130:131]
	v_lshlrev_b64 v[132:133], 11, v[188:189]
	v_add_f32_e32 v141, 1.0, v136
	v_add_f32_e32 v142, 1.0, v137
	v_lshlrev_b64 v[136:137], 13, v[190:191]
	v_lshl_add_u64 v[230:231], v[174:175], 0, v[134:135]
	v_lshl_add_u64 v[114:115], v[174:175], 0, v[126:127]
	v_lshl_add_u64 v[126:127], v[174:175], 0, v[128:129]
	v_lshl_add_u64 v[128:129], v[174:175], 0, v[130:131]
	v_add_f32_e32 v187, 1.0, v138
	v_lshl_add_u64 v[224:225], v[132:133], 0, v[176:177]
	v_rcp_f32_e32 v226, v139
	v_rcp_f32_e32 v227, v140
	v_rcp_f32_e32 v228, v141
	v_rcp_f32_e32 v229, v142
	v_lshl_add_u64 v[178:179], v[174:175], 0, v[136:137]
	global_load_dwordx4 v[208:211], v[230:231], off
	global_load_dwordx4 v[212:215], v[230:231], off offset:64
	global_load_dwordx4 v[162:165], v[178:179], off
	global_load_dwordx4 v[158:161], v[178:179], off offset:64
	global_load_dwordx4 v[146:149], v[114:115], off
	global_load_dwordx4 v[142:145], v[114:115], off offset:64
	global_load_dwordx4 v[138:141], v[126:127], off
	global_load_dwordx4 v[134:137], v[126:127], off offset:64
	global_load_dwordx4 v[130:133], v[128:129], off
	s_nop 0
	global_load_dwordx4 v[126:129], v[128:129], off offset:64
	v_mul_f32_e32 v116, 0xbfb8aa3b, v116
	v_mul_f32_e32 v117, 0xbfb8aa3b, v117
	v_exp_f32_e32 v116, v116
	v_exp_f32_e32 v117, v117
	v_mul_f32_e32 v106, 0xbfb8aa3b, v106
	v_mul_f32_e32 v107, 0xbfb8aa3b, v107
	v_mul_f32_e32 v108, 0xbfb8aa3b, v108
	v_mul_f32_e32 v109, 0xbfb8aa3b, v109
	v_mul_f32_e32 v98, 0xbfb8aa3b, v98
	v_mul_f32_e32 v99, 0xbfb8aa3b, v99
	v_mul_f32_e32 v100, 0xbfb8aa3b, v100
	v_mul_f32_e32 v101, 0xbfb8aa3b, v101
	v_exp_f32_e32 v106, v106
	v_exp_f32_e32 v107, v107
	v_exp_f32_e32 v108, v108
	v_exp_f32_e32 v109, v109
	v_exp_f32_e32 v98, v98
	v_exp_f32_e32 v99, v99
	v_exp_f32_e32 v100, v100
	v_exp_f32_e32 v101, v101
	v_add_f32_e32 v186, 1.0, v186
	v_add_f32_e32 v116, 1.0, v116
	v_add_f32_e32 v117, 1.0, v117
	s_waitcnt vmcnt(0)
	v_pk_fma_f32 v[122:123], v[122:123], v[226:227], v[192:193]
	v_rcp_f32_e32 v192, v187
	v_rcp_f32_e32 v193, v186
	v_rcp_f32_e32 v116, v116
	v_rcp_f32_e32 v117, v117
	v_mul_f32_e32 v90, 0xbfb8aa3b, v90
	v_mul_f32_e32 v91, 0xbfb8aa3b, v91
	v_mul_f32_e32 v92, 0xbfb8aa3b, v92
	v_mul_f32_e32 v93, 0xbfb8aa3b, v93
	v_mul_f32_e32 v82, 0xbfb8aa3b, v82
	v_mul_f32_e32 v83, 0xbfb8aa3b, v83
	v_mul_f32_e32 v84, 0xbfb8aa3b, v84
	v_mul_f32_e32 v85, 0xbfb8aa3b, v85
	v_exp_f32_e32 v90, v90
	v_exp_f32_e32 v91, v91
	v_exp_f32_e32 v92, v92
	v_exp_f32_e32 v93, v93
	v_exp_f32_e32 v82, v82
	v_exp_f32_e32 v83, v83
	v_exp_f32_e32 v84, v84
	v_exp_f32_e32 v85, v85
	v_pk_fma_f32 v[124:125], v[124:125], v[228:229], v[194:195]
	v_add_f32_e32 v106, 1.0, v106
	v_add_f32_e32 v107, 1.0, v107
	v_add_f32_e32 v108, 1.0, v108
	v_add_f32_e32 v109, 1.0, v109
	v_add_f32_e32 v98, 1.0, v98
	v_add_f32_e32 v99, 1.0, v99
	v_add_f32_e32 v100, 1.0, v100
	v_add_f32_e32 v101, 1.0, v101
	v_cvt_pk_bf16_f32 v114, v122, v123
	v_cvt_pk_bf16_f32 v115, v124, v125
	v_lshl_add_u64 v[194:195], v[224:225], 1, s[54:55]
	v_rcp_f32_e32 v106, v106
	v_rcp_f32_e32 v107, v107
	v_rcp_f32_e32 v108, v108
	v_rcp_f32_e32 v109, v109
	v_rcp_f32_e32 v98, v98
	v_rcp_f32_e32 v99, v99
	v_rcp_f32_e32 v100, v100
	v_rcp_f32_e32 v101, v101
	v_mul_f32_e32 v74, 0xbfb8aa3b, v74
	v_mul_f32_e32 v75, 0xbfb8aa3b, v75
	v_mul_f32_e32 v76, 0xbfb8aa3b, v76
	v_mul_f32_e32 v77, 0xbfb8aa3b, v77
	v_mul_f32_e32 v66, 0xbfb8aa3b, v66
	v_mul_f32_e32 v67, 0xbfb8aa3b, v67
	v_mul_f32_e32 v68, 0xbfb8aa3b, v68
	v_mul_f32_e32 v69, 0xbfb8aa3b, v69
	global_store_dwordx4 v[216:217], v[122:125], off nt
	global_store_dwordx2 v[194:195], v[114:115], off
; __device__ __forceinline__ float sigmoidf_(float x) { return __builtin_amdgcn_rcpf(1.0f + __expf(-x)); }
; __device__ __forceinline__ float ssq4(const f32x4 o) { return (o[0] * o[0] + o[1] * o[1]) + (o[2] * o[2] + o[3] * o[3]); }
;     __device__ __forceinline__ void operator()(f32x4 (&acc)[2][2][4][2], const Unit& u, int wr, int wc, int fr, int fq) const {
;     ...
;             for (int q = 0; q < 4; ++q) { const int r = 4 * k + q, ai = r >> 2, m = r & 3; const size_t off = (size_t)EPI_ROW(r) * D + ch0; float sr = 0.f;
; #pragma unroll
;                 for (int n = 0; n < 2; ++n) { const f32x4 b = cur[q][n]; const f32x4 v = acc[ai][0][m][n], g = acc[ai][1][m][n]; f32x4 o;
; #pragma unroll
;                     for (int j = 0; j < 4; ++j) o[j] = b[j] + v[j] * sigmoidf_(g[j]);
;                     *(f32x4*)(h + off + n * 16) = o; u32x2 w; w.x = cvt_pk_bf16(o[0], o[1]); w.y = cvt_pk_bf16(o[2], o[3]); *(u32x2*)(hb + off + n * 16) = w; sr += ssq4(o); }
;                 s[ai][m] = sr; }
	v_pk_fma_f32 v[114:115], v[118:119], v[192:193], v[196:197]
	v_pk_fma_f32 v[116:117], v[120:121], v[116:117], v[198:199]
	v_exp_f32_e32 v74, v74
	v_exp_f32_e32 v75, v75
	v_exp_f32_e32 v76, v76
	v_exp_f32_e32 v77, v77
	v_exp_f32_e32 v66, v66
	v_exp_f32_e32 v67, v67
	v_exp_f32_e32 v68, v68
	v_exp_f32_e32 v69, v69
	v_cvt_pk_bf16_f32 v118, v114, v115
	v_cvt_pk_bf16_f32 v119, v116, v117
	v_add_f32_e32 v90, 1.0, v90
	v_add_f32_e32 v91, 1.0, v91
	v_add_f32_e32 v92, 1.0, v92
	v_add_f32_e32 v93, 1.0, v93
	v_add_f32_e32 v82, 1.0, v82
	v_add_f32_e32 v83, 1.0, v83
	v_add_f32_e32 v84, 1.0, v84
	v_add_f32_e32 v85, 1.0, v85
	global_store_dwordx4 v[216:217], v[114:117], off offset:64 nt
	global_store_dwordx2 v[194:195], v[118:119], off offset:32
	v_lshlrev_b64 v[118:119], 11, v[218:219]
	v_rcp_f32_e32 v90, v90
	v_rcp_f32_e32 v91, v91
	v_rcp_f32_e32 v92, v92
	v_rcp_f32_e32 v93, v93
	v_rcp_f32_e32 v82, v82
	v_rcp_f32_e32 v83, v83
	v_rcp_f32_e32 v84, v84
	v_rcp_f32_e32 v85, v85
	v_lshl_add_u64 v[118:119], v[118:119], 0, v[176:177]
	v_pk_fma_f32 v[106:107], v[110:111], v[106:107], v[200:201]
	v_pk_fma_f32 v[108:109], v[112:113], v[108:109], v[202:203]
	v_pk_fma_f32 v[98:99], v[102:103], v[98:99], v[204:205]
	v_pk_fma_f32 v[100:101], v[104:105], v[100:101], v[206:207]
	v_cvt_pk_bf16_f32 v110, v106, v107
	v_cvt_pk_bf16_f32 v111, v108, v109
	v_lshl_add_u64 v[112:113], v[118:119], 1, s[54:55]
	v_cvt_pk_bf16_f32 v102, v98, v99
	v_cvt_pk_bf16_f32 v103, v100, v101
	v_add_f32_e32 v74, 1.0, v74
	v_add_f32_e32 v75, 1.0, v75
	v_add_f32_e32 v76, 1.0, v76
	v_add_f32_e32 v77, 1.0, v77
	v_add_f32_e32 v66, 1.0, v66
	v_add_f32_e32 v67, 1.0, v67
	v_add_f32_e32 v68, 1.0, v68
	v_add_f32_e32 v69, 1.0, v69
	global_store_dwordx4 v[222:223], v[106:109], off nt
	global_store_dwordx2 v[112:113], v[110:111], off
	global_store_dwordx4 v[222:223], v[98:101], off offset:64 nt
	global_store_dwordx2 v[112:113], v[102:103], off offset:32
	v_lshlrev_b64 v[102:103], 11, v[220:221]
	v_rcp_f32_e32 v74, v74
	v_rcp_f32_e32 v75, v75
	v_rcp_f32_e32 v76, v76
	v_rcp_f32_e32 v77, v77
	v_rcp_f32_e32 v66, v66
	v_rcp_f32_e32 v67, v67
	v_rcp_f32_e32 v68, v68
	v_rcp_f32_e32 v69, v69
	v_lshl_add_u64 v[102:103], v[102:103], 0, v[176:177]
	v_pk_fma_f32 v[90:91], v[94:95], v[90:91], v[208:209]
	v_pk_fma_f32 v[92:93], v[96:97], v[92:93], v[210:211]
	v_pk_fma_f32 v[82:83], v[86:87], v[82:83], v[212:213]
	v_pk_fma_f32 v[84:85], v[88:89], v[84:85], v[214:215]
	v_cvt_pk_bf16_f32 v94, v90, v91
	v_cvt_pk_bf16_f32 v95, v92, v93
	v_lshl_add_u64 v[96:97], v[102:103], 1, s[54:55]
	v_cvt_pk_bf16_f32 v86, v82, v83
	v_cvt_pk_bf16_f32 v87, v84, v85
	v_mul_f32_e32 v58, 0xbfb8aa3b, v58
	v_mul_f32_e32 v59, 0xbfb8aa3b, v59
	v_mul_f32_e32 v60, 0xbfb8aa3b, v60
	v_mul_f32_e32 v61, 0xbfb8aa3b, v61
	v_mul_f32_e32 v50, 0xbfb8aa3b, v50
	v_mul_f32_e32 v51, 0xbfb8aa3b, v51
	v_mul_f32_e32 v52, 0xbfb8aa3b, v52
	v_mul_f32_e32 v53, 0xbfb8aa3b, v53
	global_store_dwordx4 v[230:231], v[90:93], off nt
	global_store_dwordx2 v[96:97], v[94:95], off
	global_store_dwordx4 v[230:231], v[82:85], off offset:64 nt
	global_store_dwordx2 v[96:97], v[86:87], off offset:32
	v_lshlrev_b64 v[86:87], 11, v[190:191]
	v_exp_f32_e32 v58, v58
	v_exp_f32_e32 v59, v59
	v_exp_f32_e32 v60, v60
	v_exp_f32_e32 v61, v61
	v_exp_f32_e32 v50, v50
	v_exp_f32_e32 v51, v51
	v_exp_f32_e32 v52, v52
	v_exp_f32_e32 v53, v53
	v_lshl_add_u64 v[86:87], v[86:87], 0, v[176:177]
	v_pk_fma_f32 v[74:75], v[78:79], v[74:75], v[162:163]
	v_pk_fma_f32 v[76:77], v[80:81], v[76:77], v[164:165]
	v_pk_fma_f32 v[66:67], v[70:71], v[66:67], v[158:159]
	v_pk_fma_f32 v[68:69], v[72:73], v[68:69], v[160:161]
	v_cvt_pk_bf16_f32 v78, v74, v75
	v_cvt_pk_bf16_f32 v79, v76, v77
	v_lshl_add_u64 v[80:81], v[86:87], 1, s[54:55]
	v_cvt_pk_bf16_f32 v70, v66, v67
	v_cvt_pk_bf16_f32 v71, v68, v69
	global_store_dwordx4 v[178:179], v[74:77], off nt
	global_store_dwordx2 v[80:81], v[78:79], off
	global_store_dwordx4 v[178:179], v[66:69], off offset:64 nt
	global_store_dwordx2 v[80:81], v[70:71], off offset:32
	v_pk_mul_f32 v[70:71], v[122:123], v[122:123]
	v_pk_mul_f32 v[72:73], v[124:125], v[124:125]
	v_pk_mul_f32 v[78:79], v[114:115], v[114:115]
	v_pk_mul_f32 v[80:81], v[116:117], v[116:117]
	v_add_f32_e32 v78, v78, v79
	v_add_f32_e32 v80, v80, v81
	v_add_f32_e32 v72, v72, v73
	v_add_f32_e32 v70, v70, v71
	v_add_f32_e32 v58, 1.0, v58
	v_add_f32_e32 v59, 1.0, v59
	v_add_f32_e32 v60, 1.0, v60
	v_add_f32_e32 v61, 1.0, v61
	v_add_f32_e32 v50, 1.0, v50
	v_add_f32_e32 v51, 1.0, v51
	v_add_f32_e32 v52, 1.0, v52
	v_add_f32_e32 v53, 1.0, v53
	v_mul_f32_e32 v42, 0xbfb8aa3b, v42
	v_mul_f32_e32 v43, 0xbfb8aa3b, v43
	v_mul_f32_e32 v44, 0xbfb8aa3b, v44
	v_mul_f32_e32 v45, 0xbfb8aa3b, v45
	v_mul_f32_e32 v34, 0xbfb8aa3b, v34
	v_mul_f32_e32 v35, 0xbfb8aa3b, v35
	v_mul_f32_e32 v36, 0xbfb8aa3b, v36
	v_mul_f32_e32 v37, 0xbfb8aa3b, v37
	v_add_f32_e32 v78, v78, v80
	v_add_f32_e32 v70, v70, v72
	v_rcp_f32_e32 v58, v58
	v_rcp_f32_e32 v59, v59
	v_rcp_f32_e32 v60, v60
	v_rcp_f32_e32 v61, v61
	v_rcp_f32_e32 v50, v50
	v_rcp_f32_e32 v51, v51
	v_rcp_f32_e32 v52, v52
	v_rcp_f32_e32 v53, v53
	v_exp_f32_e32 v42, v42
	v_exp_f32_e32 v43, v43
	v_exp_f32_e32 v44, v44
	v_exp_f32_e32 v45, v45
	v_exp_f32_e32 v34, v34
	v_exp_f32_e32 v35, v35
	v_exp_f32_e32 v36, v36
	v_exp_f32_e32 v37, v37
	v_add_f32_e32 v78, v70, v78
	v_add_u32_e32 v70, 0x80, v188
	v_ashrrev_i32_e32 v71, 31, v70
	v_lshlrev_b64 v[72:73], 11, v[70:71]
	v_lshl_add_u64 v[72:73], v[72:73], 0, v[176:177]
	v_pk_fma_f32 v[58:59], v[62:63], v[58:59], v[154:155]
	v_pk_fma_f32 v[60:61], v[64:65], v[60:61], v[156:157]
	v_lshlrev_b64 v[62:63], 13, v[70:71]
	v_pk_fma_f32 v[50:51], v[54:55], v[50:51], v[150:151]
; __device__ __forceinline__ float sigmoidf_(float x) { return __builtin_amdgcn_rcpf(1.0f + __expf(-x)); }
; __device__ __forceinline__ float shx(float v, int o, int lane) { return __builtin_bit_cast(float, __builtin_amdgcn_ds_bpermute((lane ^ o) << 2, __builtin_bit_cast(int, v))); }
; __device__ __forceinline__ float ssq4(const f32x4 o) { return (o[0] * o[0] + o[1] * o[1]) + (o[2] * o[2] + o[3] * o[3]); }
; template <bool SIXTEEN> __device__ __forceinline__ void tile_ssq(const float (&s)[2][4], const Unit& u, int wr, int wc, int fr, int fq, float* ssq, LAS float* ptab) {
;     ...
;         for (int m = 0; m < 4; ++m) { float v = s[ai][m]; v += shx(v, 16, lane); v += shx(v, 32, lane); if (fq == 0) ptab[(ai * HALF + wr * 64 + m * 16 + fr) * 4 + wc] = v; }
;     __device__ __forceinline__ void operator()(f32x4 (&acc)[2][2][4][2], const Unit& u, int wr, int wc, int fr, int fq) const {
;     ...
;             for (int q = 0; q < 4; ++q) { const int r = 4 * k + q, ai = r >> 2, m = r & 3; const size_t off = (size_t)EPI_ROW(r) * D + ch0; float sr = 0.f;
; #pragma unroll
;                 for (int n = 0; n < 2; ++n) { const f32x4 b = cur[q][n]; const f32x4 v = acc[ai][0][m][n], g = acc[ai][1][m][n]; f32x4 o;
; #pragma unroll
;                     for (int j = 0; j < 4; ++j) o[j] = b[j] + v[j] * sigmoidf_(g[j]);
;                     *(f32x4*)(h + off + n * 16) = o; u32x2 w; w.x = cvt_pk_bf16(o[0], o[1]); w.y = cvt_pk_bf16(o[2], o[3]); *(u32x2*)(hb + off + n * 16) = w; sr += ssq4(o); }
;                 s[ai][m] = sr; }
	v_pk_fma_f32 v[52:53], v[56:57], v[52:53], v[152:153]
	v_add_f32_e32 v42, 1.0, v42
	v_add_f32_e32 v43, 1.0, v43
	v_add_f32_e32 v44, 1.0, v44
	v_add_f32_e32 v45, 1.0, v45
	v_add_f32_e32 v34, 1.0, v34
	v_add_f32_e32 v35, 1.0, v35
	v_add_f32_e32 v36, 1.0, v36
	v_add_f32_e32 v37, 1.0, v37
	v_mul_f32_e32 v26, 0xbfb8aa3b, v26
	v_mul_f32_e32 v27, 0xbfb8aa3b, v27
	v_mul_f32_e32 v28, 0xbfb8aa3b, v28
	v_mul_f32_e32 v29, 0xbfb8aa3b, v29
	v_mul_f32_e32 v18, 0xbfb8aa3b, v18
	v_mul_f32_e32 v19, 0xbfb8aa3b, v19
	v_mul_f32_e32 v20, 0xbfb8aa3b, v20
	v_mul_f32_e32 v21, 0xbfb8aa3b, v21
	v_lshl_add_u64 v[62:63], v[174:175], 0, v[62:63]
	v_cvt_pk_bf16_f32 v64, v58, v59
	v_cvt_pk_bf16_f32 v65, v60, v61
	v_lshl_add_u64 v[70:71], v[72:73], 1, s[54:55]
	v_cvt_pk_bf16_f32 v54, v50, v51
	v_cvt_pk_bf16_f32 v55, v52, v53
	v_rcp_f32_e32 v42, v42
	v_rcp_f32_e32 v43, v43
	v_rcp_f32_e32 v44, v44
	v_rcp_f32_e32 v45, v45
	v_rcp_f32_e32 v34, v34
	v_rcp_f32_e32 v35, v35
	v_rcp_f32_e32 v36, v36
	v_rcp_f32_e32 v37, v37
	v_exp_f32_e32 v26, v26
	v_exp_f32_e32 v27, v27
	v_exp_f32_e32 v28, v28
	v_exp_f32_e32 v29, v29
	v_exp_f32_e32 v18, v18
	v_exp_f32_e32 v19, v19
	v_exp_f32_e32 v20, v20
	v_exp_f32_e32 v21, v21
	global_store_dwordx4 v[62:63], v[58:61], off nt
	global_store_dwordx2 v[70:71], v[64:65], off
	global_store_dwordx4 v[62:63], v[50:53], off offset:64 nt
	global_store_dwordx2 v[70:71], v[54:55], off offset:32
	v_add_u32_e32 v54, 0x90, v188
	v_ashrrev_i32_e32 v55, 31, v54
	v_lshlrev_b64 v[56:57], 11, v[54:55]
	v_lshl_add_u64 v[56:57], v[56:57], 0, v[176:177]
	v_pk_fma_f32 v[42:43], v[46:47], v[42:43], v[146:147]
	v_pk_fma_f32 v[44:45], v[48:49], v[44:45], v[148:149]
	v_lshlrev_b64 v[46:47], 13, v[54:55]
	v_pk_fma_f32 v[34:35], v[38:39], v[34:35], v[142:143]
	v_pk_fma_f32 v[36:37], v[40:41], v[36:37], v[144:145]
	v_add_f32_e32 v26, 1.0, v26
	v_add_f32_e32 v27, 1.0, v27
	v_add_f32_e32 v28, 1.0, v28
	v_add_f32_e32 v29, 1.0, v29
	v_add_f32_e32 v18, 1.0, v18
	v_add_f32_e32 v19, 1.0, v19
	v_add_f32_e32 v20, 1.0, v20
	v_add_f32_e32 v21, 1.0, v21
	v_mul_f32_e32 v10, 0xbfb8aa3b, v10
	v_mul_f32_e32 v11, 0xbfb8aa3b, v11
	v_mul_f32_e32 v12, 0xbfb8aa3b, v12
	v_mul_f32_e32 v13, 0xbfb8aa3b, v13
	v_lshl_add_u64 v[46:47], v[174:175], 0, v[46:47]
	v_cvt_pk_bf16_f32 v48, v42, v43
	v_cvt_pk_bf16_f32 v49, v44, v45
	v_lshl_add_u64 v[54:55], v[56:57], 1, s[54:55]
	v_cvt_pk_bf16_f32 v38, v34, v35
	v_cvt_pk_bf16_f32 v39, v36, v37
	v_rcp_f32_e32 v26, v26
	v_rcp_f32_e32 v27, v27
	v_rcp_f32_e32 v28, v28
	v_rcp_f32_e32 v29, v29
	v_rcp_f32_e32 v18, v18
	v_rcp_f32_e32 v19, v19
	v_rcp_f32_e32 v20, v20
	v_rcp_f32_e32 v21, v21
	v_exp_f32_e32 v10, v10
	v_exp_f32_e32 v11, v11
	v_exp_f32_e32 v12, v12
	v_exp_f32_e32 v13, v13
	v_mul_f32_e32 v2, 0xbfb8aa3b, v2
	v_mul_f32_e32 v3, 0xbfb8aa3b, v3
	v_mul_f32_e32 v4, 0xbfb8aa3b, v4
	v_mul_f32_e32 v5, 0xbfb8aa3b, v5
	global_store_dwordx4 v[46:47], v[42:45], off nt
	global_store_dwordx2 v[54:55], v[48:49], off
	global_store_dwordx4 v[46:47], v[34:37], off offset:64 nt
	global_store_dwordx2 v[54:55], v[38:39], off offset:32
	v_add_u32_e32 v38, 0xa0, v188
	v_exp_f32_e32 v2, v2
	v_exp_f32_e32 v3, v3
	v_exp_f32_e32 v4, v4
	v_exp_f32_e32 v5, v5
	v_ashrrev_i32_e32 v39, 31, v38
	v_lshlrev_b64 v[40:41], 11, v[38:39]
	v_lshl_add_u64 v[40:41], v[40:41], 0, v[176:177]
	v_pk_fma_f32 v[26:27], v[30:31], v[26:27], v[138:139]
	v_pk_fma_f32 v[28:29], v[32:33], v[28:29], v[140:141]
	v_lshlrev_b64 v[30:31], 13, v[38:39]
	v_pk_fma_f32 v[18:19], v[22:23], v[18:19], v[134:135]
	v_pk_fma_f32 v[20:21], v[24:25], v[20:21], v[136:137]
	v_add_f32_e32 v10, 1.0, v10
	v_add_f32_e32 v11, 1.0, v11
	v_add_f32_e32 v12, 1.0, v12
	v_add_f32_e32 v13, 1.0, v13
	v_lshl_add_u64 v[30:31], v[174:175], 0, v[30:31]
	v_cvt_pk_bf16_f32 v32, v26, v27
	v_cvt_pk_bf16_f32 v33, v28, v29
	v_lshl_add_u64 v[38:39], v[40:41], 1, s[54:55]
	v_cvt_pk_bf16_f32 v22, v18, v19
	v_cvt_pk_bf16_f32 v23, v20, v21
	v_rcp_f32_e32 v10, v10
	v_rcp_f32_e32 v11, v11
	v_rcp_f32_e32 v12, v12
	v_rcp_f32_e32 v13, v13
	v_add_f32_e32 v2, 1.0, v2
	v_add_f32_e32 v3, 1.0, v3
	v_add_f32_e32 v4, 1.0, v4
	v_add_f32_e32 v5, 1.0, v5
	global_store_dwordx4 v[30:31], v[26:29], off nt
	global_store_dwordx2 v[38:39], v[32:33], off
	global_store_dwordx4 v[30:31], v[18:21], off offset:64 nt
	global_store_dwordx2 v[38:39], v[22:23], off offset:32
	v_add_u32_e32 v22, 0xb0, v188
	v_rcp_f32_e32 v2, v2
	v_rcp_f32_e32 v3, v3
	v_rcp_f32_e32 v4, v4
	v_rcp_f32_e32 v5, v5
	v_ashrrev_i32_e32 v23, 31, v22
	v_lshlrev_b64 v[24:25], 11, v[22:23]
	v_lshl_add_u64 v[24:25], v[24:25], 0, v[176:177]
	v_pk_fma_f32 v[10:11], v[14:15], v[10:11], v[130:131]
	v_pk_fma_f32 v[12:13], v[16:17], v[12:13], v[132:133]
	v_lshlrev_b64 v[14:15], 13, v[22:23]
	v_lshl_add_u64 v[14:15], v[174:175], 0, v[14:15]
	v_cvt_pk_bf16_f32 v16, v10, v11
	v_cvt_pk_bf16_f32 v17, v12, v13
	v_lshl_add_u64 v[22:23], v[24:25], 1, s[54:55]
	v_pk_fma_f32 v[2:3], v[6:7], v[2:3], v[126:127]
	v_pk_fma_f32 v[4:5], v[8:9], v[4:5], v[128:129]
	v_and_b32_e32 v6, 63, v185
	global_store_dwordx4 v[14:15], v[10:13], off nt
	global_store_dwordx2 v[22:23], v[16:17], off
	global_store_dwordx4 v[14:15], v[2:5], off offset:64 nt
	v_lshlrev_b32_e32 v14, 2, v6
	v_xor_b32_e32 v7, 64, v14
	ds_bpermute_b32 v15, v7, v78
	v_cvt_pk_bf16_f32 v8, v2, v3
	v_cvt_pk_bf16_f32 v9, v4, v5
	global_store_dwordx2 v[22:23], v[8:9], off offset:32
	v_xor_b32_e32 v9, 0x80, v14
	s_waitcnt lgkmcnt(0)
	v_add_f32_e32 v14, v78, v15
	ds_bpermute_b32 v15, v9, v14
	v_cmp_eq_u32_e32 vcc, 0, v184
	v_lshl_add_u32 v8, v183, 4, s63
	s_and_saveexec_b64 s[14:15], vcc
	s_cbranch_execz .LBB0_1329
	s_waitcnt lgkmcnt(0)
	v_add_f32_e32 v14, v14, v15
	ds_write_b32 v8, v14

;     __device__ __forceinline__ void operator()(f32x4 (&acc)[2][2][4][2], const Unit& u, int wr, int wc, int fr, int fq) const {
;         const int row0 = u.pm * BM + wr * 64 + fr; const int col0 = u.pn * BM + wc * 32 + 8 * fq;
;         float rsv[8]; if (ssq) rows_rstd(ssq, row0, fr, fq, rsv);
; #pragma unroll
;         for (int ai = 0; ai < 2; ++ai)
; #pragma unroll
;             for (int m = 0; m < 4; ++m) { const int row = row0 + ai * HALF + m * 16; bf16_t* rowp = O + (size_t)row * ldc + col0;
;                 const float rs = ssq ? rsv[ai * 4 + m] : 1.0f;
; #pragma unroll
;                 for (int bj = 0; bj < 2; ++bj) { f32x4 v0 = acc[ai][bj][m][0] * rs, v1 = acc[ai][bj][m][1] * rs;
;                     if (ACT == 2) {
; #pragma unroll
;                         for (int j = 0; j < 4; ++j) { float a = v0[j] > 0.f ? v0[j] : 0.f; v0[j] = a * a; float b = v1[j] > 0.f ? v1[j] : 0.f; v1[j] = b * b; } }
;                     u32x4 w; w.x = cvt_pk_bf16(v0[0], v0[1]); w.y = cvt_pk_bf16(v0[2], v0[3]); w.z = cvt_pk_bf16(v1[0], v1[1]); w.w = cvt_pk_bf16(v1[2], v1[3]);
;                     *(u32x4*)(rowp + bj * HALF) = w; } }
.LBB0_1417:
	s_lshl_b32 s3, s62, 8
	v_lshl_or_b32 v130, v163, 3, s3
	v_or_b32_e32 v132, s42, v130
	v_ashrrev_i32_e32 v133, 31, v132
	v_mov_b64_e32 v[130:131], s[58:59]
	v_cndmask_b32_e64 v140, v165, 1.0, s[92:93]
	v_mad_i64_i32 v[136:137], s[6:7], v158, s90, v[130:131]
	v_lshlrev_b64 v[132:133], 1, v[132:133]
	v_pk_mul_f32 v[128:129], v[128:129], v[140:141] op_sel_hi:[1,0]
	v_pk_mul_f32 v[126:127], v[126:127], v[140:141] op_sel_hi:[1,0]
	v_pk_mul_f32 v[142:143], v[124:125], v[140:141] op_sel_hi:[1,0]
	v_pk_mul_f32 v[124:125], v[122:123], v[140:141] op_sel_hi:[1,0]
	v_lshl_add_u64 v[136:137], v[136:137], 0, v[132:133]
	v_cvt_pk_bf16_f32 v122, v126, v127
	v_cvt_pk_bf16_f32 v123, v128, v129
	v_cvt_pk_bf16_f32 v124, v124, v125
	v_cvt_pk_bf16_f32 v125, v142, v143
	global_store_dwordx4 v[136:137], v[122:125], off nt
	v_pk_mul_f32 v[116:117], v[116:117], v[140:141] op_sel_hi:[1,0]
	v_pk_mul_f32 v[114:115], v[114:115], v[140:141] op_sel_hi:[1,0]
	v_pk_mul_f32 v[122:123], v[108:109], v[140:141] op_sel_hi:[1,0]
	v_pk_mul_f32 v[108:109], v[106:107], v[140:141] op_sel_hi:[1,0]
	v_cvt_pk_bf16_f32 v106, v114, v115
	v_cvt_pk_bf16_f32 v107, v116, v117
	v_cvt_pk_bf16_f32 v108, v108, v109
	v_cvt_pk_bf16_f32 v109, v122, v123
	global_store_dwordx4 v[136:137], v[106:109], off offset:256 nt
	v_cndmask_b32_e64 v116, v164, 1.0, s[92:93]
	v_pk_mul_f32 v[112:113], v[112:113], v[116:117] op_sel_hi:[1,0]
	v_or_b32_e32 v106, 16, v158
	v_mad_i64_i32 v[106:107], s[6:7], v106, s90, v[130:131]
	v_lshl_add_u64 v[114:115], v[106:107], 0, v[132:133]
	v_pk_mul_f32 v[108:109], v[120:121], v[116:117] op_sel_hi:[1,0]
	v_pk_mul_f32 v[106:107], v[118:119], v[116:117] op_sel_hi:[1,0]
	v_pk_mul_f32 v[110:111], v[110:111], v[116:117] op_sel_hi:[1,0]
	v_cvt_pk_bf16_f32 v106, v106, v107
	v_cvt_pk_bf16_f32 v107, v108, v109
	v_cvt_pk_bf16_f32 v108, v110, v111
	v_cvt_pk_bf16_f32 v109, v112, v113
	global_store_dwordx4 v[114:115], v[106:109], off nt
	v_pk_mul_f32 v[100:101], v[100:101], v[116:117] op_sel_hi:[1,0]
	v_pk_mul_f32 v[98:99], v[98:99], v[116:117] op_sel_hi:[1,0]
	v_pk_mul_f32 v[106:107], v[92:93], v[116:117] op_sel_hi:[1,0]
	v_pk_mul_f32 v[92:93], v[90:91], v[116:117] op_sel_hi:[1,0]
	v_cvt_pk_bf16_f32 v90, v98, v99
	v_cvt_pk_bf16_f32 v91, v100, v101
	v_cvt_pk_bf16_f32 v92, v92, v93
	v_cvt_pk_bf16_f32 v93, v106, v107
	global_store_dwordx4 v[114:115], v[90:93], off offset:256 nt
	v_cndmask_b32_e64 v100, v167, 1.0, s[92:93]
	v_pk_mul_f32 v[96:97], v[96:97], v[100:101] op_sel_hi:[1,0]
	v_or_b32_e32 v90, 32, v158
	v_mad_i64_i32 v[90:91], s[6:7], v90, s90, v[130:131]
	v_lshl_add_u64 v[98:99], v[90:91], 0, v[132:133]
	v_pk_mul_f32 v[92:93], v[104:105], v[100:101] op_sel_hi:[1,0]
	v_pk_mul_f32 v[90:91], v[102:103], v[100:101] op_sel_hi:[1,0]
	v_pk_mul_f32 v[94:95], v[94:95], v[100:101] op_sel_hi:[1,0]
	v_cvt_pk_bf16_f32 v90, v90, v91
	v_cvt_pk_bf16_f32 v91, v92, v93
	v_cvt_pk_bf16_f32 v92, v94, v95
	v_cvt_pk_bf16_f32 v93, v96, v97
	global_store_dwordx4 v[98:99], v[90:93], off nt
	v_pk_mul_f32 v[84:85], v[84:85], v[100:101] op_sel_hi:[1,0]
	v_pk_mul_f32 v[82:83], v[82:83], v[100:101] op_sel_hi:[1,0]
	v_pk_mul_f32 v[90:91], v[76:77], v[100:101] op_sel_hi:[1,0]
	v_pk_mul_f32 v[76:77], v[74:75], v[100:101] op_sel_hi:[1,0]
	v_cvt_pk_bf16_f32 v74, v82, v83
	v_cvt_pk_bf16_f32 v75, v84, v85
	v_cvt_pk_bf16_f32 v76, v76, v77
	v_cvt_pk_bf16_f32 v77, v90, v91
	global_store_dwordx4 v[98:99], v[74:77], off offset:256 nt
	v_cndmask_b32_e64 v84, v166, 1.0, s[92:93]
	v_pk_mul_f32 v[80:81], v[80:81], v[84:85] op_sel_hi:[1,0]
	v_or_b32_e32 v74, 48, v158
	v_mad_i64_i32 v[74:75], s[6:7], v74, s90, v[130:131]
	v_lshl_add_u64 v[82:83], v[74:75], 0, v[132:133]
	v_pk_mul_f32 v[76:77], v[88:89], v[84:85] op_sel_hi:[1,0]
	v_pk_mul_f32 v[74:75], v[86:87], v[84:85] op_sel_hi:[1,0]
	v_pk_mul_f32 v[78:79], v[78:79], v[84:85] op_sel_hi:[1,0]
	v_cvt_pk_bf16_f32 v74, v74, v75
	v_cvt_pk_bf16_f32 v75, v76, v77
	v_cvt_pk_bf16_f32 v76, v78, v79
	v_cvt_pk_bf16_f32 v77, v80, v81
	global_store_dwordx4 v[82:83], v[74:77], off nt
	v_pk_mul_f32 v[72:73], v[72:73], v[84:85] op_sel_hi:[1,0]
	v_pk_mul_f32 v[70:71], v[70:71], v[84:85] op_sel_hi:[1,0]
	v_pk_mul_f32 v[74:75], v[68:69], v[84:85] op_sel_hi:[1,0]
	v_pk_mul_f32 v[68:69], v[66:67], v[84:85] op_sel_hi:[1,0]
	v_cvt_pk_bf16_f32 v66, v70, v71
	v_cvt_pk_bf16_f32 v67, v72, v73
	v_cvt_pk_bf16_f32 v68, v68, v69
;     __device__ __forceinline__ void operator()(f32x4 (&acc)[2][2][4][2], const Unit& u, int wr, int wc, int fr, int fq) const {
;     ...
;             for (int m = 0; m < 4; ++m) { const int row = row0 + ai * HALF + m * 16; bf16_t* rowp = O + (size_t)row * ldc + col0;
;                 const float rs = ssq ? rsv[ai * 4 + m] : 1.0f;
; #pragma unroll
;                 for (int bj = 0; bj < 2; ++bj) { f32x4 v0 = acc[ai][bj][m][0] * rs, v1 = acc[ai][bj][m][1] * rs;
;                     if (ACT == 2) {
; #pragma unroll
;                         for (int j = 0; j < 4; ++j) { float a = v0[j] > 0.f ? v0[j] : 0.f; v0[j] = a * a; float b = v1[j] > 0.f ? v1[j] : 0.f; v1[j] = b * b; } }
;                     u32x4 w; w.x = cvt_pk_bf16(v0[0], v0[1]); w.y = cvt_pk_bf16(v0[2], v0[3]); w.z = cvt_pk_bf16(v1[0], v1[1]); w.w = cvt_pk_bf16(v1[2], v1[3]);
;                     *(u32x4*)(rowp + bj * HALF) = w; } }
	v_cvt_pk_bf16_f32 v69, v74, v75
	global_store_dwordx4 v[82:83], v[66:69], off offset:256 nt
	s_andn2_b64 vcc, exec, s[4:5]
	s_mov_b64 s[4:5], -1
	v_add_u32_e32 v66, 0x80, v158
	v_cndmask_b32_e64 v68, v139, 1.0, s[92:93]
	v_mad_i64_i32 v[66:67], s[6:7], v66, s90, v[130:131]
	v_pk_mul_f32 v[64:65], v[64:65], v[68:69] op_sel_hi:[1,0]
	v_pk_mul_f32 v[62:63], v[62:63], v[68:69] op_sel_hi:[1,0]
	v_pk_mul_f32 v[70:71], v[60:61], v[68:69] op_sel_hi:[1,0]
	v_pk_mul_f32 v[60:61], v[58:59], v[68:69] op_sel_hi:[1,0]
	v_lshl_add_u64 v[66:67], v[66:67], 0, v[132:133]
	v_cvt_pk_bf16_f32 v58, v62, v63
	v_cvt_pk_bf16_f32 v59, v64, v65
	v_cvt_pk_bf16_f32 v60, v60, v61
	v_cvt_pk_bf16_f32 v61, v70, v71
	global_store_dwordx4 v[66:67], v[58:61], off nt
	v_pk_mul_f32 v[52:53], v[52:53], v[68:69] op_sel_hi:[1,0]
	v_pk_mul_f32 v[50:51], v[50:51], v[68:69] op_sel_hi:[1,0]
	v_pk_mul_f32 v[58:59], v[44:45], v[68:69] op_sel_hi:[1,0]
	v_pk_mul_f32 v[44:45], v[42:43], v[68:69] op_sel_hi:[1,0]
	v_cvt_pk_bf16_f32 v42, v50, v51
	v_cvt_pk_bf16_f32 v43, v52, v53
	v_cvt_pk_bf16_f32 v44, v44, v45
	v_cvt_pk_bf16_f32 v45, v58, v59
	global_store_dwordx4 v[66:67], v[42:45], off offset:256 nt
	v_cndmask_b32_e64 v52, v138, 1.0, s[92:93]
	v_pk_mul_f32 v[48:49], v[48:49], v[52:53] op_sel_hi:[1,0]
	v_add_u32_e32 v42, 0x90, v158
	v_mad_i64_i32 v[42:43], s[6:7], v42, s90, v[130:131]
	v_lshl_add_u64 v[50:51], v[42:43], 0, v[132:133]
	v_pk_mul_f32 v[44:45], v[56:57], v[52:53] op_sel_hi:[1,0]
	v_pk_mul_f32 v[42:43], v[54:55], v[52:53] op_sel_hi:[1,0]
	v_pk_mul_f32 v[46:47], v[46:47], v[52:53] op_sel_hi:[1,0]
	v_cvt_pk_bf16_f32 v42, v42, v43
	v_cvt_pk_bf16_f32 v43, v44, v45
	v_cvt_pk_bf16_f32 v44, v46, v47
	v_cvt_pk_bf16_f32 v45, v48, v49
	global_store_dwordx4 v[50:51], v[42:45], off nt
	v_pk_mul_f32 v[36:37], v[36:37], v[52:53] op_sel_hi:[1,0]
	v_pk_mul_f32 v[34:35], v[34:35], v[52:53] op_sel_hi:[1,0]
	v_pk_mul_f32 v[42:43], v[28:29], v[52:53] op_sel_hi:[1,0]
	v_pk_mul_f32 v[28:29], v[26:27], v[52:53] op_sel_hi:[1,0]
	v_cvt_pk_bf16_f32 v26, v34, v35
	v_cvt_pk_bf16_f32 v27, v36, v37
	v_cvt_pk_bf16_f32 v28, v28, v29
	v_cvt_pk_bf16_f32 v29, v42, v43
	global_store_dwordx4 v[50:51], v[26:29], off offset:256 nt
	v_cndmask_b32_e64 v36, v135, 1.0, s[92:93]
	v_pk_mul_f32 v[32:33], v[32:33], v[36:37] op_sel_hi:[1,0]
	v_add_u32_e32 v26, 0xa0, v158
	v_mad_i64_i32 v[26:27], s[6:7], v26, s90, v[130:131]
	v_lshl_add_u64 v[34:35], v[26:27], 0, v[132:133]
	v_pk_mul_f32 v[28:29], v[40:41], v[36:37] op_sel_hi:[1,0]
	v_pk_mul_f32 v[26:27], v[38:39], v[36:37] op_sel_hi:[1,0]
	v_pk_mul_f32 v[30:31], v[30:31], v[36:37] op_sel_hi:[1,0]
	v_cvt_pk_bf16_f32 v26, v26, v27
	v_cvt_pk_bf16_f32 v27, v28, v29
	v_cvt_pk_bf16_f32 v28, v30, v31
	v_cvt_pk_bf16_f32 v29, v32, v33
	global_store_dwordx4 v[34:35], v[26:29], off nt
	v_pk_mul_f32 v[20:21], v[20:21], v[36:37] op_sel_hi:[1,0]
	v_pk_mul_f32 v[18:19], v[18:19], v[36:37] op_sel_hi:[1,0]
	v_pk_mul_f32 v[26:27], v[12:13], v[36:37] op_sel_hi:[1,0]
	v_pk_mul_f32 v[12:13], v[10:11], v[36:37] op_sel_hi:[1,0]
	v_cvt_pk_bf16_f32 v10, v18, v19
	v_cvt_pk_bf16_f32 v11, v20, v21
	v_cvt_pk_bf16_f32 v12, v12, v13
	v_cvt_pk_bf16_f32 v13, v26, v27
	global_store_dwordx4 v[34:35], v[10:13], off offset:256 nt
	v_cndmask_b32_e64 v20, v134, 1.0, s[92:93]
	v_pk_mul_f32 v[16:17], v[16:17], v[20:21] op_sel_hi:[1,0]
	v_add_u32_e32 v10, 0xb0, v158
	v_mad_i64_i32 v[10:11], s[6:7], v10, s90, v[130:131]
	v_lshl_add_u64 v[18:19], v[10:11], 0, v[132:133]
	v_pk_mul_f32 v[12:13], v[24:25], v[20:21] op_sel_hi:[1,0]
	v_pk_mul_f32 v[10:11], v[22:23], v[20:21] op_sel_hi:[1,0]
	v_pk_mul_f32 v[14:15], v[14:15], v[20:21] op_sel_hi:[1,0]
	v_cvt_pk_bf16_f32 v10, v10, v11
	v_cvt_pk_bf16_f32 v11, v12, v13
	v_cvt_pk_bf16_f32 v12, v14, v15
	v_cvt_pk_bf16_f32 v13, v16, v17
	global_store_dwordx4 v[18:19], v[10:13], off nt
	v_pk_mul_f32 v[8:9], v[8:9], v[20:21] op_sel_hi:[1,0]
	v_pk_mul_f32 v[6:7], v[6:7], v[20:21] op_sel_hi:[1,0]
	v_pk_mul_f32 v[10:11], v[4:5], v[20:21] op_sel_hi:[1,0]
	v_pk_mul_f32 v[4:5], v[2:3], v[20:21] op_sel_hi:[1,0]
	v_cvt_pk_bf16_f32 v2, v6, v7
	v_cvt_pk_bf16_f32 v3, v8, v9
	v_cvt_pk_bf16_f32 v4, v4, v5
	v_cvt_pk_bf16_f32 v5, v10, v11
	global_store_dwordx4 v[18:19], v[2:5], off offset:256 nt
	s_cbranch_vccnz .LBB0_1408
	s_andn2_b64 vcc, exec, s[8:9]
	s_cbranch_vccnz .LBB0_1407
	s_barrier
	s_branch .LBB0_1407

;     __device__ __forceinline__ void operator()(f32x4 (&acc)[2][2][4][2], const Unit& u, int wr, int wc, int fr, int fq) const {
;     ...
;             for (int m = 0; m < 4; ++m) { const int row = row0 + ai * HALF + m * 16; bf16_t* rowp = O + (size_t)row * ldc + col0;
;                 const float rs = ssq ? rsv[ai * 4 + m] : 1.0f;
; #pragma unroll
;                 for (int bj = 0; bj < 2; ++bj) { f32x4 v0 = acc[ai][bj][m][0] * rs, v1 = acc[ai][bj][m][1] * rs;
;                     if (ACT == 2) {
; #pragma unroll
;                         for (int j = 0; j < 4; ++j) { float a = v0[j] > 0.f ? v0[j] : 0.f; v0[j] = a * a; float b = v1[j] > 0.f ? v1[j] : 0.f; v1[j] = b * b; } }
;                     u32x4 w; w.x = cvt_pk_bf16(v0[0], v0[1]); w.y = cvt_pk_bf16(v0[2], v0[3]); w.z = cvt_pk_bf16(v1[0], v1[1]); w.w = cvt_pk_bf16(v1[2], v1[3]);
;                     *(u32x4*)(rowp + bj * HALF) = w; } }
.LBB0_1443:
	v_mov_b32_e32 v139, v246
	s_lshl_b32 s3, s10, 8
	s_add_i32 s3, s3, s74
	v_and_or_b32 v140, v139, 15, s3
	v_lshrrev_b32_e32 v139, 1, v139
	s_lshl_b32 s3, s95, 8
	v_and_or_b32 v139, v139, 24, s3
	v_ashrrev_i32_e32 v141, 31, v140
	v_or_b32_e32 v142, s75, v139
	v_ashrrev_i32_e32 v143, 31, v142
	v_lshlrev_b64 v[144:145], 12, v[140:141]
	v_lshl_add_u64 v[144:145], s[56:57], 0, v[144:145]
	v_lshlrev_b64 v[142:143], 1, v[142:143]
	v_lshl_add_u64 v[144:145], v[144:145], 0, v[142:143]
	s_mov_b32 s3, 0x80000
	s_mov_b64 s[12:13], 0x80000
	v_cvt_pk_bf16_f32 v62, v62, v63
	v_cvt_pk_bf16_f32 v63, v64, v65
	v_cvt_pk_bf16_f32 v64, v58, v59
	v_add_co_u32_e32 v58, vcc, s3, v144
	v_cvt_pk_bf16_f32 v70, v70, v71
	v_cvt_pk_bf16_f32 v71, v72, v73
	v_cvt_pk_bf16_f32 v72, v66, v67
	v_lshl_add_u64 v[66:67], v[144:145], 0, s[12:13]
	v_addc_co_u32_e32 v59, vcc, 0, v145, vcc
	v_cvt_pk_bf16_f32 v46, v46, v47
	v_cvt_pk_bf16_f32 v47, v48, v49
	v_cvt_pk_bf16_f32 v48, v42, v43
	v_cvt_pk_bf16_f32 v49, v44, v45
	s_mov_b32 s3, 0x90000
	v_cvt_pk_bf16_f32 v110, v110, v111
	v_cvt_pk_bf16_f32 v111, v112, v113
	v_cvt_pk_bf16_f32 v112, v106, v107
	v_or_b32_e32 v106, 16, v140
	global_store_dwordx4 v[66:67], v[46:49], off offset:256 nt
	s_mov_b64 s[12:13], 0x90000
	v_ashrrev_i32_e32 v107, 31, v106
	v_add_co_u32_e32 v48, vcc, s3, v144
	v_cvt_pk_bf16_f32 v94, v94, v95
	v_cvt_pk_bf16_f32 v95, v96, v97
	v_cvt_pk_bf16_f32 v96, v90, v91
	v_or_b32_e32 v90, 32, v140
	v_lshl_add_u64 v[46:47], v[144:145], 0, s[12:13]
	v_addc_co_u32_e32 v49, vcc, 0, v145, vcc
	v_cvt_pk_bf16_f32 v30, v30, v31
	v_cvt_pk_bf16_f32 v31, v32, v33
	v_cvt_pk_bf16_f32 v32, v26, v27
	v_cvt_pk_bf16_f32 v33, v28, v29
	s_mov_b32 s3, 0xa0000
	v_lshlrev_b64 v[106:107], 12, v[106:107]
	v_ashrrev_i32_e32 v91, 31, v90
	v_cvt_pk_bf16_f32 v78, v78, v79
	v_cvt_pk_bf16_f32 v79, v80, v81
	v_cvt_pk_bf16_f32 v80, v74, v75
	v_or_b32_e32 v74, 48, v140
	global_store_dwordx4 v[46:47], v[30:33], off offset:256 nt
	s_mov_b64 s[12:13], 0xa0000
	v_cvt_pk_bf16_f32 v113, v108, v109
	v_add_co_u32_e32 v32, vcc, s3, v144
	v_lshl_add_u64 v[106:107], s[56:57], 0, v[106:107]
	v_lshlrev_b64 v[90:91], 12, v[90:91]
	v_ashrrev_i32_e32 v75, 31, v74
	v_lshl_add_u64 v[30:31], v[144:145], 0, s[12:13]
	v_addc_co_u32_e32 v33, vcc, 0, v145, vcc
	v_cvt_pk_bf16_f32 v14, v14, v15
	v_cvt_pk_bf16_f32 v15, v16, v17
	v_cvt_pk_bf16_f32 v16, v10, v11
	v_cvt_pk_bf16_f32 v17, v12, v13
	global_store_dwordx4 v[144:145], v[110:113], off offset:256 nt
	v_cvt_pk_bf16_f32 v97, v92, v93
	v_lshl_add_u64 v[90:91], s[56:57], 0, v[90:91]
	v_lshl_add_u64 v[110:111], v[106:107], 0, v[142:143]
	v_lshlrev_b64 v[74:75], 12, v[74:75]
	global_store_dwordx4 v[30:31], v[14:17], off offset:256 nt
	global_store_dwordx4 v[110:111], v[94:97], off offset:256 nt
	v_cvt_pk_bf16_f32 v81, v76, v77
	v_add_co_u32_e32 v16, vcc, 0xb0000, v144
	v_lshl_add_u64 v[94:95], v[90:91], 0, v[142:143]
	v_lshl_add_u64 v[74:75], s[56:57], 0, v[74:75]
	s_mov_b64 s[12:13], 0xb0000
	v_addc_co_u32_e32 v17, vcc, 0, v145, vcc
	v_readlane_b32 s30, v255, 26
	v_cvt_pk_bf16_f32 v126, v126, v127
	v_cvt_pk_bf16_f32 v127, v128, v129
	v_cvt_pk_bf16_f32 v128, v122, v123
	v_cvt_pk_bf16_f32 v129, v124, v125
	v_cvt_pk_bf16_f32 v106, v118, v119
	v_cvt_pk_bf16_f32 v107, v120, v121
	v_cvt_pk_bf16_f32 v108, v114, v115
	v_cvt_pk_bf16_f32 v109, v116, v117
	v_cvt_pk_bf16_f32 v90, v102, v103
	v_cvt_pk_bf16_f32 v91, v104, v105
	v_cvt_pk_bf16_f32 v92, v98, v99
	v_cvt_pk_bf16_f32 v93, v100, v101
	global_store_dwordx4 v[94:95], v[78:81], off offset:256 nt
	v_cvt_pk_bf16_f32 v76, v82, v83
	v_cvt_pk_bf16_f32 v77, v84, v85
	v_lshl_add_u64 v[78:79], v[74:75], 0, v[142:143]
	v_cvt_pk_bf16_f32 v74, v86, v87
	v_cvt_pk_bf16_f32 v75, v88, v89
	v_cvt_pk_bf16_f32 v73, v68, v69
	v_cvt_pk_bf16_f32 v65, v60, v61
	v_cvt_pk_bf16_f32 v42, v54, v55
	v_cvt_pk_bf16_f32 v43, v56, v57
	v_cvt_pk_bf16_f32 v44, v50, v51
	v_cvt_pk_bf16_f32 v45, v52, v53
	v_cvt_pk_bf16_f32 v26, v38, v39
	v_cvt_pk_bf16_f32 v27, v40, v41
	v_cvt_pk_bf16_f32 v28, v34, v35
	v_cvt_pk_bf16_f32 v29, v36, v37
	v_lshl_add_u64 v[14:15], v[144:145], 0, s[12:13]
	v_cvt_pk_bf16_f32 v10, v22, v23
	v_cvt_pk_bf16_f32 v11, v24, v25
	v_cvt_pk_bf16_f32 v12, v18, v19
	v_cvt_pk_bf16_f32 v13, v20, v21
	v_cvt_pk_bf16_f32 v6, v6, v7
	v_cvt_pk_bf16_f32 v7, v8, v9
	v_cvt_pk_bf16_f32 v8, v2, v3
	v_cvt_pk_bf16_f32 v9, v4, v5
	s_andn2_b64 vcc, exec, s[4:5]
	s_mov_b64 s[4:5], -1
	v_readlane_b32 s31, v255, 27
	global_store_dwordx4 v[144:145], v[126:129], off nt
	global_store_dwordx4 v[110:111], v[106:109], off nt
	global_store_dwordx4 v[94:95], v[90:93], off nt
	global_store_dwordx4 v[78:79], v[74:77], off nt
	global_store_dwordx4 v[78:79], v[70:73], off offset:256 nt
	global_store_dwordx4 v[58:59], v[62:65], off nt
	global_store_dwordx4 v[48:49], v[42:45], off nt
	global_store_dwordx4 v[32:33], v[26:29], off nt
	global_store_dwordx4 v[16:17], v[10:13], off nt
	global_store_dwordx4 v[14:15], v[6:9], off offset:256 nt
	s_cbranch_vccnz .LBB0_1432
	s_andn2_b64 vcc, exec, s[6:7]
	s_cbranch_vccnz .LBB0_1431
	s_barrier
	s_branch .LBB0_1431

; __device__ __forceinline__ float ssq4(const f32x4 o) { return (o[0] * o[0] + o[1] * o[1]) + (o[2] * o[2] + o[3] * o[3]); }
;     __device__ __forceinline__ void operator()(f32x4 (&acc)[2][2][4][2], const Unit& u, int wr, int wc, int fr, int fq) const {
;     ...
;         f32x4 cur[2][4], nxt[2][4];
; #pragma unroll
;         for (int q = 0; q < 2; ++q)
; #pragma unroll
;             for (int c = 0; c < 4; ++c) cur[q][c] = *(const f32x4*)(base + (size_t)EPI_ROW(q) * D + col0 + (c >> 1) * HALF + (c & 1) * 4);
; #pragma unroll
;         for (int k = 0; k < 4; ++k) {
;             if (k < 3) {
; #pragma unroll
;                 for (int q = 0; q < 2; ++q)
; #pragma unroll
;                     for (int c = 0; c < 4; ++c) nxt[q][c] = *(const f32x4*)(base + (size_t)EPI_ROW(2 * k + 2 + q) * D + col0 + (c >> 1) * HALF + (c & 1) * 4);
;             }
;             asm volatile("" ::: "memory");
; #pragma unroll
;             for (int q = 0; q < 2; ++q) { const int r = 2 * k + q, ai = r >> 2, m = r & 3; const size_t off = (size_t)EPI_ROW(r) * D + col0; float sr = 0.f;
; #pragma unroll
;                 for (int bj = 0; bj < 2; ++bj) { const f32x4 o0 = cur[q][2 * bj] + acc[ai][bj][m][0], o1 = cur[q][2 * bj + 1] + acc[ai][bj][m][1];
;                     *(f32x4*)(out + off + bj * HALF) = o0; *(f32x4*)(out + off + bj * HALF + 4) = o1;
;                     u32x4 w; w.x = cvt_pk_bf16(o0[0], o0[1]); w.y = cvt_pk_bf16(o0[2], o0[3]); w.z = cvt_pk_bf16(o1[0], o1[1]); w.w = cvt_pk_bf16(o1[2], o1[3]); *(u32x4*)(hb + off + bj * HALF) = w; sr += ssq4(o0) + ssq4(o1); }
;                 s[ai][m] = sr; }
.LBB0_2038:
	v_mov_b32_e32 v185, v246
	s_lshl_b32 s1, s6, 8
	s_or_b32 s1, s1, s45
	v_bfe_u32 v184, v185, 4, 2
	v_lshl_or_b32 v200, v184, 3, s1
	s_lshl_b32 s1, s22, 8
	v_and_b32_e32 v183, 15, v185
	s_add_i32 s3, s1, s44
	v_or_b32_e32 v202, s3, v183
	v_readlane_b32 s14, v255, 40
	v_ashrrev_i32_e32 v203, 31, v202
	v_ashrrev_i32_e32 v201, 31, v200
	v_readlane_b32 s15, v255, 41
	v_lshlrev_b64 v[130:131], 13, v[202:203]
	v_or_b32_e32 v178, 16, v202
	v_lshl_add_u64 v[204:205], v[200:201], 2, s[14:15]
	v_lshl_add_u64 v[130:131], v[204:205], 0, v[130:131]
	global_load_dwordx4 v[210:213], v[130:131], off offset:16
	global_load_dwordx4 v[214:217], v[130:131], off
	global_load_dwordx4 v[218:221], v[130:131], off offset:528
	global_load_dwordx4 v[222:225], v[130:131], off offset:512
	v_ashrrev_i32_e32 v179, 31, v178
	v_lshlrev_b64 v[130:131], 13, v[178:179]
	v_lshl_add_u64 v[130:131], v[204:205], 0, v[130:131]
	global_load_dwordx4 v[170:173], v[130:131], off offset:16
	global_load_dwordx4 v[174:177], v[130:131], off
	global_load_dwordx4 v[162:165], v[130:131], off offset:528
	global_load_dwordx4 v[166:169], v[130:131], off offset:512
	v_or_b32_e32 v208, 32, v202
	v_ashrrev_i32_e32 v209, 31, v208
	v_lshlrev_b64 v[130:131], 13, v[208:209]
	v_lshl_add_u64 v[130:131], v[204:205], 0, v[130:131]
	v_or_b32_e32 v206, 48, v202
	global_load_dwordx4 v[154:157], v[130:131], off offset:16
	global_load_dwordx4 v[158:161], v[130:131], off
	global_load_dwordx4 v[138:141], v[130:131], off offset:528
	global_load_dwordx4 v[142:145], v[130:131], off offset:512
	v_ashrrev_i32_e32 v207, 31, v206
	v_lshlrev_b64 v[130:131], 13, v[206:207]
	v_lshl_add_u64 v[134:135], v[204:205], 0, v[130:131]
	global_load_dwordx4 v[146:149], v[134:135], off offset:16
	global_load_dwordx4 v[150:153], v[134:135], off
	global_load_dwordx4 v[130:133], v[134:135], off offset:528
	s_nop 0
	global_load_dwordx4 v[134:137], v[134:135], off offset:512
	v_lshlrev_b64 v[226:227], 11, v[202:203]
	v_lshl_add_u64 v[226:227], v[226:227], 0, v[200:201]
	v_lshlrev_b64 v[208:209], 11, v[208:209]
	v_lshl_add_u64 v[208:209], v[208:209], 0, v[200:201]
	v_cmp_eq_u32_e32 vcc, 0, v184
	s_waitcnt vmcnt(0)
	v_pk_add_f32 v[122:123], v[122:123], v[210:211]
	v_pk_add_f32 v[128:129], v[128:129], v[216:217]
	v_pk_add_f32 v[126:127], v[126:127], v[214:215]
	v_lshl_add_u64 v[214:215], v[226:227], 2, s[36:37]
	v_pk_add_f32 v[124:125], v[124:125], v[212:213]
	global_store_dwordx4 v[214:215], v[126:129], off nt
	global_store_dwordx4 v[214:215], v[122:125], off offset:16 nt
	v_cvt_pk_bf16_f32 v210, v126, v127
	v_cvt_pk_bf16_f32 v212, v122, v123
	v_mul_f32_e32 v127, v127, v127
	v_mul_f32_e32 v123, v123, v123
	v_fmac_f32_e32 v127, v126, v126
	v_mul_f32_e32 v126, v129, v129
	v_fmac_f32_e32 v123, v122, v122
	v_mul_f32_e32 v122, v125, v125
	v_fmac_f32_e32 v126, v128, v128
	v_fmac_f32_e32 v122, v124, v124
	v_cvt_pk_bf16_f32 v211, v128, v129
	v_cvt_pk_bf16_f32 v213, v124, v125
	v_lshl_add_u64 v[216:217], v[226:227], 1, s[54:55]
	v_add_f32_e32 v126, v127, v126
	v_add_f32_e32 v122, v123, v122
	v_pk_add_f32 v[120:121], v[120:121], v[224:225]
	v_pk_add_f32 v[118:119], v[118:119], v[222:223]
	v_pk_add_f32 v[114:115], v[114:115], v[218:219]
	global_store_dwordx4 v[216:217], v[210:213], off
	v_add_f32_e32 v126, v126, v122
	v_pk_add_f32 v[116:117], v[116:117], v[220:221]
	global_store_dwordx4 v[214:215], v[118:121], off offset:512 nt
	global_store_dwordx4 v[214:215], v[114:117], off offset:528 nt
	v_cvt_pk_bf16_f32 v122, v118, v119
	v_cvt_pk_bf16_f32 v124, v114, v115
	v_mul_f32_e32 v119, v119, v119
	v_mul_f32_e32 v115, v115, v115
	v_fmac_f32_e32 v119, v118, v118
	v_mul_f32_e32 v118, v121, v121
	v_fmac_f32_e32 v115, v114, v114
	v_mul_f32_e32 v114, v117, v117
	v_fmac_f32_e32 v118, v120, v120
	v_fmac_f32_e32 v114, v116, v116
	v_add_f32_e32 v118, v119, v118
	v_add_f32_e32 v114, v115, v114
	v_add_f32_e32 v114, v118, v114
	v_add_f32_e32 v187, v126, v114
	v_lshlrev_b64 v[114:115], 11, v[178:179]
	v_lshl_add_u64 v[118:119], v[114:115], 0, v[200:201]
	v_pk_add_f32 v[112:113], v[112:113], v[176:177]
	v_pk_add_f32 v[110:111], v[110:111], v[174:175]
	v_pk_add_f32 v[108:109], v[108:109], v[172:173]
	v_pk_add_f32 v[106:107], v[106:107], v[170:171]
	v_cvt_pk_bf16_f32 v123, v120, v121
	v_cvt_pk_bf16_f32 v125, v116, v117
	v_lshl_add_u64 v[120:121], v[118:119], 2, s[36:37]
	v_cvt_pk_bf16_f32 v114, v110, v111
	v_cvt_pk_bf16_f32 v115, v112, v113
	v_cvt_pk_bf16_f32 v116, v106, v107
	v_cvt_pk_bf16_f32 v117, v108, v109
	v_lshl_add_u64 v[118:119], v[118:119], 1, s[54:55]
	v_pk_add_f32 v[104:105], v[104:105], v[168:169]
	v_pk_add_f32 v[102:103], v[102:103], v[166:167]
	v_pk_add_f32 v[100:101], v[100:101], v[164:165]
	v_pk_add_f32 v[98:99], v[98:99], v[162:163]
	v_add_u32_e32 v210, 0x80, v202
	global_store_dwordx4 v[216:217], v[122:125], off offset:256 nt
	global_store_dwordx4 v[120:121], v[110:113], off nt
	global_store_dwordx4 v[120:121], v[106:109], off offset:16 nt
	global_store_dwordx4 v[118:119], v[114:117], off nt
	v_ashrrev_i32_e32 v211, 31, v210
	global_store_dwordx4 v[120:121], v[102:105], off offset:512 nt
	global_store_dwordx4 v[120:121], v[98:101], off offset:528 nt
	v_cvt_pk_bf16_f32 v114, v102, v103
	v_cvt_pk_bf16_f32 v115, v104, v105
	v_cvt_pk_bf16_f32 v116, v98, v99
	v_cvt_pk_bf16_f32 v117, v100, v101
	global_store_dwordx4 v[118:119], v[114:117], off offset:256 nt
	v_add_u32_e32 v170, 0x90, v202
	v_ashrrev_i32_e32 v171, 31, v170
	v_lshlrev_b64 v[114:115], 13, v[210:211]
	v_lshl_add_u64 v[114:115], v[204:205], 0, v[114:115]
	global_load_dwordx4 v[172:175], v[114:115], off offset:16
	global_load_dwordx4 v[176:179], v[114:115], off
; __device__ __forceinline__ float ssq4(const f32x4 o) { return (o[0] * o[0] + o[1] * o[1]) + (o[2] * o[2] + o[3] * o[3]); }
;     __device__ __forceinline__ void operator()(f32x4 (&acc)[2][2][4][2], const Unit& u, int wr, int wc, int fr, int fq) const {
;     ...
;         for (int k = 0; k < 4; ++k) {
;             if (k < 3) {
; #pragma unroll
;                 for (int q = 0; q < 2; ++q)
; #pragma unroll
;                     for (int c = 0; c < 4; ++c) nxt[q][c] = *(const f32x4*)(base + (size_t)EPI_ROW(2 * k + 2 + q) * D + col0 + (c >> 1) * HALF + (c & 1) * 4);
;             }
;             asm volatile("" ::: "memory");
; #pragma unroll
;             for (int q = 0; q < 2; ++q) { const int r = 2 * k + q, ai = r >> 2, m = r & 3; const size_t off = (size_t)EPI_ROW(r) * D + col0; float sr = 0.f;
; #pragma unroll
;                 for (int bj = 0; bj < 2; ++bj) { const f32x4 o0 = cur[q][2 * bj] + acc[ai][bj][m][0], o1 = cur[q][2 * bj + 1] + acc[ai][bj][m][1];
;                     *(f32x4*)(out + off + bj * HALF) = o0; *(f32x4*)(out + off + bj * HALF + 4) = o1;
;                     u32x4 w; w.x = cvt_pk_bf16(o0[0], o0[1]); w.y = cvt_pk_bf16(o0[2], o0[3]); w.z = cvt_pk_bf16(o1[0], o1[1]); w.w = cvt_pk_bf16(o1[2], o1[3]); *(u32x4*)(hb + off + bj * HALF) = w; sr += ssq4(o0) + ssq4(o1); }
;                 s[ai][m] = sr; }
	global_load_dwordx4 v[162:165], v[114:115], off offset:528
	global_load_dwordx4 v[166:169], v[114:115], off offset:512
	v_lshlrev_b64 v[114:115], 13, v[170:171]
	v_pk_add_f32 v[96:97], v[96:97], v[160:161]
	v_pk_add_f32 v[94:95], v[94:95], v[158:159]
	v_pk_add_f32 v[92:93], v[92:93], v[156:157]
	v_pk_add_f32 v[90:91], v[90:91], v[154:155]
	v_pk_add_f32 v[88:89], v[88:89], v[144:145]
	v_pk_add_f32 v[86:87], v[86:87], v[142:143]
	v_pk_add_f32 v[80:81], v[80:81], v[140:141]
	v_pk_add_f32 v[78:79], v[78:79], v[138:139]
	v_lshl_add_u64 v[118:119], v[204:205], 0, v[114:115]
	v_lshl_add_u64 v[158:159], v[208:209], 2, s[36:37]
	v_cvt_pk_bf16_f32 v154, v94, v95
	v_cvt_pk_bf16_f32 v155, v96, v97
	v_cvt_pk_bf16_f32 v156, v90, v91
	v_cvt_pk_bf16_f32 v157, v92, v93
	v_lshl_add_u64 v[160:161], v[208:209], 1, s[54:55]
	v_cvt_pk_bf16_f32 v138, v86, v87
	v_cvt_pk_bf16_f32 v139, v88, v89
	v_cvt_pk_bf16_f32 v140, v78, v79
	v_cvt_pk_bf16_f32 v141, v80, v81
	global_load_dwordx4 v[122:125], v[118:119], off offset:16
	global_load_dwordx4 v[126:129], v[118:119], off
	global_load_dwordx4 v[114:117], v[118:119], off offset:528
	s_nop 0
	global_load_dwordx4 v[118:121], v[118:119], off offset:512
	global_store_dwordx4 v[158:159], v[94:97], off nt
	global_store_dwordx4 v[158:159], v[90:93], off offset:16 nt
	global_store_dwordx4 v[160:161], v[154:157], off
	global_store_dwordx4 v[158:159], v[86:89], off offset:512 nt
	global_store_dwordx4 v[158:159], v[78:81], off offset:528 nt
	global_store_dwordx4 v[160:161], v[138:141], off offset:256
	v_pk_add_f32 v[84:85], v[84:85], v[152:153]
	v_pk_add_f32 v[82:83], v[82:83], v[150:151]
	v_lshlrev_b64 v[138:139], 11, v[206:207]
	v_lshl_add_u64 v[142:143], v[138:139], 0, v[200:201]
	v_pk_add_f32 v[76:77], v[76:77], v[148:149]
	v_pk_add_f32 v[74:75], v[74:75], v[146:147]
	v_pk_add_f32 v[72:73], v[72:73], v[136:137]
	v_pk_add_f32 v[70:71], v[70:71], v[134:135]
	v_pk_add_f32 v[68:69], v[68:69], v[132:133]
	v_pk_add_f32 v[66:67], v[66:67], v[130:131]
	v_add_u32_e32 v206, 0xa0, v202
	v_lshl_add_u64 v[144:145], v[142:143], 2, s[36:37]
	v_cvt_pk_bf16_f32 v138, v82, v83
	v_cvt_pk_bf16_f32 v139, v84, v85
	v_cvt_pk_bf16_f32 v140, v74, v75
	v_cvt_pk_bf16_f32 v141, v76, v77
	v_lshl_add_u64 v[142:143], v[142:143], 1, s[54:55]
	v_cvt_pk_bf16_f32 v130, v70, v71
	v_cvt_pk_bf16_f32 v131, v72, v73
	v_cvt_pk_bf16_f32 v132, v66, v67
	v_cvt_pk_bf16_f32 v133, v68, v69
	v_ashrrev_i32_e32 v207, 31, v206
	global_store_dwordx4 v[144:145], v[82:85], off nt
	global_store_dwordx4 v[144:145], v[74:77], off offset:16 nt
	global_store_dwordx4 v[142:143], v[138:141], off
	global_store_dwordx4 v[144:145], v[70:73], off offset:512 nt
	global_store_dwordx4 v[144:145], v[66:69], off offset:528 nt
	global_store_dwordx4 v[142:143], v[130:133], off offset:256
	v_add_u32_e32 v202, 0xb0, v202
	v_ashrrev_i32_e32 v203, 31, v202
	v_lshlrev_b64 v[130:131], 13, v[206:207]
	v_lshl_add_u64 v[142:143], v[204:205], 0, v[130:131]
	global_load_dwordx4 v[130:133], v[142:143], off offset:16
	global_load_dwordx4 v[134:137], v[142:143], off
	global_load_dwordx4 v[138:141], v[142:143], off offset:528
	s_nop 0
	global_load_dwordx4 v[142:145], v[142:143], off offset:512
	v_lshlrev_b64 v[146:147], 13, v[202:203]
	v_lshl_add_u64 v[158:159], v[204:205], 0, v[146:147]
	global_load_dwordx4 v[146:149], v[158:159], off offset:16
	global_load_dwordx4 v[150:153], v[158:159], off
	global_load_dwordx4 v[154:157], v[158:159], off offset:528
	s_nop 0
	global_load_dwordx4 v[158:161], v[158:159], off offset:512
	v_lshlrev_b64 v[204:205], 11, v[210:211]
	v_lshl_add_u64 v[204:205], v[204:205], 0, v[200:201]
	s_waitcnt vmcnt(27)
	v_pk_add_f32 v[60:61], v[60:61], v[174:175]
	s_waitcnt vmcnt(26)
	v_pk_add_f32 v[64:65], v[64:65], v[178:179]
	v_pk_add_f32 v[62:63], v[62:63], v[176:177]
	v_pk_add_f32 v[58:59], v[58:59], v[172:173]
	s_waitcnt vmcnt(24)
	v_pk_add_f32 v[56:57], v[56:57], v[168:169]
	v_pk_add_f32 v[54:55], v[54:55], v[166:167]
	v_pk_add_f32 v[48:49], v[48:49], v[164:165]
	v_pk_add_f32 v[46:47], v[46:47], v[162:163]
	v_lshl_add_u64 v[176:177], v[204:205], 2, s[36:37]
	v_cvt_pk_bf16_f32 v172, v62, v63
	v_cvt_pk_bf16_f32 v173, v64, v65
	v_cvt_pk_bf16_f32 v174, v58, v59
	v_cvt_pk_bf16_f32 v175, v60, v61
	v_lshl_add_u64 v[178:179], v[204:205], 1, s[54:55]
	v_cvt_pk_bf16_f32 v162, v54, v55
	v_cvt_pk_bf16_f32 v163, v56, v57
	v_cvt_pk_bf16_f32 v164, v46, v47
	v_cvt_pk_bf16_f32 v165, v48, v49
	global_store_dwordx4 v[176:177], v[62:65], off nt
	global_store_dwordx4 v[176:177], v[58:61], off offset:16 nt
	global_store_dwordx4 v[178:179], v[172:175], off
	global_store_dwordx4 v[176:177], v[54:57], off offset:512 nt
	global_store_dwordx4 v[176:177], v[46:49], off offset:528 nt
	global_store_dwordx4 v[178:179], v[162:165], off offset:256
	s_waitcnt vmcnt(28)
; __device__ __forceinline__ float shx(float v, int o, int lane) { return __builtin_bit_cast(float, __builtin_amdgcn_ds_bpermute((lane ^ o) << 2, __builtin_bit_cast(int, v))); }
; __device__ __forceinline__ float ssq4(const f32x4 o) { return (o[0] * o[0] + o[1] * o[1]) + (o[2] * o[2] + o[3] * o[3]); }
; template <bool SIXTEEN> __device__ __forceinline__ void tile_ssq(const float (&s)[2][4], const Unit& u, int wr, int wc, int fr, int fq, float* ssq, LAS float* ptab) {
;     ...
;         for (int m = 0; m < 4; ++m) { float v = s[ai][m]; v += shx(v, 16, lane); v += shx(v, 32, lane); if (fq == 0) ptab[(ai * HALF + wr * 64 + m * 16 + fr) * 4 + wc] = v; }
;     __device__ __forceinline__ void operator()(f32x4 (&acc)[2][2][4][2], const Unit& u, int wr, int wc, int fr, int fq) const {
;     ...
;             for (int q = 0; q < 2; ++q) { const int r = 2 * k + q, ai = r >> 2, m = r & 3; const size_t off = (size_t)EPI_ROW(r) * D + col0; float sr = 0.f;
; #pragma unroll
;                 for (int bj = 0; bj < 2; ++bj) { const f32x4 o0 = cur[q][2 * bj] + acc[ai][bj][m][0], o1 = cur[q][2 * bj + 1] + acc[ai][bj][m][1];
;                     *(f32x4*)(out + off + bj * HALF) = o0; *(f32x4*)(out + off + bj * HALF + 4) = o1;
;                     u32x4 w; w.x = cvt_pk_bf16(o0[0], o0[1]); w.y = cvt_pk_bf16(o0[2], o0[3]); w.z = cvt_pk_bf16(o1[0], o1[1]); w.w = cvt_pk_bf16(o1[2], o1[3]); *(u32x4*)(hb + off + bj * HALF) = w; sr += ssq4(o0) + ssq4(o1); }
;                 s[ai][m] = sr; }
	v_pk_add_f32 v[52:53], v[52:53], v[128:129]
	v_pk_add_f32 v[50:51], v[50:51], v[126:127]
	v_lshlrev_b64 v[162:163], 11, v[170:171]
	v_lshl_add_u64 v[162:163], v[162:163], 0, v[200:201]
	v_pk_add_f32 v[44:45], v[44:45], v[124:125]
	v_pk_add_f32 v[42:43], v[42:43], v[122:123]
	s_waitcnt vmcnt(26)
	v_pk_add_f32 v[40:41], v[40:41], v[120:121]
	v_pk_add_f32 v[38:39], v[38:39], v[118:119]
	v_pk_add_f32 v[36:37], v[36:37], v[116:117]
	v_pk_add_f32 v[34:35], v[34:35], v[114:115]
	v_lshl_add_u64 v[126:127], v[162:163], 2, s[36:37]
	v_cvt_pk_bf16_f32 v122, v50, v51
	v_cvt_pk_bf16_f32 v123, v52, v53
	v_cvt_pk_bf16_f32 v124, v42, v43
	v_cvt_pk_bf16_f32 v125, v44, v45
	v_lshl_add_u64 v[128:129], v[162:163], 1, s[54:55]
	v_cvt_pk_bf16_f32 v114, v38, v39
	v_cvt_pk_bf16_f32 v115, v40, v41
	v_cvt_pk_bf16_f32 v116, v34, v35
	v_cvt_pk_bf16_f32 v117, v36, v37
	global_store_dwordx4 v[126:127], v[50:53], off nt
	global_store_dwordx4 v[126:127], v[42:45], off offset:16 nt
	global_store_dwordx4 v[128:129], v[122:125], off nt
	global_store_dwordx4 v[126:127], v[38:41], off offset:512 nt
	global_store_dwordx4 v[126:127], v[34:37], off offset:528 nt
	global_store_dwordx4 v[128:129], v[114:117], off offset:256 nt
	s_waitcnt vmcnt(19)
	v_pk_add_f32 v[28:29], v[28:29], v[132:133]
	v_lshlrev_b64 v[114:115], 11, v[206:207]
	v_lshl_add_u64 v[118:119], v[114:115], 0, v[200:201]
	s_waitcnt vmcnt(18)
	v_pk_add_f32 v[32:33], v[32:33], v[136:137]
	v_pk_add_f32 v[30:31], v[30:31], v[134:135]
	v_pk_add_f32 v[26:27], v[26:27], v[130:131]
	v_lshl_add_u64 v[120:121], v[118:119], 2, s[36:37]
	v_cvt_pk_bf16_f32 v114, v30, v31
	v_cvt_pk_bf16_f32 v115, v32, v33
	v_cvt_pk_bf16_f32 v116, v26, v27
	v_cvt_pk_bf16_f32 v117, v28, v29
	v_lshl_add_u64 v[118:119], v[118:119], 1, s[54:55]
	s_waitcnt vmcnt(16)
	v_pk_add_f32 v[24:25], v[24:25], v[144:145]
	v_pk_add_f32 v[22:23], v[22:23], v[142:143]
	v_pk_add_f32 v[16:17], v[16:17], v[140:141]
	v_pk_add_f32 v[14:15], v[14:15], v[138:139]
	global_store_dwordx4 v[120:121], v[30:33], off nt
	global_store_dwordx4 v[120:121], v[26:29], off offset:16 nt
	global_store_dwordx4 v[118:119], v[114:117], off nt
	global_store_dwordx4 v[120:121], v[22:25], off offset:512 nt
	global_store_dwordx4 v[120:121], v[14:17], off offset:528 nt
	v_cvt_pk_bf16_f32 v114, v22, v23
	v_cvt_pk_bf16_f32 v115, v24, v25
	v_cvt_pk_bf16_f32 v116, v14, v15
	v_cvt_pk_bf16_f32 v117, v16, v17
	global_store_dwordx4 v[118:119], v[114:117], off offset:256 nt
	s_waitcnt vmcnt(20)
	v_pk_add_f32 v[20:21], v[20:21], v[152:153]
	v_pk_add_f32 v[18:19], v[18:19], v[150:151]
	v_lshlrev_b64 v[114:115], 11, v[202:203]
	v_lshl_add_u64 v[118:119], v[114:115], 0, v[200:201]
	v_pk_add_f32 v[12:13], v[12:13], v[148:149]
	v_pk_add_f32 v[10:11], v[10:11], v[146:147]
	v_lshl_add_u64 v[120:121], v[118:119], 2, s[36:37]
	v_cvt_pk_bf16_f32 v114, v18, v19
	v_cvt_pk_bf16_f32 v115, v20, v21
	v_cvt_pk_bf16_f32 v116, v10, v11
	v_cvt_pk_bf16_f32 v117, v12, v13
	v_lshl_add_u64 v[118:119], v[118:119], 1, s[54:55]
	s_waitcnt vmcnt(18)
	v_pk_add_f32 v[8:9], v[8:9], v[160:161]
	v_pk_add_f32 v[6:7], v[6:7], v[158:159]
	v_pk_add_f32 v[4:5], v[4:5], v[156:157]
	v_pk_add_f32 v[2:3], v[2:3], v[154:155]
	global_store_dwordx4 v[120:121], v[18:21], off nt
	global_store_dwordx4 v[120:121], v[10:13], off offset:16 nt
	global_store_dwordx4 v[118:119], v[114:117], off nt
	global_store_dwordx4 v[120:121], v[6:9], off offset:512 nt
	global_store_dwordx4 v[120:121], v[2:5], off offset:528 nt
	v_cvt_pk_bf16_f32 v114, v6, v7
	v_cvt_pk_bf16_f32 v115, v8, v9
	v_cvt_pk_bf16_f32 v116, v2, v3
	v_cvt_pk_bf16_f32 v117, v4, v5
	global_store_dwordx4 v[118:119], v[114:117], off offset:256 nt
	s_nop 1
	v_and_b32_e32 v114, 63, v185
	v_lshlrev_b32_e32 v115, 2, v114
	v_xor_b32_e32 v116, 64, v115
	ds_bpermute_b32 v117, v116, v187
	v_xor_b32_e32 v115, 0x80, v115
	s_waitcnt lgkmcnt(0)
	v_add_f32_e32 v118, v187, v117
	ds_bpermute_b32 v119, v115, v118
	v_lshl_add_u32 v117, v183, 4, s91
	s_and_saveexec_b64 s[14:15], vcc
	s_cbranch_execz .LBB0_2040
	s_waitcnt lgkmcnt(0)
	v_add_f32_e32 v118, v118, v119
	ds_write_b32 v117, v118

;     __device__ __forceinline__ void operator()(f32x4 (&acc)[2][2][4][2], const Unit& u, int wr, int wc, int fr, int fq) const {
;     ...
;             for (int m = 0; m < 4; ++m) { const int row = row0 + ai * HALF + m * 16; bf16_t* rowp = O + (size_t)row * ldc + col0;
;                 const float rs = ssq ? rsv[ai * 4 + m] : 1.0f;
; #pragma unroll
;                 for (int bj = 0; bj < 2; ++bj) { f32x4 v0 = acc[ai][bj][m][0] * rs, v1 = acc[ai][bj][m][1] * rs;
;                     if (ACT == 2) {
; #pragma unroll
;                         for (int j = 0; j < 4; ++j) { float a = v0[j] > 0.f ? v0[j] : 0.f; v0[j] = a * a; float b = v1[j] > 0.f ? v1[j] : 0.f; v1[j] = b * b; } }
;                     u32x4 w; w.x = cvt_pk_bf16(v0[0], v0[1]); w.y = cvt_pk_bf16(v0[2], v0[3]); w.z = cvt_pk_bf16(v1[0], v1[1]); w.w = cvt_pk_bf16(v1[2], v1[3]);
;                     *(u32x4*)(rowp + bj * HALF) = w; } }
.LBB0_2133:
	v_mov_b32_e32 v142, v246
	s_lshl_b32 s3, s18, 8
	s_add_i32 s3, s3, s31
	v_and_or_b32 v146, v142, 15, s3
	v_lshrrev_b32_e32 v142, 1, v142
	s_lshl_b32 s3, s45, 8
	v_max_f32_e32 v122, v122, v122
	v_max_f32_e32 v123, v123, v123
	v_max_f32_e32 v124, v124, v124
	v_and_or_b32 v142, v142, 24, s3
	v_max_f32_e32 v122, 0, v122
	v_max_f32_e32 v123, 0, v123
	v_max_f32_e32 v124, 0, v124
	v_ashrrev_i32_e32 v147, 31, v146
	v_or_b32_e32 v142, s33, v142
	v_max_f32_e32 v126, v126, v126
	v_mul_f32_e32 v145, v122, v122
	v_max_f32_e32 v122, v127, v127
	v_mul_f32_e32 v127, v123, v123
	v_max_f32_e32 v123, v128, v128
	v_mul_f32_e32 v128, v124, v124
	v_max_f32_e32 v124, v129, v129
	v_max_f32_e32 v125, v125, v125
	v_ashrrev_i32_e32 v143, 31, v142
	v_lshlrev_b64 v[148:149], 14, v[146:147]
	v_max_f32_e32 v126, 0, v126
	v_max_f32_e32 v122, 0, v122
	v_max_f32_e32 v123, 0, v123
	v_max_f32_e32 v124, 0, v124
	v_max_f32_e32 v125, 0, v125
	v_lshl_add_u64 v[148:149], s[58:59], 0, v[148:149]
	v_lshlrev_b64 v[150:151], 1, v[142:143]
	v_mul_f32_e32 v126, v126, v126
	v_mul_f32_e32 v122, v122, v122
	v_mul_f32_e32 v123, v123, v123
	v_mul_f32_e32 v124, v124, v124
	v_mul_f32_e32 v125, v125, v125
	v_max_f32_e32 v114, v114, v114
	v_max_f32_e32 v115, v115, v115
	v_max_f32_e32 v116, v116, v116
	v_lshl_add_u64 v[142:143], v[148:149], 0, v[150:151]
	v_cvt_pk_bf16_f32 v122, v126, v122
	v_cvt_pk_bf16_f32 v123, v123, v124
	v_cvt_pk_bf16_f32 v124, v145, v127
	v_cvt_pk_bf16_f32 v125, v128, v125
	v_max_f32_e32 v114, 0, v114
	v_max_f32_e32 v115, 0, v115
	v_max_f32_e32 v116, 0, v116
	global_store_dwordx4 v[142:143], v[122:125], off nt
	v_max_f32_e32 v118, v118, v118
	v_max_f32_e32 v117, v117, v117
	v_mul_f32_e32 v122, v114, v114
	v_max_f32_e32 v114, v119, v119
	v_mul_f32_e32 v119, v115, v115
	v_max_f32_e32 v115, v120, v120
	v_mul_f32_e32 v120, v116, v116
	v_max_f32_e32 v116, v121, v121
	v_max_f32_e32 v118, 0, v118
	v_max_f32_e32 v114, 0, v114
	v_max_f32_e32 v115, 0, v115
	v_max_f32_e32 v116, 0, v116
	v_max_f32_e32 v117, 0, v117
	v_mul_f32_e32 v118, v118, v118
	v_mul_f32_e32 v114, v114, v114
	v_mul_f32_e32 v115, v115, v115
	v_mul_f32_e32 v116, v116, v116
	v_mul_f32_e32 v117, v117, v117
	v_cvt_pk_bf16_f32 v114, v118, v114
	v_cvt_pk_bf16_f32 v115, v115, v116
	v_cvt_pk_bf16_f32 v116, v122, v119
	v_cvt_pk_bf16_f32 v117, v120, v117
	v_max_f32_e32 v106, v106, v106
	v_max_f32_e32 v107, v107, v107
	v_max_f32_e32 v108, v108, v108
	global_store_dwordx4 v[142:143], v[114:117], off offset:256 nt
	v_max_f32_e32 v106, 0, v106
	v_max_f32_e32 v107, 0, v107
	v_or_b32_e32 v114, 16, v146
	v_max_f32_e32 v108, 0, v108
	v_ashrrev_i32_e32 v115, 31, v114
	v_max_f32_e32 v110, v110, v110
	v_mul_f32_e32 v116, v106, v106
	v_max_f32_e32 v106, v111, v111
	v_mul_f32_e32 v111, v107, v107
	v_max_f32_e32 v107, v112, v112
	v_mul_f32_e32 v112, v108, v108
	v_max_f32_e32 v108, v113, v113
	v_max_f32_e32 v109, v109, v109
	v_lshlrev_b64 v[114:115], 14, v[114:115]
	v_max_f32_e32 v110, 0, v110
	v_max_f32_e32 v106, 0, v106
	v_max_f32_e32 v107, 0, v107
	v_max_f32_e32 v108, 0, v108
	v_max_f32_e32 v109, 0, v109
	v_lshl_add_u64 v[114:115], s[58:59], 0, v[114:115]
	v_mul_f32_e32 v110, v110, v110
	v_mul_f32_e32 v106, v106, v106
	v_mul_f32_e32 v107, v107, v107
	v_mul_f32_e32 v108, v108, v108
	v_mul_f32_e32 v109, v109, v109
	v_max_f32_e32 v98, v98, v98
	v_max_f32_e32 v99, v99, v99
	v_max_f32_e32 v100, v100, v100
	v_lshl_add_u64 v[114:115], v[114:115], 0, v[150:151]
	v_cvt_pk_bf16_f32 v106, v110, v106
	v_cvt_pk_bf16_f32 v107, v107, v108
	v_cvt_pk_bf16_f32 v108, v116, v111
	v_cvt_pk_bf16_f32 v109, v112, v109
	v_max_f32_e32 v98, 0, v98
	v_max_f32_e32 v99, 0, v99
	v_max_f32_e32 v100, 0, v100
	global_store_dwordx4 v[114:115], v[106:109], off nt
	v_max_f32_e32 v102, v102, v102
	v_max_f32_e32 v101, v101, v101
	v_mul_f32_e32 v106, v98, v98
	v_max_f32_e32 v98, v103, v103
	v_mul_f32_e32 v103, v99, v99
	v_max_f32_e32 v99, v104, v104
	v_mul_f32_e32 v104, v100, v100
	v_max_f32_e32 v100, v105, v105
	v_max_f32_e32 v102, 0, v102
	v_max_f32_e32 v98, 0, v98
	v_max_f32_e32 v99, 0, v99
	v_max_f32_e32 v100, 0, v100
	v_max_f32_e32 v101, 0, v101
	v_mul_f32_e32 v102, v102, v102
	v_mul_f32_e32 v98, v98, v98
	v_mul_f32_e32 v99, v99, v99
	v_mul_f32_e32 v100, v100, v100
	v_mul_f32_e32 v101, v101, v101
	v_cvt_pk_bf16_f32 v98, v102, v98
	v_cvt_pk_bf16_f32 v99, v99, v100
	v_cvt_pk_bf16_f32 v100, v106, v103
	v_cvt_pk_bf16_f32 v101, v104, v101
	v_max_f32_e32 v90, v90, v90
	v_max_f32_e32 v91, v91, v91
	v_max_f32_e32 v92, v92, v92
	global_store_dwordx4 v[114:115], v[98:101], off offset:256 nt
	v_max_f32_e32 v90, 0, v90
	v_max_f32_e32 v91, 0, v91
	v_or_b32_e32 v98, 32, v146
	v_max_f32_e32 v92, 0, v92
	v_ashrrev_i32_e32 v99, 31, v98
	v_max_f32_e32 v94, v94, v94
	v_mul_f32_e32 v100, v90, v90
	v_max_f32_e32 v90, v95, v95
	v_mul_f32_e32 v95, v91, v91
	v_max_f32_e32 v91, v96, v96
	v_mul_f32_e32 v96, v92, v92
	v_max_f32_e32 v92, v97, v97
	v_max_f32_e32 v93, v93, v93
	v_lshlrev_b64 v[98:99], 14, v[98:99]
	v_max_f32_e32 v94, 0, v94
	v_max_f32_e32 v90, 0, v90
	v_max_f32_e32 v91, 0, v91
	v_max_f32_e32 v92, 0, v92
	v_max_f32_e32 v93, 0, v93
	v_lshl_add_u64 v[98:99], s[58:59], 0, v[98:99]
	v_mul_f32_e32 v94, v94, v94
	v_mul_f32_e32 v90, v90, v90
	v_mul_f32_e32 v91, v91, v91
	v_mul_f32_e32 v92, v92, v92
	v_mul_f32_e32 v93, v93, v93
	v_max_f32_e32 v82, v82, v82
	v_max_f32_e32 v83, v83, v83
	v_max_f32_e32 v84, v84, v84
	v_lshl_add_u64 v[98:99], v[98:99], 0, v[150:151]
	v_cvt_pk_bf16_f32 v90, v94, v90
	v_cvt_pk_bf16_f32 v91, v91, v92
	v_cvt_pk_bf16_f32 v92, v100, v95
	v_cvt_pk_bf16_f32 v93, v96, v93
	v_max_f32_e32 v82, 0, v82
	v_max_f32_e32 v83, 0, v83
	v_max_f32_e32 v84, 0, v84
;     __device__ __forceinline__ void operator()(f32x4 (&acc)[2][2][4][2], const Unit& u, int wr, int wc, int fr, int fq) const {
;     ...
;             for (int m = 0; m < 4; ++m) { const int row = row0 + ai * HALF + m * 16; bf16_t* rowp = O + (size_t)row * ldc + col0;
;                 const float rs = ssq ? rsv[ai * 4 + m] : 1.0f;
; #pragma unroll
;                 for (int bj = 0; bj < 2; ++bj) { f32x4 v0 = acc[ai][bj][m][0] * rs, v1 = acc[ai][bj][m][1] * rs;
;                     if (ACT == 2) {
; #pragma unroll
;                         for (int j = 0; j < 4; ++j) { float a = v0[j] > 0.f ? v0[j] : 0.f; v0[j] = a * a; float b = v1[j] > 0.f ? v1[j] : 0.f; v1[j] = b * b; } }
;                     u32x4 w; w.x = cvt_pk_bf16(v0[0], v0[1]); w.y = cvt_pk_bf16(v0[2], v0[3]); w.z = cvt_pk_bf16(v1[0], v1[1]); w.w = cvt_pk_bf16(v1[2], v1[3]);
;                     *(u32x4*)(rowp + bj * HALF) = w; } }
	global_store_dwordx4 v[98:99], v[90:93], off nt
	v_max_f32_e32 v86, v86, v86
	v_max_f32_e32 v85, v85, v85
	v_mul_f32_e32 v90, v82, v82
	v_max_f32_e32 v82, v87, v87
	v_mul_f32_e32 v87, v83, v83
	v_max_f32_e32 v83, v88, v88
	v_mul_f32_e32 v88, v84, v84
	v_max_f32_e32 v84, v89, v89
	v_max_f32_e32 v86, 0, v86
	v_max_f32_e32 v82, 0, v82
	v_max_f32_e32 v83, 0, v83
	v_max_f32_e32 v84, 0, v84
	v_max_f32_e32 v85, 0, v85
	v_mul_f32_e32 v86, v86, v86
	v_mul_f32_e32 v82, v82, v82
	v_mul_f32_e32 v83, v83, v83
	v_mul_f32_e32 v84, v84, v84
	v_mul_f32_e32 v85, v85, v85
	v_cvt_pk_bf16_f32 v82, v86, v82
	v_cvt_pk_bf16_f32 v83, v83, v84
	v_cvt_pk_bf16_f32 v84, v90, v87
	v_cvt_pk_bf16_f32 v85, v88, v85
	v_max_f32_e32 v74, v74, v74
	v_max_f32_e32 v75, v75, v75
	v_max_f32_e32 v76, v76, v76
	global_store_dwordx4 v[98:99], v[82:85], off offset:256 nt
	v_max_f32_e32 v74, 0, v74
	v_max_f32_e32 v75, 0, v75
	v_or_b32_e32 v82, 48, v146
	v_max_f32_e32 v76, 0, v76
	v_ashrrev_i32_e32 v83, 31, v82
	v_max_f32_e32 v78, v78, v78
	v_mul_f32_e32 v84, v74, v74
	v_max_f32_e32 v74, v79, v79
	v_mul_f32_e32 v79, v75, v75
	v_max_f32_e32 v75, v80, v80
	v_mul_f32_e32 v80, v76, v76
	v_max_f32_e32 v76, v81, v81
	v_max_f32_e32 v77, v77, v77
	v_lshlrev_b64 v[82:83], 14, v[82:83]
	v_max_f32_e32 v78, 0, v78
	v_max_f32_e32 v74, 0, v74
	v_max_f32_e32 v75, 0, v75
	v_max_f32_e32 v76, 0, v76
	v_max_f32_e32 v77, 0, v77
	v_lshl_add_u64 v[82:83], s[58:59], 0, v[82:83]
	v_mul_f32_e32 v78, v78, v78
	v_mul_f32_e32 v74, v74, v74
	v_mul_f32_e32 v75, v75, v75
	v_mul_f32_e32 v76, v76, v76
	v_mul_f32_e32 v77, v77, v77
	v_max_f32_e32 v66, v66, v66
	v_max_f32_e32 v67, v67, v67
	v_max_f32_e32 v68, v68, v68
	v_lshl_add_u64 v[82:83], v[82:83], 0, v[150:151]
	v_cvt_pk_bf16_f32 v74, v78, v74
	v_cvt_pk_bf16_f32 v75, v75, v76
	v_cvt_pk_bf16_f32 v76, v84, v79
	v_cvt_pk_bf16_f32 v77, v80, v77
	v_max_f32_e32 v66, 0, v66
	v_max_f32_e32 v67, 0, v67
	v_max_f32_e32 v68, 0, v68
	global_store_dwordx4 v[82:83], v[74:77], off nt
	v_max_f32_e32 v70, v70, v70
	v_max_f32_e32 v69, v69, v69
	v_mul_f32_e32 v74, v66, v66
	v_max_f32_e32 v66, v71, v71
	v_mul_f32_e32 v71, v67, v67
	v_max_f32_e32 v67, v72, v72
	v_mul_f32_e32 v72, v68, v68
	v_max_f32_e32 v68, v73, v73
	v_max_f32_e32 v70, 0, v70
	v_max_f32_e32 v66, 0, v66
	v_max_f32_e32 v67, 0, v67
	v_max_f32_e32 v68, 0, v68
	v_max_f32_e32 v69, 0, v69
	v_mul_f32_e32 v70, v70, v70
	v_mul_f32_e32 v66, v66, v66
	v_mul_f32_e32 v67, v67, v67
	v_mul_f32_e32 v68, v68, v68
	v_mul_f32_e32 v69, v69, v69
	v_max_f32_e32 v58, v58, v58
	v_cvt_pk_bf16_f32 v66, v70, v66
	v_cvt_pk_bf16_f32 v67, v67, v68
	v_cvt_pk_bf16_f32 v68, v74, v71
	v_cvt_pk_bf16_f32 v69, v72, v69
	v_max_f32_e32 v58, 0, v58
	v_max_f32_e32 v59, v59, v59
	v_max_f32_e32 v60, v60, v60
	global_store_dwordx4 v[82:83], v[66:69], off offset:256 nt
	v_max_f32_e32 v62, v62, v62
	v_max_f32_e32 v59, 0, v59
	v_mul_f32_e32 v68, v58, v58
	v_max_f32_e32 v58, v63, v63
	v_max_f32_e32 v60, 0, v60
	v_max_f32_e32 v62, 0, v62
	v_max_f32_e32 v58, 0, v58
	v_mul_f32_e32 v63, v59, v59
	v_max_f32_e32 v59, v64, v64
	v_mul_f32_e32 v64, v60, v60
	v_max_f32_e32 v60, v65, v65
	v_max_f32_e32 v61, v61, v61
	v_mul_f32_e32 v62, v62, v62
	v_mul_f32_e32 v58, v58, v58
	v_max_f32_e32 v59, 0, v59
	v_max_f32_e32 v60, 0, v60
	v_max_f32_e32 v61, 0, v61
	s_mov_b32 s3, 0x200000
	v_mul_f32_e32 v59, v59, v59
	v_mul_f32_e32 v60, v60, v60
	v_mul_f32_e32 v61, v61, v61
	v_cvt_pk_bf16_f32 v58, v62, v58
	v_add_co_u32_e32 v62, vcc, s3, v142
	v_max_f32_e32 v50, v50, v50
	v_max_f32_e32 v51, v51, v51
	v_max_f32_e32 v52, v52, v52
	v_cvt_pk_bf16_f32 v59, v59, v60
	v_cvt_pk_bf16_f32 v60, v68, v63
	v_cvt_pk_bf16_f32 v61, v64, v61
	v_addc_co_u32_e32 v63, vcc, 0, v143, vcc
	v_max_f32_e32 v50, 0, v50
	v_max_f32_e32 v51, 0, v51
	v_max_f32_e32 v52, 0, v52
	global_store_dwordx4 v[62:63], v[58:61], off nt
	v_max_f32_e32 v54, v54, v54
	v_max_f32_e32 v53, v53, v53
	v_mul_f32_e32 v58, v50, v50
	v_max_f32_e32 v50, v55, v55
	v_mul_f32_e32 v55, v51, v51
	v_max_f32_e32 v51, v56, v56
	v_mul_f32_e32 v56, v52, v52
	v_max_f32_e32 v52, v57, v57
	v_max_f32_e32 v54, 0, v54
	v_max_f32_e32 v50, 0, v50
	v_max_f32_e32 v51, 0, v51
	v_max_f32_e32 v52, 0, v52
	v_max_f32_e32 v53, 0, v53
	s_mov_b64 s[14:15], 0x200000
	v_mul_f32_e32 v54, v54, v54
	v_mul_f32_e32 v50, v50, v50
	v_mul_f32_e32 v51, v51, v51
	v_mul_f32_e32 v52, v52, v52
	v_mul_f32_e32 v53, v53, v53
	v_max_f32_e32 v42, v42, v42
	v_lshl_add_u64 v[66:67], v[142:143], 0, s[14:15]
	v_cvt_pk_bf16_f32 v50, v54, v50
	v_cvt_pk_bf16_f32 v51, v51, v52
	v_cvt_pk_bf16_f32 v52, v58, v55
	v_cvt_pk_bf16_f32 v53, v56, v53
	v_max_f32_e32 v42, 0, v42
	v_max_f32_e32 v43, v43, v43
	v_max_f32_e32 v44, v44, v44
	global_store_dwordx4 v[66:67], v[50:53], off offset:256 nt
	v_max_f32_e32 v46, v46, v46
	v_max_f32_e32 v43, 0, v43
	v_mul_f32_e32 v52, v42, v42
	v_max_f32_e32 v42, v47, v47
	v_max_f32_e32 v44, 0, v44
	v_max_f32_e32 v46, 0, v46
	v_max_f32_e32 v42, 0, v42
	v_mul_f32_e32 v47, v43, v43
	v_max_f32_e32 v43, v48, v48
	v_mul_f32_e32 v48, v44, v44
	v_max_f32_e32 v44, v49, v49
	v_max_f32_e32 v45, v45, v45
	v_mul_f32_e32 v46, v46, v46
	v_mul_f32_e32 v42, v42, v42
	v_max_f32_e32 v43, 0, v43
	v_max_f32_e32 v44, 0, v44
	v_max_f32_e32 v45, 0, v45
	s_mov_b32 s3, 0x240000
;     __device__ __forceinline__ void operator()(f32x4 (&acc)[2][2][4][2], const Unit& u, int wr, int wc, int fr, int fq) const {
;     ...
;             for (int m = 0; m < 4; ++m) { const int row = row0 + ai * HALF + m * 16; bf16_t* rowp = O + (size_t)row * ldc + col0;
;                 const float rs = ssq ? rsv[ai * 4 + m] : 1.0f;
; #pragma unroll
;                 for (int bj = 0; bj < 2; ++bj) { f32x4 v0 = acc[ai][bj][m][0] * rs, v1 = acc[ai][bj][m][1] * rs;
;                     if (ACT == 2) {
; #pragma unroll
;                         for (int j = 0; j < 4; ++j) { float a = v0[j] > 0.f ? v0[j] : 0.f; v0[j] = a * a; float b = v1[j] > 0.f ? v1[j] : 0.f; v1[j] = b * b; } }
;                     u32x4 w; w.x = cvt_pk_bf16(v0[0], v0[1]); w.y = cvt_pk_bf16(v0[2], v0[3]); w.z = cvt_pk_bf16(v1[0], v1[1]); w.w = cvt_pk_bf16(v1[2], v1[3]);
;                     *(u32x4*)(rowp + bj * HALF) = w; } }
	v_mul_f32_e32 v43, v43, v43
	v_mul_f32_e32 v44, v44, v44
	v_mul_f32_e32 v45, v45, v45
	v_cvt_pk_bf16_f32 v42, v46, v42
	v_add_co_u32_e32 v46, vcc, s3, v142
	v_max_f32_e32 v34, v34, v34
	v_max_f32_e32 v35, v35, v35
	v_max_f32_e32 v36, v36, v36
	v_cvt_pk_bf16_f32 v43, v43, v44
	v_cvt_pk_bf16_f32 v44, v52, v47
	v_cvt_pk_bf16_f32 v45, v48, v45
	v_addc_co_u32_e32 v47, vcc, 0, v143, vcc
	v_max_f32_e32 v34, 0, v34
	v_max_f32_e32 v35, 0, v35
	v_max_f32_e32 v36, 0, v36
	global_store_dwordx4 v[46:47], v[42:45], off nt
	v_max_f32_e32 v38, v38, v38
	v_max_f32_e32 v37, v37, v37
	v_mul_f32_e32 v42, v34, v34
	v_max_f32_e32 v34, v39, v39
	v_mul_f32_e32 v39, v35, v35
	v_max_f32_e32 v35, v40, v40
	v_mul_f32_e32 v40, v36, v36
	v_max_f32_e32 v36, v41, v41
	v_max_f32_e32 v38, 0, v38
	v_max_f32_e32 v34, 0, v34
	v_max_f32_e32 v35, 0, v35
	v_max_f32_e32 v36, 0, v36
	v_max_f32_e32 v37, 0, v37
	s_mov_b64 s[14:15], 0x240000
	v_mul_f32_e32 v38, v38, v38
	v_mul_f32_e32 v34, v34, v34
	v_mul_f32_e32 v35, v35, v35
	v_mul_f32_e32 v36, v36, v36
	v_mul_f32_e32 v37, v37, v37
	v_max_f32_e32 v26, v26, v26
	v_lshl_add_u64 v[50:51], v[142:143], 0, s[14:15]
	v_cvt_pk_bf16_f32 v34, v38, v34
	v_cvt_pk_bf16_f32 v35, v35, v36
	v_cvt_pk_bf16_f32 v36, v42, v39
	v_cvt_pk_bf16_f32 v37, v40, v37
	v_max_f32_e32 v26, 0, v26
	v_max_f32_e32 v27, v27, v27
	v_max_f32_e32 v28, v28, v28
	global_store_dwordx4 v[50:51], v[34:37], off offset:256 nt
	v_max_f32_e32 v30, v30, v30
	v_max_f32_e32 v27, 0, v27
	v_mul_f32_e32 v36, v26, v26
	v_max_f32_e32 v26, v31, v31
	v_max_f32_e32 v28, 0, v28
	v_max_f32_e32 v30, 0, v30
	v_max_f32_e32 v26, 0, v26
	v_mul_f32_e32 v31, v27, v27
	v_max_f32_e32 v27, v32, v32
	v_mul_f32_e32 v32, v28, v28
	v_max_f32_e32 v28, v33, v33
	v_max_f32_e32 v29, v29, v29
	v_mul_f32_e32 v30, v30, v30
	v_mul_f32_e32 v26, v26, v26
	v_max_f32_e32 v27, 0, v27
	v_max_f32_e32 v28, 0, v28
	v_max_f32_e32 v29, 0, v29
	s_mov_b32 s3, 0x280000
	v_mul_f32_e32 v27, v27, v27
	v_mul_f32_e32 v28, v28, v28
	v_mul_f32_e32 v29, v29, v29
	v_cvt_pk_bf16_f32 v26, v30, v26
	v_add_co_u32_e32 v30, vcc, s3, v142
	v_max_f32_e32 v18, v18, v18
	v_max_f32_e32 v19, v19, v19
	v_max_f32_e32 v20, v20, v20
	v_cvt_pk_bf16_f32 v27, v27, v28
	v_cvt_pk_bf16_f32 v28, v36, v31
	v_cvt_pk_bf16_f32 v29, v32, v29
	v_addc_co_u32_e32 v31, vcc, 0, v143, vcc
	v_max_f32_e32 v18, 0, v18
	v_max_f32_e32 v19, 0, v19
	v_max_f32_e32 v20, 0, v20
	global_store_dwordx4 v[30:31], v[26:29], off nt
	v_max_f32_e32 v22, v22, v22
	v_max_f32_e32 v21, v21, v21
	v_mul_f32_e32 v26, v18, v18
	v_max_f32_e32 v18, v23, v23
	v_mul_f32_e32 v23, v19, v19
	v_max_f32_e32 v19, v24, v24
	v_mul_f32_e32 v24, v20, v20
	v_max_f32_e32 v20, v25, v25
	v_max_f32_e32 v22, 0, v22
	v_max_f32_e32 v18, 0, v18
	v_max_f32_e32 v19, 0, v19
	v_max_f32_e32 v20, 0, v20
	v_max_f32_e32 v21, 0, v21
	s_mov_b64 s[14:15], 0x280000
	v_mul_f32_e32 v22, v22, v22
	v_mul_f32_e32 v18, v18, v18
	v_mul_f32_e32 v19, v19, v19
	v_mul_f32_e32 v20, v20, v20
	v_mul_f32_e32 v21, v21, v21
	v_max_f32_e32 v10, v10, v10
	v_lshl_add_u64 v[34:35], v[142:143], 0, s[14:15]
	v_cvt_pk_bf16_f32 v18, v22, v18
	v_cvt_pk_bf16_f32 v19, v19, v20
	v_cvt_pk_bf16_f32 v20, v26, v23
	v_cvt_pk_bf16_f32 v21, v24, v21
	v_max_f32_e32 v10, 0, v10
	v_max_f32_e32 v11, v11, v11
	v_max_f32_e32 v12, v12, v12
	global_store_dwordx4 v[34:35], v[18:21], off offset:256 nt
	v_max_f32_e32 v14, v14, v14
	v_max_f32_e32 v11, 0, v11
	v_mul_f32_e32 v20, v10, v10
	v_max_f32_e32 v10, v15, v15
	v_max_f32_e32 v12, 0, v12
	v_max_f32_e32 v14, 0, v14
	v_max_f32_e32 v10, 0, v10
	v_mul_f32_e32 v15, v11, v11
	v_max_f32_e32 v11, v16, v16
	v_mul_f32_e32 v16, v12, v12
	v_max_f32_e32 v12, v17, v17
	v_max_f32_e32 v13, v13, v13
	v_mul_f32_e32 v14, v14, v14
	v_mul_f32_e32 v10, v10, v10
	v_max_f32_e32 v11, 0, v11
	v_max_f32_e32 v12, 0, v12
	v_max_f32_e32 v13, 0, v13
	s_mov_b32 s3, 0x2c0000
	v_mul_f32_e32 v11, v11, v11
	v_mul_f32_e32 v12, v12, v12
	v_mul_f32_e32 v13, v13, v13
	v_cvt_pk_bf16_f32 v10, v14, v10
	v_add_co_u32_e32 v14, vcc, s3, v142
	v_max_f32_e32 v2, v2, v2
	v_max_f32_e32 v3, v3, v3
	v_max_f32_e32 v4, v4, v4
	v_cvt_pk_bf16_f32 v11, v11, v12
	v_cvt_pk_bf16_f32 v12, v20, v15
	v_cvt_pk_bf16_f32 v13, v16, v13
	v_addc_co_u32_e32 v15, vcc, 0, v143, vcc
	v_max_f32_e32 v2, 0, v2
	v_max_f32_e32 v3, 0, v3
	v_max_f32_e32 v4, 0, v4
	global_store_dwordx4 v[14:15], v[10:13], off nt
	v_max_f32_e32 v6, v6, v6
	v_max_f32_e32 v5, v5, v5
	v_mul_f32_e32 v10, v2, v2
	v_max_f32_e32 v2, v7, v7
	v_mul_f32_e32 v7, v3, v3
	v_max_f32_e32 v3, v8, v8
	v_mul_f32_e32 v8, v4, v4
	v_max_f32_e32 v4, v9, v9
	v_max_f32_e32 v6, 0, v6
	v_max_f32_e32 v2, 0, v2
	v_max_f32_e32 v3, 0, v3
	v_max_f32_e32 v4, 0, v4
	v_max_f32_e32 v5, 0, v5
	s_mov_b64 s[14:15], 0x2c0000
	v_mul_f32_e32 v6, v6, v6
	v_mul_f32_e32 v2, v2, v2
	v_mul_f32_e32 v3, v3, v3
	v_mul_f32_e32 v4, v4, v4
	v_mul_f32_e32 v5, v5, v5
	v_lshl_add_u64 v[18:19], v[142:143], 0, s[14:15]
	v_cvt_pk_bf16_f32 v2, v6, v2
	v_cvt_pk_bf16_f32 v3, v3, v4
	v_cvt_pk_bf16_f32 v4, v10, v7
	v_cvt_pk_bf16_f32 v5, v8, v5
	s_andn2_b64 vcc, exec, s[4:5]
	s_mov_b64 s[4:5], -1
	global_store_dwordx4 v[18:19], v[2:5], off offset:256 nt
	s_cbranch_vccnz .LBB0_2122
	s_andn2_b64 vcc, exec, s[0:1]
	s_cbranch_vccnz .LBB0_2121
	s_barrier
	s_branch .LBB0_2121

;     __device__ __forceinline__ void operator()(f32x4 (&acc)[2][2][4][2], const Unit& u, int wr, int wc, int fr, int fq) const {
;     ...
;             for (int m = 0; m < 4; ++m) { const int row = row0 + ai * HALF + m * 16; bf16_t* rowp = O + (size_t)row * ldc + col0;
;                 const float rs = ssq ? rsv[ai * 4 + m] : 1.0f;
; #pragma unroll
;                 for (int bj = 0; bj < 2; ++bj) { f32x4 v0 = acc[ai][bj][m][0] * rs, v1 = acc[ai][bj][m][1] * rs;
;                     if (ACT == 2) {
; #pragma unroll
;                         for (int j = 0; j < 4; ++j) { float a = v0[j] > 0.f ? v0[j] : 0.f; v0[j] = a * a; float b = v1[j] > 0.f ? v1[j] : 0.f; v1[j] = b * b; } }
;                     u32x4 w; w.x = cvt_pk_bf16(v0[0], v0[1]); w.y = cvt_pk_bf16(v0[2], v0[3]); w.z = cvt_pk_bf16(v1[0], v1[1]); w.w = cvt_pk_bf16(v1[2], v1[3]);
;                     *(u32x4*)(rowp + bj * HALF) = w; } }
.LBB0_2158:
	v_mov_b32_e32 v139, v246
	s_lshl_b32 s3, s10, 8
	s_add_i32 s3, s3, s74
	v_and_or_b32 v140, v139, 15, s3
	v_lshrrev_b32_e32 v139, 1, v139
	s_lshl_b32 s3, s95, 8
	v_and_or_b32 v139, v139, 24, s3
	v_ashrrev_i32_e32 v141, 31, v140
	v_or_b32_e32 v142, s75, v139
	v_ashrrev_i32_e32 v143, 31, v142
	v_lshlrev_b64 v[144:145], 12, v[140:141]
	v_lshl_add_u64 v[144:145], s[56:57], 0, v[144:145]
	v_lshlrev_b64 v[142:143], 1, v[142:143]
	v_lshl_add_u64 v[144:145], v[144:145], 0, v[142:143]
	s_mov_b32 s3, 0x80000
	s_mov_b64 s[12:13], 0x80000
	v_cvt_pk_bf16_f32 v62, v62, v63
	v_cvt_pk_bf16_f32 v63, v64, v65
	v_cvt_pk_bf16_f32 v64, v58, v59
	v_add_co_u32_e32 v58, vcc, s3, v144
	v_cvt_pk_bf16_f32 v70, v70, v71
	v_cvt_pk_bf16_f32 v71, v72, v73
	v_cvt_pk_bf16_f32 v72, v66, v67
	v_lshl_add_u64 v[66:67], v[144:145], 0, s[12:13]
	v_addc_co_u32_e32 v59, vcc, 0, v145, vcc
	v_cvt_pk_bf16_f32 v46, v46, v47
	v_cvt_pk_bf16_f32 v47, v48, v49
	v_cvt_pk_bf16_f32 v48, v42, v43
	v_cvt_pk_bf16_f32 v49, v44, v45
	s_mov_b32 s3, 0x90000
	v_cvt_pk_bf16_f32 v110, v110, v111
	v_cvt_pk_bf16_f32 v111, v112, v113
	v_cvt_pk_bf16_f32 v112, v106, v107
	v_or_b32_e32 v106, 16, v140
	global_store_dwordx4 v[66:67], v[46:49], off offset:256 nt
	s_mov_b64 s[12:13], 0x90000
	v_ashrrev_i32_e32 v107, 31, v106
	v_add_co_u32_e32 v48, vcc, s3, v144
	v_cvt_pk_bf16_f32 v94, v94, v95
	v_cvt_pk_bf16_f32 v95, v96, v97
	v_cvt_pk_bf16_f32 v96, v90, v91
	v_or_b32_e32 v90, 32, v140
	v_lshl_add_u64 v[46:47], v[144:145], 0, s[12:13]
	v_addc_co_u32_e32 v49, vcc, 0, v145, vcc
	v_cvt_pk_bf16_f32 v30, v30, v31
	v_cvt_pk_bf16_f32 v31, v32, v33
	v_cvt_pk_bf16_f32 v32, v26, v27
	v_cvt_pk_bf16_f32 v33, v28, v29
	s_mov_b32 s3, 0xa0000
	v_lshlrev_b64 v[106:107], 12, v[106:107]
	v_ashrrev_i32_e32 v91, 31, v90
	v_cvt_pk_bf16_f32 v78, v78, v79
	v_cvt_pk_bf16_f32 v79, v80, v81
	v_cvt_pk_bf16_f32 v80, v74, v75
	v_or_b32_e32 v74, 48, v140
	global_store_dwordx4 v[46:47], v[30:33], off offset:256 nt
	s_mov_b64 s[12:13], 0xa0000
	v_cvt_pk_bf16_f32 v113, v108, v109
	v_add_co_u32_e32 v32, vcc, s3, v144
	v_lshl_add_u64 v[106:107], s[56:57], 0, v[106:107]
	v_lshlrev_b64 v[90:91], 12, v[90:91]
	v_ashrrev_i32_e32 v75, 31, v74
	v_lshl_add_u64 v[30:31], v[144:145], 0, s[12:13]
	v_addc_co_u32_e32 v33, vcc, 0, v145, vcc
	v_cvt_pk_bf16_f32 v14, v14, v15
	v_cvt_pk_bf16_f32 v15, v16, v17
	v_cvt_pk_bf16_f32 v16, v10, v11
	v_cvt_pk_bf16_f32 v17, v12, v13
	global_store_dwordx4 v[144:145], v[110:113], off offset:256 nt
	v_cvt_pk_bf16_f32 v97, v92, v93
	v_lshl_add_u64 v[90:91], s[56:57], 0, v[90:91]
	v_lshl_add_u64 v[110:111], v[106:107], 0, v[142:143]
	v_lshlrev_b64 v[74:75], 12, v[74:75]
	global_store_dwordx4 v[30:31], v[14:17], off offset:256 nt
	global_store_dwordx4 v[110:111], v[94:97], off offset:256 nt
	v_cvt_pk_bf16_f32 v81, v76, v77
	v_add_co_u32_e32 v16, vcc, 0xb0000, v144
	v_lshl_add_u64 v[94:95], v[90:91], 0, v[142:143]
	v_lshl_add_u64 v[74:75], s[56:57], 0, v[74:75]
	s_mov_b64 s[12:13], 0xb0000
	v_addc_co_u32_e32 v17, vcc, 0, v145, vcc
	v_readlane_b32 s30, v255, 26
	v_cvt_pk_bf16_f32 v126, v126, v127
	v_cvt_pk_bf16_f32 v127, v128, v129
	v_cvt_pk_bf16_f32 v128, v122, v123
	v_cvt_pk_bf16_f32 v129, v124, v125
	v_cvt_pk_bf16_f32 v106, v118, v119
	v_cvt_pk_bf16_f32 v107, v120, v121
	v_cvt_pk_bf16_f32 v108, v114, v115
	v_cvt_pk_bf16_f32 v109, v116, v117
	v_cvt_pk_bf16_f32 v90, v102, v103
	v_cvt_pk_bf16_f32 v91, v104, v105
	v_cvt_pk_bf16_f32 v92, v98, v99
	v_cvt_pk_bf16_f32 v93, v100, v101
	global_store_dwordx4 v[94:95], v[78:81], off offset:256 nt
	v_cvt_pk_bf16_f32 v76, v82, v83
	v_cvt_pk_bf16_f32 v77, v84, v85
	v_lshl_add_u64 v[78:79], v[74:75], 0, v[142:143]
	v_cvt_pk_bf16_f32 v74, v86, v87
	v_cvt_pk_bf16_f32 v75, v88, v89
	v_cvt_pk_bf16_f32 v73, v68, v69
	v_cvt_pk_bf16_f32 v65, v60, v61
	v_cvt_pk_bf16_f32 v42, v54, v55
	v_cvt_pk_bf16_f32 v43, v56, v57
	v_cvt_pk_bf16_f32 v44, v50, v51
	v_cvt_pk_bf16_f32 v45, v52, v53
	v_cvt_pk_bf16_f32 v26, v38, v39
	v_cvt_pk_bf16_f32 v27, v40, v41
	v_cvt_pk_bf16_f32 v28, v34, v35
	v_cvt_pk_bf16_f32 v29, v36, v37
	v_lshl_add_u64 v[14:15], v[144:145], 0, s[12:13]
	v_cvt_pk_bf16_f32 v10, v22, v23
	v_cvt_pk_bf16_f32 v11, v24, v25
	v_cvt_pk_bf16_f32 v12, v18, v19
	v_cvt_pk_bf16_f32 v13, v20, v21
	v_cvt_pk_bf16_f32 v6, v6, v7
	v_cvt_pk_bf16_f32 v7, v8, v9
	v_cvt_pk_bf16_f32 v8, v2, v3
	v_cvt_pk_bf16_f32 v9, v4, v5
	s_andn2_b64 vcc, exec, s[6:7]
	s_mov_b64 s[6:7], -1
	v_readlane_b32 s31, v255, 27
	global_store_dwordx4 v[144:145], v[126:129], off nt
	global_store_dwordx4 v[110:111], v[106:109], off nt
	global_store_dwordx4 v[94:95], v[90:93], off nt
	global_store_dwordx4 v[78:79], v[74:77], off nt
	global_store_dwordx4 v[78:79], v[70:73], off offset:256 nt
	global_store_dwordx4 v[58:59], v[62:65], off nt
	global_store_dwordx4 v[48:49], v[42:45], off nt
	global_store_dwordx4 v[32:33], v[26:29], off nt
	global_store_dwordx4 v[16:17], v[10:13], off nt
	global_store_dwordx4 v[14:15], v[6:9], off offset:256 nt
	s_cbranch_vccnz .LBB0_2147
	s_andn2_b64 vcc, exec, s[0:1]
	s_cbranch_vccnz .LBB0_2146
	s_barrier
	s_branch .LBB0_2146

; __device__ __forceinline__ float ssq4(const f32x4 o) { return (o[0] * o[0] + o[1] * o[1]) + (o[2] * o[2] + o[3] * o[3]); }
;     __device__ __forceinline__ void operator()(f32x4 (&acc)[2][2][4][2], const Unit& u, int wr, int wc, int fr, int fq) const {
;     ...
;         f32x4 cur[2][4], nxt[2][4];
; #pragma unroll
;         for (int q = 0; q < 2; ++q)
; #pragma unroll
;             for (int c = 0; c < 4; ++c) cur[q][c] = *(const f32x4*)(base + (size_t)EPI_ROW(q) * D + col0 + (c >> 1) * HALF + (c & 1) * 4);
; #pragma unroll
;         for (int k = 0; k < 4; ++k) {
;             if (k < 3) {
; #pragma unroll
;                 for (int q = 0; q < 2; ++q)
; #pragma unroll
;                     for (int c = 0; c < 4; ++c) nxt[q][c] = *(const f32x4*)(base + (size_t)EPI_ROW(2 * k + 2 + q) * D + col0 + (c >> 1) * HALF + (c & 1) * 4);
;             }
;             asm volatile("" ::: "memory");
; #pragma unroll
;             for (int q = 0; q < 2; ++q) { const int r = 2 * k + q, ai = r >> 2, m = r & 3; const size_t off = (size_t)EPI_ROW(r) * D + col0; float sr = 0.f;
; #pragma unroll
;                 for (int bj = 0; bj < 2; ++bj) { const f32x4 o0 = cur[q][2 * bj] + acc[ai][bj][m][0], o1 = cur[q][2 * bj + 1] + acc[ai][bj][m][1];
;                     *(f32x4*)(out + off + bj * HALF) = o0; *(f32x4*)(out + off + bj * HALF + 4) = o1;
;                     u32x4 w; w.x = cvt_pk_bf16(o0[0], o0[1]); w.y = cvt_pk_bf16(o0[2], o0[3]); w.z = cvt_pk_bf16(o1[0], o1[1]); w.w = cvt_pk_bf16(o1[2], o1[3]); *(u32x4*)(hb + off + bj * HALF) = w; sr += ssq4(o0) + ssq4(o1); }
;                 s[ai][m] = sr; }
.LBB0_2238:
	s_lshl_b32 s3, s0, 8
	s_or_b32 s3, s3, s45
	v_lshl_or_b32 v130, v168, 3, s3
	v_ashrrev_i32_e32 v131, 31, v130
	v_or_b32_e32 v138, 16, v162
	v_lshl_add_u64 v[132:133], v[130:131], 2, s[36:37]
	v_lshlrev_b64 v[134:135], 13, v[162:163]
	v_ashrrev_i32_e32 v139, 31, v138
	v_lshl_add_u64 v[148:149], v[132:133], 0, v[134:135]
	v_lshlrev_b64 v[134:135], 13, v[138:139]
	global_load_dwordx4 v[140:143], v[148:149], off
	global_load_dwordx4 v[144:147], v[148:149], off offset:16
	global_load_dwordx4 v[170:173], v[148:149], off offset:528
	global_load_dwordx4 v[174:177], v[148:149], off offset:512
	v_lshl_add_u64 v[164:165], v[132:133], 0, v[134:135]
	global_load_dwordx4 v[188:191], v[164:165], off
	global_load_dwordx4 v[192:195], v[164:165], off offset:16
	global_load_dwordx4 v[196:199], v[164:165], off offset:512
	global_load_dwordx4 v[200:203], v[164:165], off offset:528
	v_or_b32_e32 v136, 32, v162
	v_or_b32_e32 v134, 48, v162
	v_ashrrev_i32_e32 v137, 31, v136
	v_ashrrev_i32_e32 v135, 31, v134
	v_lshlrev_b64 v[184:185], 13, v[136:137]
	v_lshlrev_b64 v[138:139], 11, v[138:139]
	v_lshlrev_b64 v[204:205], 13, v[134:135]
	v_lshl_add_u64 v[206:207], v[138:139], 0, v[130:131]
	v_lshl_add_u64 v[184:185], v[132:133], 0, v[184:185]
	v_lshl_add_u64 v[138:139], v[132:133], 0, v[204:205]
	v_lshl_add_u64 v[236:237], v[206:207], 1, s[60:61]
	global_load_dwordx4 v[204:207], v[184:185], off offset:16
	global_load_dwordx4 v[208:211], v[184:185], off
	global_load_dwordx4 v[212:215], v[184:185], off offset:528
	global_load_dwordx4 v[216:219], v[184:185], off offset:512
	global_load_dwordx4 v[220:223], v[138:139], off offset:16
	global_load_dwordx4 v[224:227], v[138:139], off
	global_load_dwordx4 v[228:231], v[138:139], off offset:528
	global_load_dwordx4 v[232:235], v[138:139], off offset:512
	v_lshlrev_b64 v[178:179], 11, v[162:163]
	v_lshl_add_u64 v[178:179], v[178:179], 0, v[130:131]
	v_lshl_add_u64 v[178:179], v[178:179], 1, s[60:61]
	v_add_u32_e32 v238, 0x90, v162
	v_ashrrev_i32_e32 v239, 31, v238
	v_cmp_eq_u32_e32 vcc, 0, v168
	s_waitcnt vmcnt(0)
	v_pk_add_f32 v[128:129], v[128:129], v[142:143]
	v_pk_add_f32 v[126:127], v[126:127], v[140:141]
	v_pk_add_f32 v[124:125], v[124:125], v[146:147]
	v_pk_add_f32 v[122:123], v[122:123], v[144:145]
	v_pk_add_f32 v[142:143], v[112:113], v[176:177]
	v_pk_add_f32 v[140:141], v[110:111], v[174:175]
	v_pk_add_f32 v[146:147], v[108:109], v[172:173]
	v_pk_add_f32 v[144:145], v[106:107], v[170:171]
	v_pk_add_f32 v[112:113], v[120:121], v[190:191]
	v_pk_add_f32 v[110:111], v[118:119], v[188:189]
	v_pk_add_f32 v[108:109], v[116:117], v[194:195]
	v_pk_add_f32 v[106:107], v[114:115], v[192:193]
	v_cvt_pk_bf16_f32 v114, v126, v127
	v_cvt_pk_bf16_f32 v115, v128, v129
	v_cvt_pk_bf16_f32 v116, v122, v123
	v_cvt_pk_bf16_f32 v117, v124, v125
	v_pk_add_f32 v[104:105], v[104:105], v[198:199]
	v_pk_add_f32 v[102:103], v[102:103], v[196:197]
	v_pk_add_f32 v[100:101], v[100:101], v[202:203]
	v_pk_add_f32 v[98:99], v[98:99], v[200:201]
	global_store_dwordx4 v[148:149], v[126:129], off nt
	global_store_dwordx4 v[148:149], v[122:125], off offset:16 nt
	v_cvt_pk_bf16_f32 v118, v140, v141
	v_cvt_pk_bf16_f32 v119, v142, v143
	v_cvt_pk_bf16_f32 v120, v144, v145
	v_cvt_pk_bf16_f32 v121, v146, v147
	v_cvt_pk_bf16_f32 v170, v110, v111
	v_cvt_pk_bf16_f32 v171, v112, v113
	v_cvt_pk_bf16_f32 v172, v106, v107
	v_cvt_pk_bf16_f32 v173, v108, v109
	global_store_dwordx4 v[178:179], v[114:117], off nt
	global_store_dwordx4 v[148:149], v[140:143], off offset:512
	global_store_dwordx4 v[148:149], v[144:147], off offset:528
	global_store_dwordx4 v[178:179], v[118:121], off offset:256 nt
	global_store_dwordx4 v[164:165], v[110:113], off nt
	global_store_dwordx4 v[164:165], v[106:109], off offset:16 nt
	global_store_dwordx4 v[236:237], v[170:173], off
	global_store_dwordx4 v[164:165], v[102:105], off offset:512 nt
	global_store_dwordx4 v[164:165], v[98:101], off offset:528 nt
	v_add_u32_e32 v178, 0x80, v162
	v_mul_f32_e32 v181, v125, v125
	v_cvt_pk_bf16_f32 v114, v102, v103
	v_cvt_pk_bf16_f32 v115, v104, v105
	v_cvt_pk_bf16_f32 v116, v98, v99
	v_cvt_pk_bf16_f32 v117, v100, v101
	v_ashrrev_i32_e32 v179, 31, v178
	v_fmac_f32_e32 v181, v124, v124
	global_store_dwordx4 v[236:237], v[114:117], off offset:256 nt
	v_lshlrev_b64 v[124:125], 11, v[136:137]
	v_mul_f32_e32 v127, v127, v127
	v_lshlrev_b64 v[114:115], 13, v[178:179]
	v_mul_f32_e32 v129, v129, v129
	v_mul_f32_e32 v163, v123, v123
	v_lshl_add_u64 v[236:237], v[132:133], 0, v[114:115]
	v_lshlrev_b64 v[114:115], 13, v[238:239]
	v_lshl_add_u64 v[124:125], v[124:125], 0, v[130:131]
	v_pk_add_f32 v[96:97], v[96:97], v[210:211]
	v_pk_add_f32 v[94:95], v[94:95], v[208:209]
	v_pk_add_f32 v[92:93], v[92:93], v[206:207]
	v_pk_add_f32 v[90:91], v[90:91], v[204:205]
	v_fmac_f32_e32 v127, v126, v126
	v_fmac_f32_e32 v129, v128, v128
	v_fmac_f32_e32 v163, v122, v122
	v_lshl_add_u64 v[122:123], v[132:133], 0, v[114:115]
	v_cvt_pk_bf16_f32 v200, v94, v95
	v_cvt_pk_bf16_f32 v201, v96, v97
	v_cvt_pk_bf16_f32 v202, v90, v91
	v_cvt_pk_bf16_f32 v203, v92, v93
	v_lshl_add_u64 v[124:125], v[124:125], 1, s[60:61]
	v_pk_add_f32 v[88:89], v[88:89], v[218:219]
	v_pk_add_f32 v[86:87], v[86:87], v[216:217]
	v_pk_add_f32 v[80:81], v[80:81], v[214:215]
	v_pk_add_f32 v[78:79], v[78:79], v[212:213]
	v_add_f32_e32 v148, v127, v129
	global_load_dwordx4 v[126:129], v[236:237], off offset:16
	global_load_dwordx4 v[170:173], v[236:237], off
	global_load_dwordx4 v[174:177], v[236:237], off offset:528
	global_load_dwordx4 v[188:191], v[236:237], off offset:512
	global_load_dwordx4 v[192:195], v[122:123], off offset:16
; __device__ __forceinline__ float ssq4(const f32x4 o) { return (o[0] * o[0] + o[1] * o[1]) + (o[2] * o[2] + o[3] * o[3]); }
;     __device__ __forceinline__ void operator()(f32x4 (&acc)[2][2][4][2], const Unit& u, int wr, int wc, int fr, int fq) const {
;     ...
;         for (int k = 0; k < 4; ++k) {
;             if (k < 3) {
; #pragma unroll
;                 for (int q = 0; q < 2; ++q)
; #pragma unroll
;                     for (int c = 0; c < 4; ++c) nxt[q][c] = *(const f32x4*)(base + (size_t)EPI_ROW(2 * k + 2 + q) * D + col0 + (c >> 1) * HALF + (c & 1) * 4);
;             }
;             asm volatile("" ::: "memory");
; #pragma unroll
;             for (int q = 0; q < 2; ++q) { const int r = 2 * k + q, ai = r >> 2, m = r & 3; const size_t off = (size_t)EPI_ROW(r) * D + col0; float sr = 0.f;
; #pragma unroll
;                 for (int bj = 0; bj < 2; ++bj) { const f32x4 o0 = cur[q][2 * bj] + acc[ai][bj][m][0], o1 = cur[q][2 * bj + 1] + acc[ai][bj][m][1];
;                     *(f32x4*)(out + off + bj * HALF) = o0; *(f32x4*)(out + off + bj * HALF + 4) = o1;
;                     u32x4 w; w.x = cvt_pk_bf16(o0[0], o0[1]); w.y = cvt_pk_bf16(o0[2], o0[3]); w.z = cvt_pk_bf16(o1[0], o1[1]); w.w = cvt_pk_bf16(o1[2], o1[3]); *(u32x4*)(hb + off + bj * HALF) = w; sr += ssq4(o0) + ssq4(o1); }
;                 s[ai][m] = sr; }
	global_load_dwordx4 v[196:199], v[122:123], off
	global_load_dwordx4 v[114:117], v[122:123], off offset:528
	global_load_dwordx4 v[118:121], v[122:123], off offset:512
	global_store_dwordx4 v[184:185], v[94:97], off nt
	global_store_dwordx4 v[184:185], v[90:93], off offset:16 nt
	global_store_dwordx4 v[124:125], v[200:203], off
	global_store_dwordx4 v[184:185], v[86:89], off offset:512 nt
	global_store_dwordx4 v[184:185], v[78:81], off offset:528 nt
	v_cvt_pk_bf16_f32 v200, v86, v87
	v_cvt_pk_bf16_f32 v201, v88, v89
	v_cvt_pk_bf16_f32 v202, v78, v79
	v_cvt_pk_bf16_f32 v203, v80, v81
	global_store_dwordx4 v[124:125], v[200:203], off offset:256
	v_lshlrev_b64 v[124:125], 11, v[134:135]
	v_lshl_add_u64 v[124:125], v[124:125], 0, v[130:131]
	v_pk_add_f32 v[84:85], v[84:85], v[226:227]
	v_pk_add_f32 v[82:83], v[82:83], v[224:225]
	v_pk_add_f32 v[76:77], v[76:77], v[222:223]
	v_pk_add_f32 v[74:75], v[74:75], v[220:221]
	v_cvt_pk_bf16_f32 v134, v82, v83
	v_cvt_pk_bf16_f32 v135, v84, v85
	v_cvt_pk_bf16_f32 v136, v74, v75
	v_cvt_pk_bf16_f32 v137, v76, v77
	v_lshl_add_u64 v[124:125], v[124:125], 1, s[60:61]
	v_pk_add_f32 v[72:73], v[72:73], v[234:235]
	v_pk_add_f32 v[70:71], v[70:71], v[232:233]
	v_pk_add_f32 v[68:69], v[68:69], v[230:231]
	v_pk_add_f32 v[66:67], v[66:67], v[228:229]
	v_add_u32_e32 v184, 0xa0, v162
	global_store_dwordx4 v[138:139], v[82:85], off nt
	global_store_dwordx4 v[138:139], v[74:77], off offset:16 nt
	global_store_dwordx4 v[124:125], v[134:137], off
	v_ashrrev_i32_e32 v185, 31, v184
	global_store_dwordx4 v[138:139], v[70:73], off offset:512 nt
	global_store_dwordx4 v[138:139], v[66:69], off offset:528 nt
	v_cvt_pk_bf16_f32 v134, v70, v71
	v_cvt_pk_bf16_f32 v135, v72, v73
	v_cvt_pk_bf16_f32 v136, v66, v67
	v_cvt_pk_bf16_f32 v137, v68, v69
	global_store_dwordx4 v[124:125], v[134:137], off offset:256
	v_lshlrev_b64 v[124:125], 13, v[184:185]
	v_lshl_add_u64 v[212:213], v[132:133], 0, v[124:125]
	v_add_f32_e32 v124, v163, v181
	v_mul_f32_e32 v125, v141, v141
	v_mul_f32_e32 v138, v143, v143
	global_load_dwordx4 v[134:137], v[212:213], off offset:16
	global_load_dwordx4 v[200:203], v[212:213], off
	v_add_f32_e32 v124, v148, v124
	v_fmac_f32_e32 v125, v140, v140
	v_fmac_f32_e32 v138, v142, v142
	v_mul_f32_e32 v148, v145, v145
	v_mul_f32_e32 v147, v147, v147
	v_add_f32_e32 v125, v125, v138
	v_fmac_f32_e32 v148, v144, v144
	global_load_dwordx4 v[138:141], v[212:213], off offset:528
	global_load_dwordx4 v[142:145], v[212:213], off offset:512
	v_fmac_f32_e32 v147, v146, v146
	v_add_f32_e32 v146, v148, v147
	v_add_u32_e32 v214, 0xb0, v162
	v_add_f32_e32 v125, v125, v146
	v_ashrrev_i32_e32 v215, 31, v214
	v_add_f32_e32 v181, v124, v125
	v_lshlrev_b64 v[124:125], 13, v[214:215]
	v_lshl_add_u64 v[124:125], v[132:133], 0, v[124:125]
	global_load_dwordx4 v[146:149], v[124:125], off offset:16
	global_load_dwordx4 v[162:165], v[124:125], off
	global_load_dwordx4 v[204:207], v[124:125], off offset:528
	global_load_dwordx4 v[208:211], v[124:125], off offset:512
	v_lshlrev_b64 v[132:133], 11, v[178:179]
	v_lshl_add_u64 v[132:133], v[132:133], 0, v[130:131]
	v_lshl_add_u64 v[132:133], v[132:133], 1, s[60:61]
	s_waitcnt vmcnt(27)
	v_pk_add_f32 v[60:61], v[60:61], v[128:129]
	s_waitcnt vmcnt(26)
	v_pk_add_f32 v[64:65], v[64:65], v[172:173]
	v_pk_add_f32 v[62:63], v[62:63], v[170:171]
	v_pk_add_f32 v[58:59], v[58:59], v[126:127]
	v_cvt_pk_bf16_f32 v126, v62, v63
	v_cvt_pk_bf16_f32 v127, v64, v65
	v_cvt_pk_bf16_f32 v128, v58, v59
	v_cvt_pk_bf16_f32 v129, v60, v61
	s_waitcnt vmcnt(24)
	v_pk_add_f32 v[56:57], v[56:57], v[190:191]
	v_pk_add_f32 v[54:55], v[54:55], v[188:189]
	v_pk_add_f32 v[48:49], v[48:49], v[176:177]
	v_pk_add_f32 v[46:47], v[46:47], v[174:175]
	global_store_dwordx4 v[236:237], v[62:65], off nt
	global_store_dwordx4 v[236:237], v[58:61], off offset:16 nt
	global_store_dwordx4 v[132:133], v[126:129], off nt
	global_store_dwordx4 v[236:237], v[54:57], off offset:512 nt
	global_store_dwordx4 v[236:237], v[46:49], off offset:528 nt
	v_cvt_pk_bf16_f32 v126, v54, v55
	v_cvt_pk_bf16_f32 v127, v56, v57
	v_cvt_pk_bf16_f32 v128, v46, v47
	v_cvt_pk_bf16_f32 v129, v48, v49
	global_store_dwordx4 v[132:133], v[126:129], off offset:256 nt
	s_waitcnt vmcnt(28)
; __device__ __forceinline__ float shx(float v, int o, int lane) { return __builtin_bit_cast(float, __builtin_amdgcn_ds_bpermute((lane ^ o) << 2, __builtin_bit_cast(int, v))); }
; __device__ __forceinline__ float ssq4(const f32x4 o) { return (o[0] * o[0] + o[1] * o[1]) + (o[2] * o[2] + o[3] * o[3]); }
; template <bool SIXTEEN> __device__ __forceinline__ void tile_ssq(const float (&s)[2][4], const Unit& u, int wr, int wc, int fr, int fq, float* ssq, LAS float* ptab) {
;     ...
;         for (int m = 0; m < 4; ++m) { float v = s[ai][m]; v += shx(v, 16, lane); v += shx(v, 32, lane); if (fq == 0) ptab[(ai * HALF + wr * 64 + m * 16 + fr) * 4 + wc] = v; }
;     __device__ __forceinline__ void operator()(f32x4 (&acc)[2][2][4][2], const Unit& u, int wr, int wc, int fr, int fq) const {
;     ...
;             for (int q = 0; q < 2; ++q) { const int r = 2 * k + q, ai = r >> 2, m = r & 3; const size_t off = (size_t)EPI_ROW(r) * D + col0; float sr = 0.f;
; #pragma unroll
;                 for (int bj = 0; bj < 2; ++bj) { const f32x4 o0 = cur[q][2 * bj] + acc[ai][bj][m][0], o1 = cur[q][2 * bj + 1] + acc[ai][bj][m][1];
;                     *(f32x4*)(out + off + bj * HALF) = o0; *(f32x4*)(out + off + bj * HALF + 4) = o1;
;                     u32x4 w; w.x = cvt_pk_bf16(o0[0], o0[1]); w.y = cvt_pk_bf16(o0[2], o0[3]); w.z = cvt_pk_bf16(o1[0], o1[1]); w.w = cvt_pk_bf16(o1[2], o1[3]); *(u32x4*)(hb + off + bj * HALF) = w; sr += ssq4(o0) + ssq4(o1); }
;                 s[ai][m] = sr; }
	v_pk_add_f32 v[52:53], v[52:53], v[198:199]
	v_pk_add_f32 v[50:51], v[50:51], v[196:197]
	v_lshlrev_b64 v[126:127], 11, v[238:239]
	v_lshl_add_u64 v[132:133], v[126:127], 0, v[130:131]
	v_pk_add_f32 v[44:45], v[44:45], v[194:195]
	v_pk_add_f32 v[42:43], v[42:43], v[192:193]
	s_waitcnt vmcnt(26)
	v_pk_add_f32 v[40:41], v[40:41], v[120:121]
	v_pk_add_f32 v[38:39], v[38:39], v[118:119]
	v_pk_add_f32 v[36:37], v[36:37], v[116:117]
	v_pk_add_f32 v[34:35], v[34:35], v[114:115]
	v_cvt_pk_bf16_f32 v126, v50, v51
	v_cvt_pk_bf16_f32 v127, v52, v53
	v_cvt_pk_bf16_f32 v128, v42, v43
	v_cvt_pk_bf16_f32 v129, v44, v45
	v_lshl_add_u64 v[132:133], v[132:133], 1, s[60:61]
	v_cvt_pk_bf16_f32 v114, v38, v39
	v_cvt_pk_bf16_f32 v115, v40, v41
	v_cvt_pk_bf16_f32 v116, v34, v35
	v_cvt_pk_bf16_f32 v117, v36, v37
	global_store_dwordx4 v[122:123], v[50:53], off nt
	global_store_dwordx4 v[122:123], v[42:45], off offset:16 nt
	global_store_dwordx4 v[132:133], v[126:129], off nt
	global_store_dwordx4 v[122:123], v[38:41], off offset:512 nt
	global_store_dwordx4 v[122:123], v[34:37], off offset:528 nt
	global_store_dwordx4 v[132:133], v[114:117], off offset:256 nt
	s_waitcnt vmcnt(19)
	v_pk_add_f32 v[28:29], v[28:29], v[136:137]
	s_waitcnt vmcnt(18)
	v_pk_add_f32 v[32:33], v[32:33], v[202:203]
	v_lshlrev_b64 v[114:115], 11, v[184:185]
	v_lshl_add_u64 v[118:119], v[114:115], 0, v[130:131]
	v_pk_add_f32 v[30:31], v[30:31], v[200:201]
	v_pk_add_f32 v[26:27], v[26:27], v[134:135]
	v_cvt_pk_bf16_f32 v114, v30, v31
	v_cvt_pk_bf16_f32 v115, v32, v33
	v_cvt_pk_bf16_f32 v116, v26, v27
	v_cvt_pk_bf16_f32 v117, v28, v29
	v_lshl_add_u64 v[118:119], v[118:119], 1, s[60:61]
	s_waitcnt vmcnt(16)
	v_pk_add_f32 v[24:25], v[24:25], v[144:145]
	v_pk_add_f32 v[22:23], v[22:23], v[142:143]
	v_pk_add_f32 v[16:17], v[16:17], v[140:141]
	v_pk_add_f32 v[14:15], v[14:15], v[138:139]
	global_store_dwordx4 v[212:213], v[30:33], off nt
	global_store_dwordx4 v[212:213], v[26:29], off offset:16 nt
	global_store_dwordx4 v[118:119], v[114:117], off nt
	global_store_dwordx4 v[212:213], v[22:25], off offset:512 nt
	global_store_dwordx4 v[212:213], v[14:17], off offset:528 nt
	v_cvt_pk_bf16_f32 v114, v22, v23
	v_cvt_pk_bf16_f32 v115, v24, v25
	v_cvt_pk_bf16_f32 v116, v14, v15
	v_cvt_pk_bf16_f32 v117, v16, v17
	global_store_dwordx4 v[118:119], v[114:117], off offset:256 nt
	s_waitcnt vmcnt(20)
	v_pk_add_f32 v[20:21], v[20:21], v[164:165]
	v_pk_add_f32 v[18:19], v[18:19], v[162:163]
	v_lshlrev_b64 v[114:115], 11, v[214:215]
	v_lshl_add_u64 v[118:119], v[114:115], 0, v[130:131]
	v_pk_add_f32 v[12:13], v[12:13], v[148:149]
	v_pk_add_f32 v[10:11], v[10:11], v[146:147]
	v_cvt_pk_bf16_f32 v114, v18, v19
	v_cvt_pk_bf16_f32 v115, v20, v21
	v_cvt_pk_bf16_f32 v116, v10, v11
	v_cvt_pk_bf16_f32 v117, v12, v13
	v_lshl_add_u64 v[120:121], v[118:119], 1, s[60:61]
	global_store_dwordx4 v[124:125], v[18:21], off nt
	global_store_dwordx4 v[124:125], v[10:13], off offset:16 nt
	global_store_dwordx4 v[120:121], v[114:117], off nt
	s_waitcnt vmcnt(21)
	v_pk_add_f32 v[8:9], v[8:9], v[210:211]
	v_pk_add_f32 v[6:7], v[6:7], v[208:209]
	v_and_b32_e32 v114, 63, v169
	v_lshlrev_b32_e32 v122, 2, v114
	v_xor_b32_e32 v115, 64, v122
	ds_bpermute_b32 v123, v115, v181
	v_pk_add_f32 v[4:5], v[4:5], v[206:207]
	v_pk_add_f32 v[2:3], v[2:3], v[204:205]
	v_cvt_pk_bf16_f32 v116, v6, v7
	v_cvt_pk_bf16_f32 v117, v8, v9
	v_cvt_pk_bf16_f32 v118, v2, v3
	v_cvt_pk_bf16_f32 v119, v4, v5
	global_store_dwordx4 v[124:125], v[6:9], off offset:512 nt
	global_store_dwordx4 v[124:125], v[2:5], off offset:528 nt
	global_store_dwordx4 v[120:121], v[116:119], off offset:256 nt
	s_nop 1
	v_xor_b32_e32 v117, 0x80, v122
	s_waitcnt lgkmcnt(0)
	v_add_f32_e32 v118, v181, v123
	ds_bpermute_b32 v119, v117, v118
	v_lshl_add_u32 v116, v167, 4, s33
	s_and_saveexec_b64 s[8:9], vcc
	s_cbranch_execz .LBB0_2240
	s_waitcnt lgkmcnt(0)
	v_add_f32_e32 v118, v118, v119
	ds_write_b32 v116, v118

; __device__ __forceinline__ float shx(float v, int o, int lane) { return __builtin_bit_cast(float, __builtin_amdgcn_ds_bpermute((lane ^ o) << 2, __builtin_bit_cast(int, v))); }
; __device__ __forceinline__ void rows_rstd(const float* ssq, int row0  , int fr, int fq, float (&rs)[8]) {
;     const int lane = fq * 16 + fr; f32x4 p[8];
;     const float* b0 = ssq + (size_t)row0 * 16 + fq * 4;
; #pragma unroll
;     for (int r = 0; r < 8; ++r) p[r] = *(const f32x4*)(b0 + (r >> 2) * (HALF * 16) + (r & 3) * 256);
; #pragma unroll
;     for (int r = 0; r < 8; ++r) { float v = (p[r][0] + p[r][1]) + (p[r][2] + p[r][3]); v += shx(v, 16, lane); v += shx(v, 32, lane); rs[r] = rsqrtf(v * (1.0f / 2048.0f) + 1e-6f); }
; }
.LBB0_2335:
	v_mov_b32_e32 v183, v246
	s_lshl_b32 s1, s8, 8
	s_add_i32 s3, s1, s68
	v_and_b32_e32 v184, 15, v183
	v_or_b32_e32 v172, s3, v184
	v_ashrrev_i32_e32 v173, 31, v172
	v_readlane_b32 s8, v254, 13
	v_bfe_u32 v185, v183, 4, 2
	v_lshlrev_b64 v[130:131], 6, v[172:173]
	v_readlane_b32 s9, v254, 14
	v_lshlrev_b32_e32 v132, 4, v185
	v_mov_b32_e32 v133, v0
	v_lshl_add_u64 v[130:131], s[8:9], 0, v[130:131]
	v_lshl_add_u64 v[130:131], v[130:131], 0, v[132:133]
	global_load_dwordx4 v[174:177], v[130:131], off
	global_load_dwordx4 v[188:191], v[130:131], off offset:1024
	global_load_dwordx4 v[150:153], v[130:131], off offset:2048
	global_load_dwordx4 v[146:149], v[130:131], off offset:3072
	v_add_co_u32_e32 v130, vcc, s63, v130
	v_lshlrev_b32_e32 v166, 6, v185
	s_nop 0
	v_addc_co_u32_e32 v131, vcc, 0, v131, vcc
	global_load_dwordx4 v[142:145], v[130:131], off
	global_load_dwordx4 v[138:141], v[130:131], off offset:1024
	global_load_dwordx4 v[134:137], v[130:131], off offset:2048
	s_nop 0
	global_load_dwordx4 v[130:133], v[130:131], off offset:3072
	v_lshlrev_b32_e32 v167, 2, v184
	v_bitop3_b32 v169, v166, 64, v167 bitop3:0x36
	v_bitop3_b32 v167, v166, s71, v167 bitop3:0x36
	s_mov_b32 s8, 0x358637bd
	v_mov_b32_e32 v182, v246
	v_or_b32_e32 v242, 32, v172
	v_or_b32_e32 v228, 48, v172
	v_ashrrev_i32_e32 v243, 31, v242
	v_ashrrev_i32_e32 v229, 31, v228
	s_waitcnt vmcnt(0)
	v_mov_b32_e32 v170, v175
	v_mov_b32_e32 v171, v176
	v_mov_b32_e32 v175, v177
	v_pk_add_f32 v[170:171], v[170:171], v[174:175]
	v_mov_b32_e32 v174, v189
	v_mov_b32_e32 v175, v190
	v_mov_b32_e32 v189, v191
	v_pk_add_f32 v[174:175], v[174:175], v[188:189]
	v_mov_b32_e32 v177, v170
	v_mov_b32_e32 v176, v174
	v_mov_b32_e32 v170, v175
	v_pk_add_f32 v[170:171], v[176:177], v[170:171]
	ds_bpermute_b32 v175, v169, v171
	ds_bpermute_b32 v174, v169, v170
	s_waitcnt lgkmcnt(0)
	v_pk_add_f32 v[170:171], v[170:171], v[174:175]
	ds_bpermute_b32 v175, v167, v171
	ds_bpermute_b32 v174, v167, v170
	s_waitcnt lgkmcnt(0)
	v_pk_add_f32 v[174:175], v[170:171], v[174:175]
	v_mov_b64_e32 v[170:171], s[8:9]
	v_pk_fma_f32 v[174:175], v[174:175], s[2:3], v[170:171] op_sel_hi:[1,0,0]
	s_nop 0
	v_mul_f32_e32 v166, 0x4b800000, v175
	v_cmp_gt_f32_e64 s[8:9], s46, v175
	v_cmp_gt_f32_e32 vcc, s46, v174
	s_nop 0
	v_cndmask_b32_e64 v166, v175, v166, s[8:9]
	v_rsq_f32_e32 v166, v166
	v_mov_b32_e32 v175, v152
	v_mov_b32_e32 v152, v147
	v_mov_b32_e32 v147, v149
	v_mul_f32_e32 v168, 0x45800000, v166
	v_cndmask_b32_e64 v168, v166, v168, s[8:9]
	v_mul_f32_e32 v166, 0x4b800000, v174
	v_cndmask_b32_e32 v166, v174, v166, vcc
	v_rsq_f32_e32 v166, v166
	v_pk_mul_f32 v[252:253], v[128:129], v[168:169] op_sel_hi:[1,0]
	v_pk_mul_f32 v[178:179], v[126:127], v[168:169] op_sel_hi:[1,0]
	v_pk_mul_f32 v[248:249], v[124:125], v[168:169] op_sel_hi:[1,0]
	v_mul_f32_e32 v174, 0x45800000, v166
	v_cndmask_b32_e32 v166, v166, v174, vcc
	v_mov_b32_e32 v174, v151
	v_mov_b32_e32 v151, v153
	v_mov_b32_e32 v153, v148
	v_pk_add_f32 v[150:151], v[174:175], v[150:151]
	v_pk_add_f32 v[146:147], v[152:153], v[146:147]
	v_mov_b32_e32 v149, v150
	v_mov_b32_e32 v148, v146
	v_mov_b32_e32 v150, v147
	v_pk_add_f32 v[146:147], v[148:149], v[150:151]
	ds_bpermute_b32 v149, v169, v147
	ds_bpermute_b32 v148, v169, v146
	v_mov_b32_e32 v150, v143
	v_mov_b32_e32 v151, v144
	v_mov_b32_e32 v143, v145
	v_mov_b32_e32 v144, v139
	v_mov_b32_e32 v145, v140
	v_mov_b32_e32 v139, v141
	v_pk_add_f32 v[142:143], v[150:151], v[142:143]
	v_pk_add_f32 v[138:139], v[144:145], v[138:139]
	s_waitcnt lgkmcnt(0)
	v_pk_add_f32 v[146:147], v[146:147], v[148:149]
	v_mov_b32_e32 v140, v138
	v_mov_b32_e32 v141, v142
	v_mov_b32_e32 v142, v139
	ds_bpermute_b32 v149, v167, v147
	ds_bpermute_b32 v148, v167, v146
	v_pk_add_f32 v[138:139], v[140:141], v[142:143]
	ds_bpermute_b32 v141, v169, v139
	ds_bpermute_b32 v140, v169, v138
	v_mov_b32_e32 v142, v135
	v_mov_b32_e32 v143, v136
	v_mov_b32_e32 v135, v137
	v_mov_b32_e32 v136, v131
	v_mov_b32_e32 v137, v132
	v_mov_b32_e32 v131, v133
	s_waitcnt lgkmcnt(2)
	v_pk_add_f32 v[146:147], v[146:147], v[148:149]
	v_pk_add_f32 v[134:135], v[142:143], v[134:135]
	v_pk_add_f32 v[130:131], v[136:137], v[130:131]
	v_pk_fma_f32 v[146:147], v[146:147], s[2:3], v[170:171] op_sel_hi:[1,0,0]
	s_waitcnt lgkmcnt(0)
	v_pk_add_f32 v[138:139], v[138:139], v[140:141]
	v_mov_b32_e32 v132, v130
	v_mov_b32_e32 v133, v134
	v_mov_b32_e32 v134, v131
	v_mul_f32_e32 v148, 0x4b800000, v147
	v_cmp_gt_f32_e64 s[8:9], s46, v147
	ds_bpermute_b32 v141, v167, v139
	ds_bpermute_b32 v140, v167, v138
	v_pk_add_f32 v[130:131], v[132:133], v[134:135]
	v_cndmask_b32_e64 v147, v147, v148, s[8:9]
	ds_bpermute_b32 v133, v169, v131
	ds_bpermute_b32 v132, v169, v130
	v_rsq_f32_e32 v147, v147
	s_waitcnt lgkmcnt(2)
	v_pk_add_f32 v[138:139], v[138:139], v[140:141]
	v_cmp_gt_f32_e32 vcc, s46, v146
	v_pk_fma_f32 v[138:139], v[138:139], s[2:3], v[170:171] op_sel_hi:[1,0,0]
	v_mul_f32_e32 v148, 0x45800000, v147
	s_waitcnt lgkmcnt(0)
	v_pk_add_f32 v[130:131], v[130:131], v[132:133]
	v_cndmask_b32_e64 v148, v147, v148, s[8:9]
	v_mul_f32_e32 v147, 0x4b800000, v146
	v_mul_f32_e32 v140, 0x4b800000, v139
	v_cmp_gt_f32_e64 s[8:9], s46, v139
	ds_bpermute_b32 v133, v167, v131
	ds_bpermute_b32 v132, v167, v130
	v_cndmask_b32_e32 v146, v146, v147, vcc
	v_cndmask_b32_e64 v139, v139, v140, s[8:9]
	v_rsq_f32_e32 v146, v146
	v_rsq_f32_e32 v139, v139
	s_waitcnt lgkmcnt(0)
;     __device__ __forceinline__ void operator()(f32x4 (&acc)[2][2][4][2], const Unit& u, int wr, int wc, int fr, int fq) const {
;     ...
;         { float rsv[8]; rows_rstd(ssq_in, u.pm * BM + wr * 64 + fr, fr, fq, rsv);
; #pragma unroll
;             for (int r = 0; r < 8; ++r)
; #pragma unroll
;                 for (int c = 0; c < 4; ++c) acc[r >> 2][c >> 1][r & 3][c & 1] = acc[r >> 2][c >> 1][r & 3][c & 1] * rsv[r]; }
;         f32x4 cur[2][4], nxt[2][4]; u32x2 pcur[4], pnxt[4];
; #pragma unroll
;         for (int q = 0; q < 2; ++q)
; #pragma unroll
;             for (int c = 0; c < 4; ++c) cur[q][c] = *(const f32x4*)(h + (size_t)EPI_ROW(q) * D + col0 + (c >> 1) * HALF + (c & 1) * 4);
; #pragma unroll
;         for (int c = 0; c < 4; ++c) pcur[c] = *(const u32x2*)(pp + (size_t)EPI_ROW(0) * D + col0 + (c >> 1) * HALF + (c & 1) * 4);
; #pragma unroll
;         for (int k = 0; k < 4; ++k) {
;             if (k < 3) {
; #pragma unroll
;                 for (int q = 0; q < 2; ++q)
; #pragma unroll
;                     for (int c = 0; c < 4; ++c) nxt[q][c] = *(const f32x4*)(h + (size_t)EPI_ROW(2 * k + 2 + q) * D + col0 + (c >> 1) * HALF + (c & 1) * 4);
	v_pk_add_f32 v[130:131], v[130:131], v[132:133]
	v_pk_mul_f32 v[250:251], v[122:123], v[168:169] op_sel_hi:[1,0]
	v_mul_f32_e32 v147, 0x45800000, v146
	v_mul_f32_e32 v140, 0x45800000, v139
	v_pk_fma_f32 v[130:131], v[130:131], s[2:3], v[170:171] op_sel_hi:[1,0,0]
	v_cndmask_b32_e32 v146, v146, v147, vcc
	v_cmp_gt_f32_e32 vcc, s46, v138
	v_cndmask_b32_e64 v140, v139, v140, s[8:9]
	v_mul_f32_e32 v139, 0x4b800000, v138
	v_mul_f32_e32 v132, 0x4b800000, v131
	v_cmp_gt_f32_e64 s[8:9], s46, v131
	v_cndmask_b32_e32 v138, v138, v139, vcc
	v_rsq_f32_e32 v138, v138
	v_cndmask_b32_e64 v131, v131, v132, s[8:9]
	v_rsq_f32_e32 v131, v131
	s_lshl_b32 s3, s0, 8
	v_mul_f32_e32 v139, 0x45800000, v138
	v_cndmask_b32_e32 v138, v138, v139, vcc
	v_mul_f32_e32 v132, 0x45800000, v131
	v_cmp_gt_f32_e32 vcc, s46, v130
	v_cndmask_b32_e64 v132, v131, v132, s[8:9]
	v_mul_f32_e32 v131, 0x4b800000, v130
	v_cndmask_b32_e32 v130, v130, v131, vcc
	v_rsq_f32_e32 v130, v130
	s_or_b32 s3, s3, s69
	v_pk_mul_f32 v[244:245], v[112:113], v[168:169] op_sel_hi:[1,0]
	v_pk_mul_f32 v[246:247], v[110:111], v[168:169] op_sel_hi:[1,0]
	v_mul_f32_e32 v131, 0x45800000, v130
	v_cndmask_b32_e32 v152, v130, v131, vcc
	v_pk_mul_f32 v[238:239], v[108:109], v[168:169] op_sel_hi:[1,0]
	v_pk_mul_f32 v[240:241], v[106:107], v[168:169] op_sel_hi:[1,0]
	v_pk_mul_f32 v[234:235], v[120:121], v[166:167] op_sel_hi:[1,0]
	v_pk_mul_f32 v[236:237], v[118:119], v[166:167] op_sel_hi:[1,0]
	v_pk_mul_f32 v[222:223], v[116:117], v[166:167] op_sel_hi:[1,0]
	v_pk_mul_f32 v[232:233], v[114:115], v[166:167] op_sel_hi:[1,0]
	v_pk_mul_f32 v[96:97], v[96:97], v[166:167] op_sel_hi:[1,0]
	v_pk_mul_f32 v[94:95], v[94:95], v[166:167] op_sel_hi:[1,0]
	v_pk_mul_f32 v[92:93], v[92:93], v[166:167] op_sel_hi:[1,0]
	v_pk_mul_f32 v[90:91], v[90:91], v[166:167] op_sel_hi:[1,0]
	v_pk_mul_f32 v[224:225], v[104:105], v[148:149] op_sel_hi:[1,0]
	v_pk_mul_f32 v[226:227], v[102:103], v[148:149] op_sel_hi:[1,0]
	v_pk_mul_f32 v[126:127], v[100:101], v[148:149] op_sel_hi:[1,0]
	v_pk_mul_f32 v[128:129], v[98:99], v[148:149] op_sel_hi:[1,0]
	v_pk_mul_f32 v[122:123], v[80:81], v[148:149] op_sel_hi:[1,0]
	v_pk_mul_f32 v[124:125], v[78:79], v[148:149] op_sel_hi:[1,0]
	v_pk_mul_f32 v[114:115], v[76:77], v[148:149] op_sel_hi:[1,0]
	v_pk_mul_f32 v[116:117], v[74:75], v[148:149] op_sel_hi:[1,0]
	v_pk_mul_f32 v[110:111], v[88:89], v[146:147] op_sel_hi:[1,0]
	v_pk_mul_f32 v[112:113], v[86:87], v[146:147] op_sel_hi:[1,0]
	v_pk_mul_f32 v[106:107], v[84:85], v[146:147] op_sel_hi:[1,0]
	v_pk_mul_f32 v[108:109], v[82:83], v[146:147] op_sel_hi:[1,0]
	v_pk_mul_f32 v[102:103], v[72:73], v[146:147] op_sel_hi:[1,0]
	v_pk_mul_f32 v[104:105], v[70:71], v[146:147] op_sel_hi:[1,0]
	v_pk_mul_f32 v[98:99], v[68:69], v[146:147] op_sel_hi:[1,0]
	v_pk_mul_f32 v[100:101], v[66:67], v[146:147] op_sel_hi:[1,0]
	v_pk_mul_f32 v[218:219], v[64:65], v[140:141] op_sel_hi:[1,0]
	v_pk_mul_f32 v[220:221], v[62:63], v[140:141] op_sel_hi:[1,0]
	v_pk_mul_f32 v[214:215], v[60:61], v[140:141] op_sel_hi:[1,0]
	v_pk_mul_f32 v[216:217], v[58:59], v[140:141] op_sel_hi:[1,0]
	v_pk_mul_f32 v[210:211], v[44:45], v[140:141] op_sel_hi:[1,0]
	v_pk_mul_f32 v[212:213], v[42:43], v[140:141] op_sel_hi:[1,0]
	v_pk_mul_f32 v[206:207], v[36:37], v[140:141] op_sel_hi:[1,0]
	v_pk_mul_f32 v[208:209], v[34:35], v[140:141] op_sel_hi:[1,0]
	v_pk_mul_f32 v[202:203], v[56:57], v[138:139] op_sel_hi:[1,0]
	v_pk_mul_f32 v[204:205], v[54:55], v[138:139] op_sel_hi:[1,0]
	v_pk_mul_f32 v[196:197], v[52:53], v[138:139] op_sel_hi:[1,0]
	v_pk_mul_f32 v[200:201], v[50:51], v[138:139] op_sel_hi:[1,0]
	v_pk_mul_f32 v[192:193], v[28:29], v[138:139] op_sel_hi:[1,0]
	v_pk_mul_f32 v[194:195], v[26:27], v[138:139] op_sel_hi:[1,0]
	v_pk_mul_f32 v[188:189], v[20:21], v[138:139] op_sel_hi:[1,0]
	v_pk_mul_f32 v[190:191], v[18:19], v[138:139] op_sel_hi:[1,0]
	v_pk_mul_f32 v[174:175], v[48:49], v[132:133] op_sel_hi:[1,0]
	v_pk_mul_f32 v[176:177], v[46:47], v[132:133] op_sel_hi:[1,0]
	v_pk_mul_f32 v[168:169], v[40:41], v[132:133] op_sel_hi:[1,0]
	v_pk_mul_f32 v[170:171], v[38:39], v[132:133] op_sel_hi:[1,0]
	v_pk_mul_f32 v[150:151], v[16:17], v[132:133] op_sel_hi:[1,0]
	v_pk_mul_f32 v[166:167], v[14:15], v[132:133] op_sel_hi:[1,0]
	v_pk_mul_f32 v[146:147], v[12:13], v[132:133] op_sel_hi:[1,0]
	v_pk_mul_f32 v[148:149], v[10:11], v[132:133] op_sel_hi:[1,0]
	v_pk_mul_f32 v[142:143], v[32:33], v[152:153] op_sel_hi:[1,0]
	v_pk_mul_f32 v[144:145], v[30:31], v[152:153] op_sel_hi:[1,0]
	v_pk_mul_f32 v[138:139], v[24:25], v[152:153] op_sel_hi:[1,0]
	v_pk_mul_f32 v[140:141], v[22:23], v[152:153] op_sel_hi:[1,0]
	v_pk_mul_f32 v[134:135], v[8:9], v[152:153] op_sel_hi:[1,0]
	v_pk_mul_f32 v[136:137], v[6:7], v[152:153] op_sel_hi:[1,0]
	v_pk_mul_f32 v[130:131], v[4:5], v[152:153] op_sel_hi:[1,0]
	v_pk_mul_f32 v[132:133], v[2:3], v[152:153] op_sel_hi:[1,0]
	v_lshl_or_b32 v152, v185, 3, s3
	v_ashrrev_i32_e32 v153, 31, v152
	v_or_b32_e32 v84, 16, v172
	v_lshl_add_u64 v[118:119], v[152:153], 2, s[36:37]
	v_lshlrev_b64 v[2:3], 13, v[172:173]
	v_ashrrev_i32_e32 v85, 31, v84
	v_lshlrev_b64 v[18:19], 12, v[172:173]
	v_lshl_add_u64 v[86:87], v[118:119], 0, v[2:3]
	v_lshlrev_b64 v[2:3], 13, v[84:85]
	v_lshl_add_u64 v[18:19], s[56:57], 0, v[18:19]
	v_lshlrev_b64 v[198:199], 1, v[152:153]
	v_lshl_add_u64 v[82:83], v[118:119], 0, v[2:3]
	v_lshl_add_u64 v[18:19], v[18:19], 0, v[198:199]
	global_load_dwordx4 v[66:69], v[86:87], off offset:16
	global_load_dwordx4 v[78:81], v[86:87], off
	global_load_dwordx4 v[54:57], v[86:87], off offset:528
	global_load_dwordx4 v[62:65], v[86:87], off offset:512
	global_load_dwordx4 v[6:9], v[82:83], off offset:16
; __device__ __forceinline__ float sigmoidf_(float x) { return __builtin_amdgcn_rcpf(1.0f + __expf(-x)); }
; __device__ __forceinline__ float ssq4(const f32x4 o) { return (o[0] * o[0] + o[1] * o[1]) + (o[2] * o[2] + o[3] * o[3]); }
;     __device__ __forceinline__ void operator()(f32x4 (&acc)[2][2][4][2], const Unit& u, int wr, int wc, int fr, int fq) const {
;     ...
;             for (int q = 0; q < 2; ++q) { const int r = 2 * k + q, ai = r >> 2, m = r & 3; const size_t off = (size_t)EPI_ROW(r) * D + col0; float sr = 0.f;
;                 if (r < 7) {
; #pragma unroll
;                     for (int c = 0; c < 4; ++c) pnxt[c] = *(const u32x2*)(pp + (size_t)EPI_ROW(r + 1) * D + col0 + (c >> 1) * HALF + (c & 1) * 4);
;                 }
;                 asm volatile("" ::: "memory");
; #pragma unroll
;                 for (int bj = 0; bj < 2; ++bj) { f32x4 o2[2];
; #pragma unroll
;                     for (int n = 0; n < 2; ++n) { const f32x4 b = cur[q][2 * bj + n]; const u32x2 qw = pcur[2 * bj + n];
;                         const f32x4 pq = (f32x4){bflo(qw.x), bfhi(qw.x), bflo(qw.y), bfhi(qw.y)}; const f32x4 a = acc[ai][bj][m][n];
; #pragma unroll
;                         for (int j = 0; j < 4; ++j) o2[n][j] = b[j] + pq[j] * sigmoidf_(a[j]); }
;                     *(f32x4*)(h + off + bj * HALF) = o2[0]; *(f32x4*)(h + off + bj * HALF + 4) = o2[1];
;                     if (!LAST) { u32x4 w; w.x = cvt_pk_bf16(o2[0][0], o2[0][1]); w.y = cvt_pk_bf16(o2[0][2], o2[0][3]); w.z = cvt_pk_bf16(o2[1][0], o2[1][1]); w.w = cvt_pk_bf16(o2[1][2], o2[1][3]);
;                         *(u32x4*)(hb + off + bj * HALF) = w; sr += ssq4(o2[0]) + ssq4(o2[1]); } }
	global_load_dwordx4 v[2:5], v[82:83], off
	global_load_dwordx4 v[14:17], v[82:83], off offset:528
	global_load_dwordx4 v[10:13], v[82:83], off offset:512
	global_load_dwordx4 v[74:77], v[18:19], off
	global_load_dwordx4 v[70:73], v[18:19], off offset:256
	v_lshlrev_b64 v[50:51], 11, v[172:173]
	v_mul_f32_e32 v173, 0xbfb8aa3b, v178
	v_exp_f32_e32 v173, v173
	v_lshl_add_u64 v[88:89], v[50:51], 0, v[152:153]
	v_lshlrev_b64 v[50:51], 12, v[84:85]
	v_lshlrev_b64 v[18:19], 13, v[242:243]
	v_add_f32_e32 v173, 1.0, v173
	v_rcp_f32_e32 v178, v173
	v_mul_f32_e32 v173, 0xbfb8aa3b, v179
	v_exp_f32_e32 v173, v173
	v_lshlrev_b64 v[34:35], 13, v[228:229]
	v_lshl_add_u64 v[50:51], s[56:57], 0, v[50:51]
	v_lshl_add_u64 v[230:231], v[118:119], 0, v[18:19]
	v_add_f32_e32 v173, 1.0, v173
	v_rcp_f32_e32 v179, v173
	v_lshl_add_u64 v[120:121], v[118:119], 0, v[34:35]
	v_lshl_add_u64 v[50:51], v[50:51], 0, v[198:199]
	global_load_dwordx4 v[22:25], v[230:231], off offset:16
	global_load_dwordx4 v[18:21], v[230:231], off
	global_load_dwordx4 v[30:33], v[230:231], off offset:528
	global_load_dwordx4 v[26:29], v[230:231], off offset:512
	global_load_dwordx4 v[38:41], v[120:121], off offset:16
	global_load_dwordx4 v[34:37], v[120:121], off
	global_load_dwordx4 v[46:49], v[120:121], off offset:528
	global_load_dwordx4 v[42:45], v[120:121], off offset:512
	global_load_dwordx4 v[58:61], v[50:51], off
	s_nop 0
	global_load_dwordx4 v[50:53], v[50:51], off offset:256
	v_lshl_add_u64 v[88:89], v[88:89], 1, s[54:55]
	v_mul_f32_e32 v173, 0xbfb8aa3b, v226
	v_exp_f32_e32 v173, v173
	v_mul_f32_e32 v176, 0xbfb8aa3b, v176
	v_mul_f32_e32 v177, 0xbfb8aa3b, v177
	v_exp_f32_e32 v176, v176
	v_add_f32_e32 v173, 1.0, v173
	v_rcp_f32_e32 v226, v173
	v_mul_f32_e32 v173, 0xbfb8aa3b, v227
	v_exp_f32_e32 v173, v173
	v_exp_f32_e32 v177, v177
	v_add_f32_e32 v176, 1.0, v176
	v_rcp_f32_e32 v176, v176
	v_add_f32_e32 v173, 1.0, v173
	v_rcp_f32_e32 v227, v173
	v_add_f32_e32 v177, 1.0, v177
	v_rcp_f32_e32 v177, v177
	v_cmp_eq_u32_e32 vcc, 0, v185
	s_waitcnt vmcnt(11)
	v_lshlrev_b32_e32 v186, 16, v74
	v_and_b32_e32 v187, 0xffff0000, v74
	v_mul_f32_e32 v74, 0xbfb8aa3b, v252
	v_exp_f32_e32 v74, v74
	v_pk_fma_f32 v[78:79], v[178:179], v[186:187], v[78:79]
	v_add_f32_e32 v74, 1.0, v74
	v_rcp_f32_e32 v178, v74
	v_mul_f32_e32 v74, 0xbfb8aa3b, v253
	v_exp_f32_e32 v74, v74
	s_nop 0
	v_add_f32_e32 v74, 1.0, v74
	v_rcp_f32_e32 v179, v74
	v_lshlrev_b32_e32 v74, 16, v75
	v_and_b32_e32 v75, 0xffff0000, v75
	v_pk_fma_f32 v[80:81], v[178:179], v[74:75], v[80:81]
	v_mul_f32_e32 v74, 0xbfb8aa3b, v250
	v_mul_f32_e32 v75, 0xbfb8aa3b, v251
	v_exp_f32_e32 v74, v74
	v_exp_f32_e32 v75, v75
	v_lshlrev_b32_e32 v178, 16, v76
	v_and_b32_e32 v179, 0xffff0000, v76
	v_add_f32_e32 v74, 1.0, v74
	v_add_f32_e32 v75, 1.0, v75
	v_rcp_f32_e32 v74, v74
	v_rcp_f32_e32 v75, v75
	v_lshlrev_b32_e32 v76, 16, v77
	v_and_b32_e32 v77, 0xffff0000, v77
	v_pk_fma_f32 v[66:67], v[74:75], v[178:179], v[66:67]
	v_mul_f32_e32 v74, 0xbfb8aa3b, v248
	v_mul_f32_e32 v75, 0xbfb8aa3b, v249
	v_exp_f32_e32 v74, v74
	v_exp_f32_e32 v75, v75
	v_mul_f32_e32 v179, 0xbfb8aa3b, v220
	v_exp_f32_e32 v179, v179
	v_add_f32_e32 v74, 1.0, v74
	v_add_f32_e32 v75, 1.0, v75
	v_rcp_f32_e32 v74, v74
	v_rcp_f32_e32 v75, v75
	v_add_f32_e32 v179, 1.0, v179
	v_rcp_f32_e32 v220, v179
	v_mul_f32_e32 v179, 0xbfb8aa3b, v221
	v_pk_fma_f32 v[68:69], v[74:75], v[76:77], v[68:69]
	v_cvt_pk_bf16_f32 v74, v78, v79
	v_cvt_pk_bf16_f32 v75, v80, v81
	v_cvt_pk_bf16_f32 v76, v66, v67
	v_cvt_pk_bf16_f32 v77, v68, v69
	global_store_dwordx4 v[86:87], v[78:81], off nt
	global_store_dwordx4 v[86:87], v[66:69], off offset:16 nt
	global_store_dwordx4 v[88:89], v[74:77], off nt
	v_exp_f32_e32 v179, v179
	s_nop 0
	v_pk_mul_f32 v[74:75], v[78:79], v[78:79]
	v_pk_mul_f32 v[78:79], v[66:67], v[66:67]
	v_mul_f32_e32 v66, 0xbfb8aa3b, v246
	v_mul_f32_e32 v67, 0xbfb8aa3b, v247
	v_exp_f32_e32 v66, v66
	v_exp_f32_e32 v67, v67
	v_pk_mul_f32 v[76:77], v[80:81], v[80:81]
	v_pk_mul_f32 v[80:81], v[68:69], v[68:69]
	v_add_f32_e32 v66, 1.0, v66
	v_add_f32_e32 v67, 1.0, v67
	v_rcp_f32_e32 v66, v66
	v_rcp_f32_e32 v67, v67
	s_waitcnt vmcnt(13)
	v_lshlrev_b32_e32 v68, 16, v70
	v_and_b32_e32 v69, 0xffff0000, v70
	v_add_f32_e32 v179, 1.0, v179
	v_pk_fma_f32 v[62:63], v[66:67], v[68:69], v[62:63]
	v_mul_f32_e32 v66, 0xbfb8aa3b, v244
	v_mul_f32_e32 v67, 0xbfb8aa3b, v245
	v_exp_f32_e32 v66, v66
	v_exp_f32_e32 v67, v67
	v_lshlrev_b32_e32 v68, 16, v71
	v_and_b32_e32 v69, 0xffff0000, v71
	v_add_f32_e32 v66, 1.0, v66
	v_add_f32_e32 v67, 1.0, v67
	v_rcp_f32_e32 v66, v66
	v_rcp_f32_e32 v67, v67
	v_rcp_f32_e32 v221, v179
	v_mul_f32_e32 v179, 0xbfb8aa3b, v204
	v_exp_f32_e32 v179, v179
	v_pk_fma_f32 v[64:65], v[66:67], v[68:69], v[64:65]
	v_mul_f32_e32 v66, 0xbfb8aa3b, v240
	v_mul_f32_e32 v67, 0xbfb8aa3b, v241
	v_exp_f32_e32 v66, v66
	v_exp_f32_e32 v67, v67
	v_lshlrev_b32_e32 v68, 16, v72
	v_and_b32_e32 v69, 0xffff0000, v72
	v_add_f32_e32 v66, 1.0, v66
	v_add_f32_e32 v67, 1.0, v67
	v_rcp_f32_e32 v66, v66
	v_rcp_f32_e32 v67, v67
	v_add_f32_e32 v179, 1.0, v179
	v_rcp_f32_e32 v204, v179
	v_mul_f32_e32 v179, 0xbfb8aa3b, v205
	v_pk_fma_f32 v[54:55], v[66:67], v[68:69], v[54:55]
	v_mul_f32_e32 v66, 0xbfb8aa3b, v238
	v_mul_f32_e32 v67, 0xbfb8aa3b, v239
	v_exp_f32_e32 v66, v66
	v_exp_f32_e32 v67, v67
	v_lshlrev_b32_e32 v68, 16, v73
	v_and_b32_e32 v69, 0xffff0000, v73
	v_add_f32_e32 v66, 1.0, v66
	v_add_f32_e32 v67, 1.0, v67
	v_rcp_f32_e32 v66, v66
	v_rcp_f32_e32 v67, v67
	v_exp_f32_e32 v179, v179
	v_pk_fma_f32 v[56:57], v[66:67], v[68:69], v[56:57]
	global_store_dwordx4 v[86:87], v[62:65], off offset:512 nt
	global_store_dwordx4 v[86:87], v[54:57], off offset:528 nt
	v_cvt_pk_bf16_f32 v68, v54, v55
	v_cvt_pk_bf16_f32 v69, v56, v57
	v_pk_mul_f32 v[54:55], v[54:55], v[54:55]
	v_pk_mul_f32 v[56:57], v[56:57], v[56:57]
	v_cvt_pk_bf16_f32 v66, v62, v63
	v_cvt_pk_bf16_f32 v67, v64, v65
	v_pk_mul_f32 v[62:63], v[62:63], v[62:63]
	v_pk_mul_f32 v[64:65], v[64:65], v[64:65]
	v_add_f32_e32 v56, v56, v57
	v_add_f32_e32 v54, v54, v55
	v_add_f32_e32 v54, v54, v56
	v_add_f32_e32 v55, v64, v65
	v_add_f32_e32 v56, v62, v63
	v_add_f32_e32 v55, v56, v55
	v_add_f32_e32 v54, v55, v54
	v_add_f32_e32 v55, v80, v81
	v_add_f32_e32 v56, v78, v79
	v_add_f32_e32 v55, v56, v55
	v_add_f32_e32 v56, v76, v77
	v_add_f32_e32 v57, v74, v75
	v_add_f32_e32 v56, v57, v56
	v_add_f32_e32 v55, v56, v55
	v_add_f32_e32 v178, v55, v54
	v_lshlrev_b64 v[54:55], 11, v[84:85]
	global_store_dwordx4 v[88:89], v[66:69], off offset:256 nt
	s_waitcnt vmcnt(7)
; __device__ __forceinline__ float sigmoidf_(float x) { return __builtin_amdgcn_rcpf(1.0f + __expf(-x)); }
; __device__ __forceinline__ float ssq4(const f32x4 o) { return (o[0] * o[0] + o[1] * o[1]) + (o[2] * o[2] + o[3] * o[3]); }
;     __device__ __forceinline__ void operator()(f32x4 (&acc)[2][2][4][2], const Unit& u, int wr, int wc, int fr, int fq) const {
;     ...
;         for (int k = 0; k < 4; ++k) {
;             if (k < 3) {
; #pragma unroll
;                 for (int q = 0; q < 2; ++q)
; #pragma unroll
;                     for (int c = 0; c < 4; ++c) nxt[q][c] = *(const f32x4*)(h + (size_t)EPI_ROW(2 * k + 2 + q) * D + col0 + (c >> 1) * HALF + (c & 1) * 4);
;             }
; #pragma unroll
;             for (int q = 0; q < 2; ++q) { const int r = 2 * k + q, ai = r >> 2, m = r & 3; const size_t off = (size_t)EPI_ROW(r) * D + col0; float sr = 0.f;
;                 if (r < 7) {
; #pragma unroll
;                     for (int c = 0; c < 4; ++c) pnxt[c] = *(const u32x2*)(pp + (size_t)EPI_ROW(r + 1) * D + col0 + (c >> 1) * HALF + (c & 1) * 4);
;                 }
;                 asm volatile("" ::: "memory");
; #pragma unroll
;                 for (int bj = 0; bj < 2; ++bj) { f32x4 o2[2];
; #pragma unroll
;                     for (int n = 0; n < 2; ++n) { const f32x4 b = cur[q][2 * bj + n]; const u32x2 qw = pcur[2 * bj + n];
;                         const f32x4 pq = (f32x4){bflo(qw.x), bfhi(qw.x), bflo(qw.y), bfhi(qw.y)}; const f32x4 a = acc[ai][bj][m][n];
; #pragma unroll
;                         for (int j = 0; j < 4; ++j) o2[n][j] = b[j] + pq[j] * sigmoidf_(a[j]); }
;                     *(f32x4*)(h + off + bj * HALF) = o2[0]; *(f32x4*)(h + off + bj * HALF + 4) = o2[1];
;                     if (!LAST) { u32x4 w; w.x = cvt_pk_bf16(o2[0][0], o2[0][1]); w.y = cvt_pk_bf16(o2[0][2], o2[0][3]); w.z = cvt_pk_bf16(o2[1][0], o2[1][1]); w.w = cvt_pk_bf16(o2[1][2], o2[1][3]);
;                         *(u32x4*)(hb + off + bj * HALF) = w; sr += ssq4(o2[0]) + ssq4(o2[1]); } }
	v_lshlrev_b32_e32 v56, 16, v58
	v_and_b32_e32 v57, 0xffff0000, v58
	v_lshl_add_u64 v[66:67], v[54:55], 0, v[152:153]
	v_lshlrev_b64 v[54:55], 12, v[242:243]
	v_lshl_add_u64 v[54:55], s[56:57], 0, v[54:55]
	v_lshl_add_u64 v[54:55], v[54:55], 0, v[198:199]
	global_load_dwordx4 v[86:89], v[54:55], off
	global_load_dwordx4 v[62:65], v[54:55], off offset:256
	v_mul_f32_e32 v54, 0xbfb8aa3b, v236
	v_mul_f32_e32 v55, 0xbfb8aa3b, v237
	v_exp_f32_e32 v54, v54
	v_exp_f32_e32 v55, v55
	v_add_u32_e32 v236, 0x80, v172
	v_add_f32_e32 v54, 1.0, v54
	v_add_f32_e32 v55, 1.0, v55
	v_rcp_f32_e32 v54, v54
	v_rcp_f32_e32 v55, v55
	v_lshlrev_b64 v[74:75], 11, v[242:243]
	v_ashrrev_i32_e32 v237, 31, v236
	v_lshl_add_u64 v[186:187], v[74:75], 0, v[152:153]
	v_pk_fma_f32 v[2:3], v[54:55], v[56:57], v[2:3]
	v_mul_f32_e32 v54, 0xbfb8aa3b, v234
	v_mul_f32_e32 v55, 0xbfb8aa3b, v235
	v_exp_f32_e32 v54, v54
	v_exp_f32_e32 v55, v55
	v_lshlrev_b32_e32 v56, 16, v59
	v_and_b32_e32 v57, 0xffff0000, v59
	v_add_f32_e32 v54, 1.0, v54
	v_add_f32_e32 v55, 1.0, v55
	v_rcp_f32_e32 v54, v54
	v_rcp_f32_e32 v55, v55
	v_lshl_add_u64 v[58:59], v[66:67], 1, s[54:55]
	v_lshlrev_b64 v[74:75], 12, v[228:229]
	v_lshl_add_u64 v[74:75], s[56:57], 0, v[74:75]
	v_pk_fma_f32 v[4:5], v[54:55], v[56:57], v[4:5]
	v_mul_f32_e32 v54, 0xbfb8aa3b, v232
	v_mul_f32_e32 v55, 0xbfb8aa3b, v233
	v_exp_f32_e32 v54, v54
	v_exp_f32_e32 v55, v55
	v_lshlrev_b32_e32 v56, 16, v60
	v_and_b32_e32 v57, 0xffff0000, v60
	v_add_f32_e32 v54, 1.0, v54
	v_add_f32_e32 v55, 1.0, v55
	v_rcp_f32_e32 v54, v54
	v_rcp_f32_e32 v55, v55
	v_add_u32_e32 v232, 0x90, v172
	v_ashrrev_i32_e32 v233, 31, v232
	v_lshl_add_u64 v[74:75], v[74:75], 0, v[198:199]
	v_pk_fma_f32 v[6:7], v[54:55], v[56:57], v[6:7]
	v_mul_f32_e32 v54, 0xbfb8aa3b, v222
	v_mul_f32_e32 v55, 0xbfb8aa3b, v223
	v_exp_f32_e32 v54, v54
	v_exp_f32_e32 v55, v55
	v_lshlrev_b32_e32 v56, 16, v61
	v_and_b32_e32 v57, 0xffff0000, v61
	v_add_f32_e32 v54, 1.0, v54
	v_add_f32_e32 v55, 1.0, v55
	v_rcp_f32_e32 v54, v54
	v_rcp_f32_e32 v55, v55
	v_add_f32_e32 v179, 1.0, v179
	v_rcp_f32_e32 v205, v179
	v_pk_fma_f32 v[8:9], v[54:55], v[56:57], v[8:9]
	v_cvt_pk_bf16_f32 v54, v2, v3
	v_cvt_pk_bf16_f32 v55, v4, v5
	v_cvt_pk_bf16_f32 v56, v6, v7
	v_cvt_pk_bf16_f32 v57, v8, v9
	global_store_dwordx4 v[82:83], v[2:5], off nt
	global_store_dwordx4 v[82:83], v[6:9], off offset:16 nt
	global_store_dwordx4 v[58:59], v[54:57], off nt
	s_waitcnt vmcnt(4)
	v_lshlrev_b32_e32 v238, 16, v86
	v_mul_f32_e32 v54, 0xbfb8aa3b, v94
	v_mul_f32_e32 v55, 0xbfb8aa3b, v95
	v_exp_f32_e32 v54, v54
	v_exp_f32_e32 v55, v55
	v_lshlrev_b32_e32 v56, 16, v50
	v_and_b32_e32 v57, 0xffff0000, v50
	v_mul_f32_e32 v50, 0xbfb8aa3b, v96
	v_add_f32_e32 v54, 1.0, v54
	v_add_f32_e32 v55, 1.0, v55
	v_exp_f32_e32 v50, v50
	v_rcp_f32_e32 v54, v54
	v_rcp_f32_e32 v55, v55
	v_and_b32_e32 v239, 0xffff0000, v86
	v_add_f32_e32 v50, 1.0, v50
	v_mul_f32_e32 v86, 0xbfb8aa3b, v224
	v_pk_fma_f32 v[10:11], v[54:55], v[56:57], v[10:11]
	v_rcp_f32_e32 v54, v50
	v_mul_f32_e32 v50, 0xbfb8aa3b, v97
	v_exp_f32_e32 v50, v50
	v_exp_f32_e32 v86, v86
	v_pk_fma_f32 v[18:19], v[226:227], v[238:239], v[18:19]
	v_add_f32_e32 v50, 1.0, v50
	v_rcp_f32_e32 v55, v50
	v_lshlrev_b32_e32 v50, 16, v51
	v_and_b32_e32 v51, 0xffff0000, v51
	v_add_f32_e32 v86, 1.0, v86
	v_pk_fma_f32 v[12:13], v[54:55], v[50:51], v[12:13]
	v_mul_f32_e32 v50, 0xbfb8aa3b, v90
	v_mul_f32_e32 v51, 0xbfb8aa3b, v91
	v_exp_f32_e32 v50, v50
	v_exp_f32_e32 v51, v51
	v_lshlrev_b32_e32 v54, 16, v52
	v_and_b32_e32 v55, 0xffff0000, v52
	v_add_f32_e32 v50, 1.0, v50
	v_add_f32_e32 v51, 1.0, v51
	v_rcp_f32_e32 v50, v50
	v_rcp_f32_e32 v51, v51
	v_rcp_f32_e32 v224, v86
	v_mul_f32_e32 v86, 0xbfb8aa3b, v225
	v_exp_f32_e32 v86, v86
	v_pk_fma_f32 v[14:15], v[50:51], v[54:55], v[14:15]
	v_mul_f32_e32 v50, 0xbfb8aa3b, v92
	v_mul_f32_e32 v51, 0xbfb8aa3b, v93
	v_exp_f32_e32 v50, v50
	v_exp_f32_e32 v51, v51
	v_lshlrev_b32_e32 v52, 16, v53
	v_and_b32_e32 v53, 0xffff0000, v53
	v_add_f32_e32 v50, 1.0, v50
	v_add_f32_e32 v51, 1.0, v51
	v_rcp_f32_e32 v50, v50
	v_rcp_f32_e32 v51, v51
	v_add_f32_e32 v86, 1.0, v86
	v_rcp_f32_e32 v225, v86
	v_lshlrev_b32_e32 v86, 16, v87
	v_pk_fma_f32 v[16:17], v[50:51], v[52:53], v[16:17]
	v_cvt_pk_bf16_f32 v50, v10, v11
	v_cvt_pk_bf16_f32 v51, v12, v13
	v_cvt_pk_bf16_f32 v52, v14, v15
	v_cvt_pk_bf16_f32 v53, v16, v17
	global_store_dwordx4 v[82:83], v[10:13], off offset:512 nt
	global_store_dwordx4 v[82:83], v[14:17], off offset:528 nt
	global_store_dwordx4 v[58:59], v[50:53], off offset:256 nt
	v_lshlrev_b64 v[58:59], 13, v[232:233]
	v_lshl_add_u64 v[222:223], v[118:119], 0, v[58:59]
	v_lshlrev_b64 v[50:51], 13, v[236:237]
	v_lshl_add_u64 v[234:235], v[118:119], 0, v[50:51]
	global_load_dwordx4 v[54:57], v[234:235], off offset:16
	global_load_dwordx4 v[50:53], v[234:235], off
	global_load_dwordx4 v[78:81], v[234:235], off offset:528
	global_load_dwordx4 v[66:69], v[234:235], off offset:512
	global_load_dwordx4 v[82:85], v[222:223], off offset:16
	global_load_dwordx4 v[90:93], v[222:223], off
	global_load_dwordx4 v[58:61], v[222:223], off offset:528
	global_load_dwordx4 v[70:73], v[222:223], off offset:512
	global_load_dwordx4 v[94:97], v[74:75], off
	s_nop 0
	global_load_dwordx4 v[74:77], v[74:75], off offset:256
	v_and_b32_e32 v87, 0xffff0000, v87
	v_pk_fma_f32 v[20:21], v[224:225], v[86:87], v[20:21]
	v_mul_f32_e32 v86, 0xbfb8aa3b, v128
	v_mul_f32_e32 v87, 0xbfb8aa3b, v129
	v_exp_f32_e32 v86, v86
	v_exp_f32_e32 v87, v87
	v_lshlrev_b32_e32 v128, 16, v88
	v_and_b32_e32 v129, 0xffff0000, v88
	v_add_f32_e32 v86, 1.0, v86
	v_add_f32_e32 v87, 1.0, v87
	v_rcp_f32_e32 v86, v86
	v_rcp_f32_e32 v87, v87
	v_lshlrev_b32_e32 v88, 16, v89
	v_and_b32_e32 v89, 0xffff0000, v89
	v_pk_fma_f32 v[22:23], v[86:87], v[128:129], v[22:23]
	v_mul_f32_e32 v86, 0xbfb8aa3b, v126
	v_mul_f32_e32 v87, 0xbfb8aa3b, v127
	v_exp_f32_e32 v86, v86
	v_exp_f32_e32 v87, v87
	v_lshl_add_u64 v[126:127], v[186:187], 1, s[54:55]
	v_add_u32_e32 v224, 0xb0, v172
	v_add_f32_e32 v86, 1.0, v86
	v_add_f32_e32 v87, 1.0, v87
	v_rcp_f32_e32 v86, v86
	v_rcp_f32_e32 v87, v87
	v_ashrrev_i32_e32 v225, 31, v224
	v_pk_fma_f32 v[24:25], v[86:87], v[88:89], v[24:25]
	v_cvt_pk_bf16_f32 v86, v18, v19
	v_cvt_pk_bf16_f32 v87, v20, v21
	v_cvt_pk_bf16_f32 v88, v22, v23
	v_cvt_pk_bf16_f32 v89, v24, v25
	global_store_dwordx4 v[230:231], v[18:21], off nt
	global_store_dwordx4 v[230:231], v[22:25], off offset:16 nt
	global_store_dwordx4 v[126:127], v[86:89], off nt
	s_nop 1
	v_mul_f32_e32 v86, 0xbfb8aa3b, v124
	v_mul_f32_e32 v87, 0xbfb8aa3b, v125
	v_exp_f32_e32 v86, v86
	v_exp_f32_e32 v87, v87
	s_waitcnt vmcnt(19)
; __device__ __forceinline__ float sigmoidf_(float x) { return __builtin_amdgcn_rcpf(1.0f + __expf(-x)); }
; __device__ __forceinline__ float ssq4(const f32x4 o) { return (o[0] * o[0] + o[1] * o[1]) + (o[2] * o[2] + o[3] * o[3]); }
;     __device__ __forceinline__ void operator()(f32x4 (&acc)[2][2][4][2], const Unit& u, int wr, int wc, int fr, int fq) const {
;     ...
;         for (int k = 0; k < 4; ++k) {
;             if (k < 3) {
; #pragma unroll
;                 for (int q = 0; q < 2; ++q)
; #pragma unroll
;                     for (int c = 0; c < 4; ++c) nxt[q][c] = *(const f32x4*)(h + (size_t)EPI_ROW(2 * k + 2 + q) * D + col0 + (c >> 1) * HALF + (c & 1) * 4);
;             }
; #pragma unroll
;             for (int q = 0; q < 2; ++q) { const int r = 2 * k + q, ai = r >> 2, m = r & 3; const size_t off = (size_t)EPI_ROW(r) * D + col0; float sr = 0.f;
;                 if (r < 7) {
; #pragma unroll
;                     for (int c = 0; c < 4; ++c) pnxt[c] = *(const u32x2*)(pp + (size_t)EPI_ROW(r + 1) * D + col0 + (c >> 1) * HALF + (c & 1) * 4);
;                 }
;                 asm volatile("" ::: "memory");
; #pragma unroll
;                 for (int bj = 0; bj < 2; ++bj) { f32x4 o2[2];
; #pragma unroll
;                     for (int n = 0; n < 2; ++n) { const f32x4 b = cur[q][2 * bj + n]; const u32x2 qw = pcur[2 * bj + n];
;                         const f32x4 pq = (f32x4){bflo(qw.x), bfhi(qw.x), bflo(qw.y), bfhi(qw.y)}; const f32x4 a = acc[ai][bj][m][n];
; #pragma unroll
;                         for (int j = 0; j < 4; ++j) o2[n][j] = b[j] + pq[j] * sigmoidf_(a[j]); }
;                     *(f32x4*)(h + off + bj * HALF) = o2[0]; *(f32x4*)(h + off + bj * HALF + 4) = o2[1];
;                     if (!LAST) { u32x4 w; w.x = cvt_pk_bf16(o2[0][0], o2[0][1]); w.y = cvt_pk_bf16(o2[0][2], o2[0][3]); w.z = cvt_pk_bf16(o2[1][0], o2[1][1]); w.w = cvt_pk_bf16(o2[1][2], o2[1][3]);
;                         *(u32x4*)(hb + off + bj * HALF) = w; sr += ssq4(o2[0]) + ssq4(o2[1]); } }
	v_lshlrev_b32_e32 v88, 16, v62
	v_and_b32_e32 v89, 0xffff0000, v62
	v_mul_f32_e32 v62, 0xbfb8aa3b, v122
	v_add_f32_e32 v86, 1.0, v86
	v_add_f32_e32 v87, 1.0, v87
	v_exp_f32_e32 v62, v62
	v_rcp_f32_e32 v86, v86
	v_rcp_f32_e32 v87, v87
	v_add_f32_e32 v62, 1.0, v62
	v_pk_fma_f32 v[26:27], v[86:87], v[88:89], v[26:27]
	v_rcp_f32_e32 v86, v62
	v_mul_f32_e32 v62, 0xbfb8aa3b, v123
	v_exp_f32_e32 v62, v62
	s_nop 0
	v_add_f32_e32 v62, 1.0, v62
	v_rcp_f32_e32 v87, v62
	v_lshlrev_b32_e32 v62, 16, v63
	v_and_b32_e32 v63, 0xffff0000, v63
	v_pk_fma_f32 v[28:29], v[86:87], v[62:63], v[28:29]
	v_mul_f32_e32 v62, 0xbfb8aa3b, v116
	v_mul_f32_e32 v63, 0xbfb8aa3b, v117
	v_exp_f32_e32 v62, v62
	v_exp_f32_e32 v63, v63
	v_lshlrev_b32_e32 v86, 16, v64
	v_and_b32_e32 v87, 0xffff0000, v64
	v_add_f32_e32 v62, 1.0, v62
	v_add_f32_e32 v63, 1.0, v63
	v_rcp_f32_e32 v62, v62
	v_rcp_f32_e32 v63, v63
	v_lshlrev_b32_e32 v64, 16, v65
	v_and_b32_e32 v65, 0xffff0000, v65
	v_pk_fma_f32 v[30:31], v[62:63], v[86:87], v[30:31]
	v_mul_f32_e32 v62, 0xbfb8aa3b, v114
	v_mul_f32_e32 v63, 0xbfb8aa3b, v115
	v_exp_f32_e32 v62, v62
	v_exp_f32_e32 v63, v63
	v_add_f32_e32 v62, 1.0, v62
	v_add_f32_e32 v63, 1.0, v63
	v_rcp_f32_e32 v62, v62
	v_rcp_f32_e32 v63, v63
	s_nop 0
	v_pk_fma_f32 v[32:33], v[62:63], v[64:65], v[32:33]
	v_cvt_pk_bf16_f32 v62, v26, v27
	v_cvt_pk_bf16_f32 v63, v28, v29
	v_cvt_pk_bf16_f32 v64, v30, v31
	v_cvt_pk_bf16_f32 v65, v32, v33
	global_store_dwordx4 v[230:231], v[26:29], off offset:512 nt
	global_store_dwordx4 v[230:231], v[30:33], off offset:528 nt
	global_store_dwordx4 v[126:127], v[62:65], off offset:256 nt
	s_nop 1
	v_lshlrev_b64 v[62:63], 11, v[228:229]
	v_lshl_add_u64 v[86:87], v[62:63], 0, v[152:153]
	v_lshlrev_b64 v[62:63], 12, v[236:237]
	v_lshl_add_u64 v[62:63], s[56:57], 0, v[62:63]
	v_lshl_add_u64 v[62:63], v[62:63], 0, v[198:199]
	global_load_dwordx4 v[122:125], v[62:63], off
	global_load_dwordx4 v[114:117], v[62:63], off offset:256
	v_mul_f32_e32 v62, 0xbfb8aa3b, v112
	v_mul_f32_e32 v63, 0xbfb8aa3b, v113
	v_exp_f32_e32 v62, v62
	v_exp_f32_e32 v63, v63
	s_waitcnt vmcnt(9)
	v_lshlrev_b32_e32 v64, 16, v94
	v_and_b32_e32 v65, 0xffff0000, v94
	v_add_f32_e32 v62, 1.0, v62
	v_add_f32_e32 v63, 1.0, v63
	v_rcp_f32_e32 v62, v62
	v_rcp_f32_e32 v63, v63
	v_lshl_add_u64 v[86:87], v[86:87], 1, s[54:55]
	v_add_u32_e32 v228, 0xa0, v172
	v_pk_fma_f32 v[34:35], v[62:63], v[64:65], v[34:35]
	v_mul_f32_e32 v62, 0xbfb8aa3b, v110
	v_mul_f32_e32 v63, 0xbfb8aa3b, v111
	v_exp_f32_e32 v62, v62
	v_exp_f32_e32 v63, v63
	v_lshlrev_b32_e32 v64, 16, v95
	v_and_b32_e32 v65, 0xffff0000, v95
	v_add_f32_e32 v62, 1.0, v62
	v_add_f32_e32 v63, 1.0, v63
	v_rcp_f32_e32 v62, v62
	v_rcp_f32_e32 v63, v63
	v_ashrrev_i32_e32 v229, 31, v228
	v_pk_fma_f32 v[36:37], v[62:63], v[64:65], v[36:37]
	v_mul_f32_e32 v62, 0xbfb8aa3b, v108
	v_mul_f32_e32 v63, 0xbfb8aa3b, v109
	v_exp_f32_e32 v62, v62
	v_exp_f32_e32 v63, v63
	v_lshlrev_b32_e32 v64, 16, v96
	v_and_b32_e32 v65, 0xffff0000, v96
	v_add_f32_e32 v62, 1.0, v62
	v_add_f32_e32 v63, 1.0, v63
	v_rcp_f32_e32 v62, v62
	v_rcp_f32_e32 v63, v63
	s_waitcnt vmcnt(1)
	v_lshlrev_b32_e32 v230, 16, v122
	v_pk_fma_f32 v[38:39], v[62:63], v[64:65], v[38:39]
	v_mul_f32_e32 v62, 0xbfb8aa3b, v106
	v_mul_f32_e32 v63, 0xbfb8aa3b, v107
	v_exp_f32_e32 v62, v62
	v_exp_f32_e32 v63, v63
	v_lshlrev_b32_e32 v64, 16, v97
	v_and_b32_e32 v65, 0xffff0000, v97
	v_add_f32_e32 v62, 1.0, v62
	v_add_f32_e32 v63, 1.0, v63
	v_rcp_f32_e32 v62, v62
	v_rcp_f32_e32 v63, v63
	v_and_b32_e32 v231, 0xffff0000, v122
	v_mul_f32_e32 v122, 0xbfb8aa3b, v218
	v_exp_f32_e32 v122, v122
	v_pk_fma_f32 v[40:41], v[62:63], v[64:65], v[40:41]
	v_cvt_pk_bf16_f32 v62, v34, v35
	v_cvt_pk_bf16_f32 v63, v36, v37
	v_cvt_pk_bf16_f32 v64, v38, v39
	v_cvt_pk_bf16_f32 v65, v40, v41
	global_store_dwordx4 v[120:121], v[34:37], off nt
	global_store_dwordx4 v[120:121], v[38:41], off offset:16 nt
	global_store_dwordx4 v[86:87], v[62:65], off nt
	v_add_f32_e32 v122, 1.0, v122
	v_rcp_f32_e32 v218, v122
	v_mul_f32_e32 v62, 0xbfb8aa3b, v104
	v_mul_f32_e32 v63, 0xbfb8aa3b, v105
	v_exp_f32_e32 v62, v62
	v_exp_f32_e32 v63, v63
	v_lshlrev_b32_e32 v64, 16, v74
	v_and_b32_e32 v65, 0xffff0000, v74
	v_add_f32_e32 v62, 1.0, v62
	v_add_f32_e32 v63, 1.0, v63
	v_rcp_f32_e32 v62, v62
	v_rcp_f32_e32 v63, v63
	v_mul_f32_e32 v122, 0xbfb8aa3b, v219
	v_exp_f32_e32 v122, v122
	v_pk_fma_f32 v[50:51], v[220:221], v[230:231], v[50:51]
	v_pk_fma_f32 v[42:43], v[62:63], v[64:65], v[42:43]
	v_mul_f32_e32 v62, 0xbfb8aa3b, v102
	v_mul_f32_e32 v63, 0xbfb8aa3b, v103
	v_exp_f32_e32 v62, v62
	v_exp_f32_e32 v63, v63
	v_lshlrev_b32_e32 v64, 16, v75
	v_and_b32_e32 v65, 0xffff0000, v75
	v_add_f32_e32 v62, 1.0, v62
	v_add_f32_e32 v63, 1.0, v63
	v_rcp_f32_e32 v62, v62
	v_rcp_f32_e32 v63, v63
	v_add_f32_e32 v122, 1.0, v122
	v_rcp_f32_e32 v219, v122
	v_lshlrev_b32_e32 v122, 16, v123
	v_pk_fma_f32 v[44:45], v[62:63], v[64:65], v[44:45]
	v_mul_f32_e32 v62, 0xbfb8aa3b, v100
	v_mul_f32_e32 v63, 0xbfb8aa3b, v101
	v_exp_f32_e32 v62, v62
	v_exp_f32_e32 v63, v63
	v_lshlrev_b32_e32 v64, 16, v76
	v_and_b32_e32 v65, 0xffff0000, v76
	v_add_f32_e32 v62, 1.0, v62
	v_add_f32_e32 v63, 1.0, v63
	v_rcp_f32_e32 v62, v62
	v_rcp_f32_e32 v63, v63
	v_and_b32_e32 v123, 0xffff0000, v123
	v_pk_fma_f32 v[52:53], v[218:219], v[122:123], v[52:53]
	v_mul_f32_e32 v122, 0xbfb8aa3b, v216
	v_pk_fma_f32 v[46:47], v[62:63], v[64:65], v[46:47]
	v_mul_f32_e32 v62, 0xbfb8aa3b, v98
	v_mul_f32_e32 v63, 0xbfb8aa3b, v99
	v_exp_f32_e32 v62, v62
	v_exp_f32_e32 v63, v63
	v_lshlrev_b32_e32 v64, 16, v77
	v_and_b32_e32 v65, 0xffff0000, v77
	v_add_f32_e32 v62, 1.0, v62
	v_add_f32_e32 v63, 1.0, v63
	v_rcp_f32_e32 v62, v62
; __device__ __forceinline__ float sigmoidf_(float x) { return __builtin_amdgcn_rcpf(1.0f + __expf(-x)); }
; __device__ __forceinline__ float ssq4(const f32x4 o) { return (o[0] * o[0] + o[1] * o[1]) + (o[2] * o[2] + o[3] * o[3]); }
;     __device__ __forceinline__ void operator()(f32x4 (&acc)[2][2][4][2], const Unit& u, int wr, int wc, int fr, int fq) const {
;     ...
;         for (int k = 0; k < 4; ++k) {
;             if (k < 3) {
; #pragma unroll
;                 for (int q = 0; q < 2; ++q)
; #pragma unroll
;                     for (int c = 0; c < 4; ++c) nxt[q][c] = *(const f32x4*)(h + (size_t)EPI_ROW(2 * k + 2 + q) * D + col0 + (c >> 1) * HALF + (c & 1) * 4);
;             }
; #pragma unroll
;             for (int q = 0; q < 2; ++q) { const int r = 2 * k + q, ai = r >> 2, m = r & 3; const size_t off = (size_t)EPI_ROW(r) * D + col0; float sr = 0.f;
;                 if (r < 7) {
; #pragma unroll
;                     for (int c = 0; c < 4; ++c) pnxt[c] = *(const u32x2*)(pp + (size_t)EPI_ROW(r + 1) * D + col0 + (c >> 1) * HALF + (c & 1) * 4);
;                 }
;                 asm volatile("" ::: "memory");
; #pragma unroll
;                 for (int bj = 0; bj < 2; ++bj) { f32x4 o2[2];
; #pragma unroll
;                     for (int n = 0; n < 2; ++n) { const f32x4 b = cur[q][2 * bj + n]; const u32x2 qw = pcur[2 * bj + n];
;                         const f32x4 pq = (f32x4){bflo(qw.x), bfhi(qw.x), bflo(qw.y), bfhi(qw.y)}; const f32x4 a = acc[ai][bj][m][n];
; #pragma unroll
;                         for (int j = 0; j < 4; ++j) o2[n][j] = b[j] + pq[j] * sigmoidf_(a[j]); }
;                     *(f32x4*)(h + off + bj * HALF) = o2[0]; *(f32x4*)(h + off + bj * HALF + 4) = o2[1];
;                     if (!LAST) { u32x4 w; w.x = cvt_pk_bf16(o2[0][0], o2[0][1]); w.y = cvt_pk_bf16(o2[0][2], o2[0][3]); w.z = cvt_pk_bf16(o2[1][0], o2[1][1]); w.w = cvt_pk_bf16(o2[1][2], o2[1][3]);
;                         *(u32x4*)(hb + off + bj * HALF) = w; sr += ssq4(o2[0]) + ssq4(o2[1]); } }
	v_rcp_f32_e32 v63, v63
	v_mul_f32_e32 v123, 0xbfb8aa3b, v217
	v_exp_f32_e32 v122, v122
	v_exp_f32_e32 v123, v123
	v_pk_fma_f32 v[48:49], v[62:63], v[64:65], v[48:49]
	v_cvt_pk_bf16_f32 v62, v42, v43
	v_cvt_pk_bf16_f32 v63, v44, v45
	v_cvt_pk_bf16_f32 v64, v46, v47
	v_cvt_pk_bf16_f32 v65, v48, v49
	global_store_dwordx4 v[120:121], v[42:45], off offset:512 nt
	global_store_dwordx4 v[120:121], v[46:49], off offset:528 nt
	global_store_dwordx4 v[86:87], v[62:65], off offset:256 nt
	v_add_f32_e32 v122, 1.0, v122
	v_add_f32_e32 v123, 1.0, v123
	v_lshlrev_b64 v[62:63], 13, v[228:229]
	v_lshl_add_u64 v[226:227], v[118:119], 0, v[62:63]
	v_lshlrev_b64 v[62:63], 13, v[224:225]
	v_lshl_add_u64 v[172:173], v[118:119], 0, v[62:63]
	v_lshlrev_b64 v[118:119], 11, v[236:237]
	v_lshl_add_u64 v[186:187], v[118:119], 0, v[152:153]
	v_lshlrev_b64 v[118:119], 12, v[232:233]
	v_lshl_add_u64 v[118:119], s[56:57], 0, v[118:119]
	v_lshl_add_u64 v[118:119], v[118:119], 0, v[198:199]
	global_load_dwordx4 v[110:113], v[226:227], off offset:16
	global_load_dwordx4 v[106:109], v[226:227], off
	global_load_dwordx4 v[98:101], v[226:227], off offset:528
	global_load_dwordx4 v[102:105], v[226:227], off offset:512
	global_load_dwordx4 v[86:89], v[172:173], off offset:16
	global_load_dwordx4 v[94:97], v[172:173], off
	global_load_dwordx4 v[62:65], v[172:173], off offset:528
	global_load_dwordx4 v[74:77], v[172:173], off offset:512
	global_load_dwordx4 v[126:129], v[118:119], off
	s_nop 0
	global_load_dwordx4 v[118:121], v[118:119], off offset:256
	v_rcp_f32_e32 v122, v122
	v_rcp_f32_e32 v123, v123
	v_lshlrev_b32_e32 v216, 16, v124
	v_and_b32_e32 v217, 0xffff0000, v124
	v_lshlrev_b32_e32 v124, 16, v125
	v_pk_fma_f32 v[54:55], v[122:123], v[216:217], v[54:55]
	v_mul_f32_e32 v122, 0xbfb8aa3b, v214
	v_mul_f32_e32 v123, 0xbfb8aa3b, v215
	v_exp_f32_e32 v122, v122
	v_exp_f32_e32 v123, v123
	v_and_b32_e32 v125, 0xffff0000, v125
	v_lshl_add_u64 v[186:187], v[186:187], 1, s[54:55]
	v_add_f32_e32 v122, 1.0, v122
	v_add_f32_e32 v123, 1.0, v123
	v_rcp_f32_e32 v122, v122
	v_rcp_f32_e32 v123, v123
	s_nop 0
	v_pk_fma_f32 v[56:57], v[122:123], v[124:125], v[56:57]
	v_cvt_pk_bf16_f32 v122, v50, v51
	v_cvt_pk_bf16_f32 v123, v52, v53
	v_cvt_pk_bf16_f32 v124, v54, v55
	v_cvt_pk_bf16_f32 v125, v56, v57
	global_store_dwordx4 v[234:235], v[50:53], off nt
	global_store_dwordx4 v[234:235], v[54:57], off offset:16 nt
	global_store_dwordx4 v[186:187], v[122:125], off nt
	s_nop 1
	v_mul_f32_e32 v122, 0xbfb8aa3b, v212
	v_mul_f32_e32 v123, 0xbfb8aa3b, v213
	v_exp_f32_e32 v122, v122
	v_exp_f32_e32 v123, v123
	s_waitcnt vmcnt(19)
	v_lshlrev_b32_e32 v124, 16, v114
	v_and_b32_e32 v125, 0xffff0000, v114
	v_mul_f32_e32 v114, 0xbfb8aa3b, v210
	v_add_f32_e32 v122, 1.0, v122
	v_add_f32_e32 v123, 1.0, v123
	v_exp_f32_e32 v114, v114
	v_rcp_f32_e32 v122, v122
	v_rcp_f32_e32 v123, v123
	v_add_f32_e32 v114, 1.0, v114
	v_pk_fma_f32 v[66:67], v[122:123], v[124:125], v[66:67]
	v_rcp_f32_e32 v122, v114
	v_mul_f32_e32 v114, 0xbfb8aa3b, v211
	v_exp_f32_e32 v114, v114
	s_nop 0
	v_add_f32_e32 v114, 1.0, v114
	v_rcp_f32_e32 v123, v114
	v_lshlrev_b32_e32 v114, 16, v115
	v_and_b32_e32 v115, 0xffff0000, v115
	v_pk_fma_f32 v[68:69], v[122:123], v[114:115], v[68:69]
	v_mul_f32_e32 v114, 0xbfb8aa3b, v208
	v_mul_f32_e32 v115, 0xbfb8aa3b, v209
	v_exp_f32_e32 v114, v114
	v_exp_f32_e32 v115, v115
	v_lshlrev_b32_e32 v122, 16, v116
	v_and_b32_e32 v123, 0xffff0000, v116
	v_add_f32_e32 v114, 1.0, v114
	v_add_f32_e32 v115, 1.0, v115
	v_rcp_f32_e32 v114, v114
	v_rcp_f32_e32 v115, v115
	v_lshlrev_b32_e32 v116, 16, v117
	v_and_b32_e32 v117, 0xffff0000, v117
	v_pk_fma_f32 v[78:79], v[114:115], v[122:123], v[78:79]
	v_mul_f32_e32 v114, 0xbfb8aa3b, v206
	v_mul_f32_e32 v115, 0xbfb8aa3b, v207
	v_exp_f32_e32 v114, v114
	v_exp_f32_e32 v115, v115
	v_add_f32_e32 v114, 1.0, v114
	v_add_f32_e32 v115, 1.0, v115
	v_rcp_f32_e32 v114, v114
	v_rcp_f32_e32 v115, v115
	s_waitcnt vmcnt(4)
	v_lshlrev_b32_e32 v206, 16, v126
	v_and_b32_e32 v207, 0xffff0000, v126
	v_mul_f32_e32 v126, 0xbfb8aa3b, v202
	v_pk_fma_f32 v[80:81], v[114:115], v[116:117], v[80:81]
	v_cvt_pk_bf16_f32 v114, v66, v67
	v_cvt_pk_bf16_f32 v115, v68, v69
	v_cvt_pk_bf16_f32 v116, v78, v79
	v_cvt_pk_bf16_f32 v117, v80, v81
	global_store_dwordx4 v[234:235], v[66:69], off offset:512 nt
	global_store_dwordx4 v[234:235], v[78:81], off offset:528 nt
	global_store_dwordx4 v[186:187], v[114:117], off offset:256 nt
	v_exp_f32_e32 v126, v126
	v_pk_fma_f32 v[90:91], v[204:205], v[206:207], v[90:91]
	v_lshlrev_b64 v[114:115], 11, v[232:233]
	v_lshl_add_u64 v[186:187], v[114:115], 0, v[152:153]
	v_lshlrev_b64 v[114:115], 12, v[228:229]
	v_lshl_add_u64 v[114:115], s[56:57], 0, v[114:115]
	v_lshl_add_u64 v[114:115], v[114:115], 0, v[198:199]
	global_load_dwordx4 v[122:125], v[114:115], off
	s_nop 0
	global_load_dwordx4 v[114:117], v[114:115], off offset:256
	v_add_f32_e32 v126, 1.0, v126
	v_rcp_f32_e32 v202, v126
	v_mul_f32_e32 v126, 0xbfb8aa3b, v203
	v_exp_f32_e32 v126, v126
	v_lshl_add_u64 v[186:187], v[186:187], 1, s[54:55]
	v_add_f32_e32 v126, 1.0, v126
	v_rcp_f32_e32 v203, v126
	v_lshlrev_b32_e32 v126, 16, v127
	v_and_b32_e32 v127, 0xffff0000, v127
	v_pk_fma_f32 v[92:93], v[202:203], v[126:127], v[92:93]
	v_mul_f32_e32 v126, 0xbfb8aa3b, v200
	v_mul_f32_e32 v127, 0xbfb8aa3b, v201
	v_exp_f32_e32 v126, v126
	v_exp_f32_e32 v127, v127
	v_lshlrev_b32_e32 v200, 16, v128
	v_and_b32_e32 v201, 0xffff0000, v128
	v_add_f32_e32 v126, 1.0, v126
	v_add_f32_e32 v127, 1.0, v127
	v_rcp_f32_e32 v126, v126
	v_rcp_f32_e32 v127, v127
	v_lshlrev_b32_e32 v128, 16, v129
	v_and_b32_e32 v129, 0xffff0000, v129
	v_pk_fma_f32 v[82:83], v[126:127], v[200:201], v[82:83]
	v_mul_f32_e32 v126, 0xbfb8aa3b, v196
	v_mul_f32_e32 v127, 0xbfb8aa3b, v197
	v_exp_f32_e32 v126, v126
	v_exp_f32_e32 v127, v127
	v_add_f32_e32 v126, 1.0, v126
	v_add_f32_e32 v127, 1.0, v127
	v_rcp_f32_e32 v126, v126
	v_rcp_f32_e32 v127, v127
	s_nop 0
	v_pk_fma_f32 v[84:85], v[126:127], v[128:129], v[84:85]
	v_cvt_pk_bf16_f32 v126, v90, v91
	v_cvt_pk_bf16_f32 v127, v92, v93
	v_cvt_pk_bf16_f32 v128, v82, v83
	v_cvt_pk_bf16_f32 v129, v84, v85
	global_store_dwordx4 v[222:223], v[90:93], off nt
	global_store_dwordx4 v[222:223], v[82:85], off offset:16 nt
	global_store_dwordx4 v[186:187], v[126:129], off nt
	s_nop 1
	v_mul_f32_e32 v126, 0xbfb8aa3b, v194
	v_mul_f32_e32 v127, 0xbfb8aa3b, v195
	v_exp_f32_e32 v126, v126
	v_exp_f32_e32 v127, v127
	s_waitcnt vmcnt(11)
; __device__ __forceinline__ float sigmoidf_(float x) { return __builtin_amdgcn_rcpf(1.0f + __expf(-x)); }
; __device__ __forceinline__ float ssq4(const f32x4 o) { return (o[0] * o[0] + o[1] * o[1]) + (o[2] * o[2] + o[3] * o[3]); }
;     __device__ __forceinline__ void operator()(f32x4 (&acc)[2][2][4][2], const Unit& u, int wr, int wc, int fr, int fq) const {
;     ...
;         for (int k = 0; k < 4; ++k) {
;             if (k < 3) {
; #pragma unroll
;                 for (int q = 0; q < 2; ++q)
; #pragma unroll
;                     for (int c = 0; c < 4; ++c) nxt[q][c] = *(const f32x4*)(h + (size_t)EPI_ROW(2 * k + 2 + q) * D + col0 + (c >> 1) * HALF + (c & 1) * 4);
;             }
; #pragma unroll
;             for (int q = 0; q < 2; ++q) { const int r = 2 * k + q, ai = r >> 2, m = r & 3; const size_t off = (size_t)EPI_ROW(r) * D + col0; float sr = 0.f;
;                 if (r < 7) {
; #pragma unroll
;                     for (int c = 0; c < 4; ++c) pnxt[c] = *(const u32x2*)(pp + (size_t)EPI_ROW(r + 1) * D + col0 + (c >> 1) * HALF + (c & 1) * 4);
;                 }
;                 asm volatile("" ::: "memory");
; #pragma unroll
;                 for (int bj = 0; bj < 2; ++bj) { f32x4 o2[2];
; #pragma unroll
;                     for (int n = 0; n < 2; ++n) { const f32x4 b = cur[q][2 * bj + n]; const u32x2 qw = pcur[2 * bj + n];
;                         const f32x4 pq = (f32x4){bflo(qw.x), bfhi(qw.x), bflo(qw.y), bfhi(qw.y)}; const f32x4 a = acc[ai][bj][m][n];
; #pragma unroll
;                         for (int j = 0; j < 4; ++j) o2[n][j] = b[j] + pq[j] * sigmoidf_(a[j]); }
;                     *(f32x4*)(h + off + bj * HALF) = o2[0]; *(f32x4*)(h + off + bj * HALF + 4) = o2[1];
;                     if (!LAST) { u32x4 w; w.x = cvt_pk_bf16(o2[0][0], o2[0][1]); w.y = cvt_pk_bf16(o2[0][2], o2[0][3]); w.z = cvt_pk_bf16(o2[1][0], o2[1][1]); w.w = cvt_pk_bf16(o2[1][2], o2[1][3]);
;                         *(u32x4*)(hb + off + bj * HALF) = w; sr += ssq4(o2[0]) + ssq4(o2[1]); } }
	v_lshlrev_b32_e32 v128, 16, v118
	v_and_b32_e32 v129, 0xffff0000, v118
	v_mul_f32_e32 v118, 0xbfb8aa3b, v192
	v_add_f32_e32 v126, 1.0, v126
	v_add_f32_e32 v127, 1.0, v127
	v_exp_f32_e32 v118, v118
	v_rcp_f32_e32 v126, v126
	v_rcp_f32_e32 v127, v127
	v_add_f32_e32 v118, 1.0, v118
	v_pk_fma_f32 v[70:71], v[126:127], v[128:129], v[70:71]
	v_rcp_f32_e32 v126, v118
	v_mul_f32_e32 v118, 0xbfb8aa3b, v193
	v_exp_f32_e32 v118, v118
	s_nop 0
	v_add_f32_e32 v118, 1.0, v118
	v_rcp_f32_e32 v127, v118
	v_lshlrev_b32_e32 v118, 16, v119
	v_and_b32_e32 v119, 0xffff0000, v119
	v_pk_fma_f32 v[72:73], v[126:127], v[118:119], v[72:73]
	v_mul_f32_e32 v118, 0xbfb8aa3b, v190
	v_mul_f32_e32 v119, 0xbfb8aa3b, v191
	v_exp_f32_e32 v118, v118
	v_exp_f32_e32 v119, v119
	v_lshlrev_b32_e32 v126, 16, v120
	v_and_b32_e32 v127, 0xffff0000, v120
	v_add_f32_e32 v118, 1.0, v118
	v_add_f32_e32 v119, 1.0, v119
	v_rcp_f32_e32 v118, v118
	v_rcp_f32_e32 v119, v119
	v_lshlrev_b32_e32 v120, 16, v121
	v_and_b32_e32 v121, 0xffff0000, v121
	v_pk_fma_f32 v[58:59], v[118:119], v[126:127], v[58:59]
	v_mul_f32_e32 v118, 0xbfb8aa3b, v188
	v_mul_f32_e32 v119, 0xbfb8aa3b, v189
	v_exp_f32_e32 v118, v118
	v_exp_f32_e32 v119, v119
	s_waitcnt vmcnt(4)
	v_lshlrev_b32_e32 v188, 16, v122
	v_and_b32_e32 v189, 0xffff0000, v122
	v_add_f32_e32 v118, 1.0, v118
	v_add_f32_e32 v119, 1.0, v119
	v_mul_f32_e32 v122, 0xbfb8aa3b, v174
	v_rcp_f32_e32 v118, v118
	v_rcp_f32_e32 v119, v119
	v_exp_f32_e32 v122, v122
	v_pk_fma_f32 v[106:107], v[176:177], v[188:189], v[106:107]
	v_pk_fma_f32 v[60:61], v[118:119], v[120:121], v[60:61]
	v_add_f32_e32 v122, 1.0, v122
	v_cvt_pk_bf16_f32 v118, v70, v71
	v_cvt_pk_bf16_f32 v119, v72, v73
	v_cvt_pk_bf16_f32 v120, v58, v59
	v_cvt_pk_bf16_f32 v121, v60, v61
	v_rcp_f32_e32 v174, v122
	v_mul_f32_e32 v122, 0xbfb8aa3b, v175
	global_store_dwordx4 v[222:223], v[70:73], off offset:512 nt
	global_store_dwordx4 v[222:223], v[58:61], off offset:528 nt
	global_store_dwordx4 v[186:187], v[118:121], off offset:256 nt
	v_exp_f32_e32 v122, v122
	s_nop 0
	v_lshlrev_b64 v[118:119], 11, v[228:229]
	v_lshl_add_u64 v[186:187], v[118:119], 0, v[152:153]
	v_lshlrev_b64 v[118:119], 12, v[224:225]
	v_lshl_add_u64 v[118:119], s[56:57], 0, v[118:119]
	v_lshl_add_u64 v[118:119], v[118:119], 0, v[198:199]
	global_load_dwordx4 v[126:129], v[118:119], off
	s_nop 0
	global_load_dwordx4 v[118:121], v[118:119], off offset:256
	v_add_f32_e32 v122, 1.0, v122
	v_rcp_f32_e32 v175, v122
	v_lshlrev_b32_e32 v122, 16, v123
	v_and_b32_e32 v123, 0xffff0000, v123
	v_pk_fma_f32 v[108:109], v[174:175], v[122:123], v[108:109]
	v_mul_f32_e32 v122, 0xbfb8aa3b, v170
	v_mul_f32_e32 v123, 0xbfb8aa3b, v171
	v_exp_f32_e32 v122, v122
	v_exp_f32_e32 v123, v123
	v_lshlrev_b32_e32 v170, 16, v124
	v_and_b32_e32 v171, 0xffff0000, v124
	v_add_f32_e32 v122, 1.0, v122
	v_add_f32_e32 v123, 1.0, v123
	v_rcp_f32_e32 v122, v122
	v_rcp_f32_e32 v123, v123
	v_lshlrev_b32_e32 v124, 16, v125
	v_and_b32_e32 v125, 0xffff0000, v125
	v_pk_fma_f32 v[110:111], v[122:123], v[170:171], v[110:111]
	v_mul_f32_e32 v122, 0xbfb8aa3b, v168
	v_mul_f32_e32 v123, 0xbfb8aa3b, v169
	v_exp_f32_e32 v122, v122
	v_exp_f32_e32 v123, v123
	v_lshl_add_u64 v[168:169], v[186:187], 1, s[54:55]
	v_add_f32_e32 v122, 1.0, v122
	v_add_f32_e32 v123, 1.0, v123
	v_rcp_f32_e32 v122, v122
	v_rcp_f32_e32 v123, v123
	s_nop 0
	v_pk_fma_f32 v[112:113], v[122:123], v[124:125], v[112:113]
	v_cvt_pk_bf16_f32 v122, v106, v107
	v_cvt_pk_bf16_f32 v123, v108, v109
	v_cvt_pk_bf16_f32 v124, v110, v111
	v_cvt_pk_bf16_f32 v125, v112, v113
	global_store_dwordx4 v[226:227], v[106:109], off nt
	global_store_dwordx4 v[226:227], v[110:113], off offset:16 nt
	global_store_dwordx4 v[168:169], v[122:125], off nt
	s_nop 1
	v_mul_f32_e32 v122, 0xbfb8aa3b, v166
	v_mul_f32_e32 v123, 0xbfb8aa3b, v167
	v_exp_f32_e32 v122, v122
	v_exp_f32_e32 v123, v123
	s_waitcnt vmcnt(11)
	v_lshlrev_b32_e32 v124, 16, v114
	v_and_b32_e32 v125, 0xffff0000, v114
	v_mul_f32_e32 v114, 0xbfb8aa3b, v150
	v_add_f32_e32 v122, 1.0, v122
	v_add_f32_e32 v123, 1.0, v123
	v_exp_f32_e32 v114, v114
	v_rcp_f32_e32 v122, v122
	v_rcp_f32_e32 v123, v123
	v_add_f32_e32 v114, 1.0, v114
	v_pk_fma_f32 v[102:103], v[122:123], v[124:125], v[102:103]
	v_rcp_f32_e32 v122, v114
	v_mul_f32_e32 v114, 0xbfb8aa3b, v151
	v_exp_f32_e32 v114, v114
	s_nop 0
	v_add_f32_e32 v114, 1.0, v114
	v_rcp_f32_e32 v123, v114
	v_lshlrev_b32_e32 v114, 16, v115
	v_and_b32_e32 v115, 0xffff0000, v115
	v_pk_fma_f32 v[104:105], v[122:123], v[114:115], v[104:105]
	v_mul_f32_e32 v114, 0xbfb8aa3b, v148
	v_mul_f32_e32 v115, 0xbfb8aa3b, v149
	v_exp_f32_e32 v114, v114
	v_exp_f32_e32 v115, v115
	v_lshlrev_b32_e32 v122, 16, v116
	v_and_b32_e32 v123, 0xffff0000, v116
	v_add_f32_e32 v114, 1.0, v114
	v_add_f32_e32 v115, 1.0, v115
	v_rcp_f32_e32 v114, v114
	v_rcp_f32_e32 v115, v115
	v_lshlrev_b32_e32 v116, 16, v117
	v_and_b32_e32 v117, 0xffff0000, v117
	v_pk_fma_f32 v[98:99], v[114:115], v[122:123], v[98:99]
	v_mul_f32_e32 v114, 0xbfb8aa3b, v146
	v_mul_f32_e32 v115, 0xbfb8aa3b, v147
	v_exp_f32_e32 v114, v114
	v_exp_f32_e32 v115, v115
	v_add_f32_e32 v114, 1.0, v114
	v_add_f32_e32 v115, 1.0, v115
	v_rcp_f32_e32 v114, v114
	v_rcp_f32_e32 v115, v115
	s_nop 0
	v_pk_fma_f32 v[100:101], v[114:115], v[116:117], v[100:101]
	v_cvt_pk_bf16_f32 v114, v102, v103
	v_cvt_pk_bf16_f32 v115, v104, v105
	v_cvt_pk_bf16_f32 v116, v98, v99
	v_cvt_pk_bf16_f32 v117, v100, v101
	global_store_dwordx4 v[226:227], v[102:105], off offset:512 nt
	global_store_dwordx4 v[226:227], v[98:101], off offset:528 nt
	global_store_dwordx4 v[168:169], v[114:117], off offset:256 nt
	s_nop 1
	v_lshlrev_b64 v[114:115], 11, v[224:225]
	v_lshl_add_u64 v[122:123], v[114:115], 0, v[152:153]
	v_mul_f32_e32 v114, 0xbfb8aa3b, v144
	v_mul_f32_e32 v115, 0xbfb8aa3b, v145
	v_exp_f32_e32 v114, v114
	v_exp_f32_e32 v115, v115
	s_waitcnt vmcnt(7)
; #define LAS __attribute__((address_space(3)))
; __device__ __forceinline__ float sigmoidf_(float x) { return __builtin_amdgcn_rcpf(1.0f + __expf(-x)); }
; __device__ __forceinline__ float shx(float v, int o, int lane) { return __builtin_bit_cast(float, __builtin_amdgcn_ds_bpermute((lane ^ o) << 2, __builtin_bit_cast(int, v))); }
; template <bool SIXTEEN> __device__ __forceinline__ void tile_ssq(const float (&s)[2][4], const Unit& u, int wr, int wc, int fr, int fq, float* ssq, LAS float* ptab) {
;     const int lane = fq * 16 + fr;
; #pragma unroll
;     for (int ai = 0; ai < 2; ++ai)
; #pragma unroll
;         for (int m = 0; m < 4; ++m) { float v = s[ai][m]; v += shx(v, 16, lane); v += shx(v, 32, lane); if (fq == 0) ptab[(ai * HALF + wr * 64 + m * 16 + fr) * 4 + wc] = v; }
;     asm volatile("s_waitcnt lgkmcnt(0)" ::: "memory"); __builtin_amdgcn_s_barrier(); asm volatile("" ::: "memory");
;     __device__ __forceinline__ void operator()(f32x4 (&acc)[2][2][4][2], const Unit& u, int wr, int wc, int fr, int fq) const {
;     ...
;             for (int q = 0; q < 2; ++q) { const int r = 2 * k + q, ai = r >> 2, m = r & 3; const size_t off = (size_t)EPI_ROW(r) * D + col0; float sr = 0.f;
;                 if (r < 7) {
; #pragma unroll
;                     for (int c = 0; c < 4; ++c) pnxt[c] = *(const u32x2*)(pp + (size_t)EPI_ROW(r + 1) * D + col0 + (c >> 1) * HALF + (c & 1) * 4);
;                 }
;                 asm volatile("" ::: "memory");
; #pragma unroll
;                 for (int bj = 0; bj < 2; ++bj) { f32x4 o2[2];
; #pragma unroll
;                     for (int n = 0; n < 2; ++n) { const f32x4 b = cur[q][2 * bj + n]; const u32x2 qw = pcur[2 * bj + n];
;                         const f32x4 pq = (f32x4){bflo(qw.x), bfhi(qw.x), bflo(qw.y), bfhi(qw.y)}; const f32x4 a = acc[ai][bj][m][n];
; #pragma unroll
;                         for (int j = 0; j < 4; ++j) o2[n][j] = b[j] + pq[j] * sigmoidf_(a[j]); }
;                     *(f32x4*)(h + off + bj * HALF) = o2[0]; *(f32x4*)(h + off + bj * HALF + 4) = o2[1];
;                     if (!LAST) { u32x4 w; w.x = cvt_pk_bf16(o2[0][0], o2[0][1]); w.y = cvt_pk_bf16(o2[0][2], o2[0][3]); w.z = cvt_pk_bf16(o2[1][0], o2[1][1]); w.w = cvt_pk_bf16(o2[1][2], o2[1][3]);
;                         *(u32x4*)(hb + off + bj * HALF) = w; sr += ssq4(o2[0]) + ssq4(o2[1]); } }
	v_lshlrev_b32_e32 v116, 16, v126
	v_and_b32_e32 v117, 0xffff0000, v126
	v_add_f32_e32 v114, 1.0, v114
	v_add_f32_e32 v115, 1.0, v115
	v_rcp_f32_e32 v114, v114
	v_rcp_f32_e32 v115, v115
	v_lshl_add_u64 v[122:123], v[122:123], 1, s[54:55]
	v_pk_fma_f32 v[94:95], v[114:115], v[116:117], v[94:95]
	v_mul_f32_e32 v114, 0xbfb8aa3b, v142
	v_mul_f32_e32 v115, 0xbfb8aa3b, v143
	v_exp_f32_e32 v114, v114
	v_exp_f32_e32 v115, v115
	v_lshlrev_b32_e32 v116, 16, v127
	v_and_b32_e32 v117, 0xffff0000, v127
	v_add_f32_e32 v114, 1.0, v114
	v_add_f32_e32 v115, 1.0, v115
	v_rcp_f32_e32 v114, v114
	v_rcp_f32_e32 v115, v115
	s_nop 0
	v_pk_fma_f32 v[96:97], v[114:115], v[116:117], v[96:97]
	v_mul_f32_e32 v114, 0xbfb8aa3b, v140
	v_mul_f32_e32 v115, 0xbfb8aa3b, v141
	v_exp_f32_e32 v114, v114
	v_exp_f32_e32 v115, v115
	v_lshlrev_b32_e32 v116, 16, v128
	v_and_b32_e32 v117, 0xffff0000, v128
	v_add_f32_e32 v114, 1.0, v114
	v_add_f32_e32 v115, 1.0, v115
	v_rcp_f32_e32 v114, v114
	v_rcp_f32_e32 v115, v115
	s_nop 0
	v_pk_fma_f32 v[86:87], v[114:115], v[116:117], v[86:87]
	v_mul_f32_e32 v114, 0xbfb8aa3b, v138
	v_mul_f32_e32 v115, 0xbfb8aa3b, v139
	v_exp_f32_e32 v114, v114
	v_exp_f32_e32 v115, v115
	v_lshlrev_b32_e32 v116, 16, v129
	v_and_b32_e32 v117, 0xffff0000, v129
	v_add_f32_e32 v114, 1.0, v114
	v_add_f32_e32 v115, 1.0, v115
	v_rcp_f32_e32 v114, v114
	v_rcp_f32_e32 v115, v115
	s_nop 0
	v_pk_fma_f32 v[88:89], v[114:115], v[116:117], v[88:89]
	v_cvt_pk_bf16_f32 v114, v94, v95
	v_cvt_pk_bf16_f32 v115, v96, v97
	v_cvt_pk_bf16_f32 v116, v86, v87
	v_cvt_pk_bf16_f32 v117, v88, v89
	global_store_dwordx4 v[172:173], v[94:97], off nt
	global_store_dwordx4 v[172:173], v[86:89], off offset:16 nt
	global_store_dwordx4 v[122:123], v[114:117], off nt
	s_nop 1
	v_mul_f32_e32 v114, 0xbfb8aa3b, v136
	v_mul_f32_e32 v115, 0xbfb8aa3b, v137
	v_exp_f32_e32 v114, v114
	v_exp_f32_e32 v115, v115
	s_waitcnt vmcnt(9)
	v_lshlrev_b32_e32 v116, 16, v118
	v_and_b32_e32 v117, 0xffff0000, v118
	v_add_f32_e32 v114, 1.0, v114
	v_add_f32_e32 v115, 1.0, v115
	v_rcp_f32_e32 v114, v114
	v_rcp_f32_e32 v115, v115
	s_nop 0
	v_pk_fma_f32 v[74:75], v[114:115], v[116:117], v[74:75]
	v_mul_f32_e32 v114, 0xbfb8aa3b, v134
	v_mul_f32_e32 v115, 0xbfb8aa3b, v135
	v_exp_f32_e32 v114, v114
	v_exp_f32_e32 v115, v115
	v_lshlrev_b32_e32 v116, 16, v119
	v_and_b32_e32 v117, 0xffff0000, v119
	v_add_f32_e32 v114, 1.0, v114
	v_add_f32_e32 v115, 1.0, v115
	v_rcp_f32_e32 v114, v114
	v_rcp_f32_e32 v115, v115
	s_nop 0
	v_pk_fma_f32 v[76:77], v[114:115], v[116:117], v[76:77]
	v_mul_f32_e32 v114, 0xbfb8aa3b, v132
	v_mul_f32_e32 v115, 0xbfb8aa3b, v133
	v_exp_f32_e32 v114, v114
	v_exp_f32_e32 v115, v115
	v_lshlrev_b32_e32 v116, 16, v120
	v_and_b32_e32 v117, 0xffff0000, v120
	v_add_f32_e32 v114, 1.0, v114
	v_add_f32_e32 v115, 1.0, v115
	v_rcp_f32_e32 v114, v114
	v_rcp_f32_e32 v115, v115
	s_nop 0
	v_pk_fma_f32 v[62:63], v[114:115], v[116:117], v[62:63]
	v_mul_f32_e32 v114, 0xbfb8aa3b, v130
	v_mul_f32_e32 v115, 0xbfb8aa3b, v131
	v_exp_f32_e32 v114, v114
	v_exp_f32_e32 v115, v115
	v_lshlrev_b32_e32 v116, 16, v121
	v_and_b32_e32 v117, 0xffff0000, v121
	v_add_f32_e32 v114, 1.0, v114
	v_add_f32_e32 v115, 1.0, v115
	v_rcp_f32_e32 v114, v114
	v_rcp_f32_e32 v115, v115
	s_nop 0
	v_pk_fma_f32 v[64:65], v[114:115], v[116:117], v[64:65]
	v_cvt_pk_bf16_f32 v114, v74, v75
	v_cvt_pk_bf16_f32 v115, v76, v77
	v_cvt_pk_bf16_f32 v116, v62, v63
	v_cvt_pk_bf16_f32 v117, v64, v65
	global_store_dwordx4 v[172:173], v[74:77], off offset:512 nt
	global_store_dwordx4 v[172:173], v[62:65], off offset:528 nt
	global_store_dwordx4 v[122:123], v[114:117], off offset:256 nt
	s_nop 1
	v_and_b32_e32 v114, 63, v183
	v_lshlrev_b32_e32 v115, 2, v114
	v_xor_b32_e32 v116, 64, v115
	ds_bpermute_b32 v117, v116, v178
	v_xor_b32_e32 v115, 0x80, v115
	s_waitcnt lgkmcnt(0)
	v_add_f32_e32 v118, v178, v117
	ds_bpermute_b32 v119, v115, v118
	v_lshl_add_u32 v117, v184, 4, s4
	s_and_saveexec_b64 s[8:9], vcc
	s_cbranch_execz .LBB0_2337
	s_waitcnt lgkmcnt(0)
	v_add_f32_e32 v118, v118, v119
	ds_write_b32 v117, v118

; __device__ __forceinline__ float shx(float v, int o, int lane) { return __builtin_bit_cast(float, __builtin_amdgcn_ds_bpermute((lane ^ o) << 2, __builtin_bit_cast(int, v))); }
; __device__ __forceinline__ void rows_rstd(const float* ssq, int row0  , int fr, int fq, float (&rs)[8]) {
;     const int lane = fq * 16 + fr; f32x4 p[8];
;     const float* b0 = ssq + (size_t)row0 * 16 + fq * 4;
; #pragma unroll
;     for (int r = 0; r < 8; ++r) p[r] = *(const f32x4*)(b0 + (r >> 2) * (HALF * 16) + (r & 3) * 256);
; #pragma unroll
;     for (int r = 0; r < 8; ++r) { float v = (p[r][0] + p[r][1]) + (p[r][2] + p[r][3]); v += shx(v, 16, lane); v += shx(v, 32, lane); rs[r] = rsqrtf(v * (1.0f / 2048.0f) + 1e-6f); }
; }
;     __device__ __forceinline__ void operator()(f32x4 (&acc)[2][2][4][2], const Unit& u, int wr, int wc, int fr, int fq) const {
;     ...
;         { float rsv[8]; rows_rstd(ssq_in, u.pm * BM + wr * 64 + fr, fr, fq, rsv);
; #pragma unroll
;             for (int r = 0; r < 8; ++r)
; #pragma unroll
;                 for (int c = 0; c < 4; ++c) acc[r >> 2][c >> 1][r & 3][c & 1] = acc[r >> 2][c >> 1][r & 3][c & 1] * rsv[r]; }
.LBB0_2379:
	v_mov_b32_e32 v130, v246
	s_lshl_b32 s3, s8, 8
	s_add_i32 s3, s3, s42
	v_and_b32_e32 v168, 15, v130
	v_or_b32_e32 v166, s3, v168
	v_ashrrev_i32_e32 v167, 31, v166
	v_readlane_b32 s8, v254, 13
	v_bfe_u32 v178, v130, 4, 2
	v_lshlrev_b64 v[130:131], 6, v[166:167]
	v_readlane_b32 s9, v254, 14
	v_lshlrev_b32_e32 v132, 4, v178
	v_mov_b32_e32 v133, v0
	v_lshl_add_u64 v[130:131], s[8:9], 0, v[130:131]
	v_lshl_add_u64 v[130:131], v[130:131], 0, v[132:133]
	global_load_dwordx4 v[172:175], v[130:131], off
	global_load_dwordx4 v[188:191], v[130:131], off offset:1024
	global_load_dwordx4 v[150:153], v[130:131], off offset:2048
	global_load_dwordx4 v[146:149], v[130:131], off offset:3072
	v_add_co_u32_e32 v130, vcc, s91, v130
	v_lshlrev_b32_e32 v169, 6, v178
	s_nop 0
	v_addc_co_u32_e32 v131, vcc, 0, v131, vcc
	global_load_dwordx4 v[142:145], v[130:131], off
	global_load_dwordx4 v[138:141], v[130:131], off offset:1024
	global_load_dwordx4 v[134:137], v[130:131], off offset:2048
	s_nop 0
	global_load_dwordx4 v[130:133], v[130:131], off offset:3072
	v_lshlrev_b32_e32 v168, 2, v168
	v_bitop3_b32 v171, v169, 64, v168 bitop3:0x36
	v_bitop3_b32 v169, v169, s71, v168 bitop3:0x36
	s_mov_b32 s8, 0x358637bd
	v_mov_b32_e32 v182, v246
	v_or_b32_e32 v248, 32, v166
	v_or_b32_e32 v238, 48, v166
	v_ashrrev_i32_e32 v249, 31, v248
	v_ashrrev_i32_e32 v239, 31, v238
	v_lshlrev_b64 v[224:225], 13, v[248:249]
	s_waitcnt vmcnt(0)
	v_mov_b32_e32 v176, v173
	v_mov_b32_e32 v177, v174
	v_mov_b32_e32 v173, v175
	v_mov_b32_e32 v174, v189
	v_mov_b32_e32 v175, v190
	v_mov_b32_e32 v189, v191
	v_pk_add_f32 v[172:173], v[176:177], v[172:173]
	v_pk_add_f32 v[174:175], v[174:175], v[188:189]
	v_mov_b32_e32 v177, v172
	v_mov_b32_e32 v176, v174
	v_mov_b32_e32 v172, v175
	v_pk_add_f32 v[172:173], v[176:177], v[172:173]
	ds_bpermute_b32 v175, v171, v173
	ds_bpermute_b32 v174, v171, v172
	s_waitcnt lgkmcnt(0)
	v_pk_add_f32 v[172:173], v[172:173], v[174:175]
	ds_bpermute_b32 v175, v169, v173
	ds_bpermute_b32 v174, v169, v172
	s_waitcnt lgkmcnt(0)
	v_pk_add_f32 v[174:175], v[172:173], v[174:175]
	v_mov_b64_e32 v[172:173], s[8:9]
	v_pk_fma_f32 v[174:175], v[174:175], s[2:3], v[172:173] op_sel_hi:[1,0,0]
	s_nop 0
	v_mul_f32_e32 v168, 0x4b800000, v175
	v_cmp_gt_f32_e64 s[8:9], s46, v175
	v_cmp_gt_f32_e32 vcc, s46, v174
	s_nop 0
	v_cndmask_b32_e64 v168, v175, v168, s[8:9]
	v_rsq_f32_e32 v168, v168
	v_mov_b32_e32 v175, v152
	v_mov_b32_e32 v152, v147
	v_mov_b32_e32 v147, v149
	v_mul_f32_e32 v170, 0x45800000, v168
	v_cndmask_b32_e64 v170, v168, v170, s[8:9]
	v_mul_f32_e32 v168, 0x4b800000, v174
	v_cndmask_b32_e32 v168, v174, v168, vcc
	v_rsq_f32_e32 v168, v168
	v_pk_mul_f32 v[236:237], v[110:111], v[170:171] op_sel_hi:[1,0]
	v_pk_mul_f32 v[234:235], v[112:113], v[170:171] op_sel_hi:[1,0]
	v_pk_mul_f32 v[228:229], v[108:109], v[170:171] op_sel_hi:[1,0]
	v_mul_f32_e32 v174, 0x45800000, v168
	v_cndmask_b32_e32 v168, v168, v174, vcc
	v_mov_b32_e32 v174, v151
	v_mov_b32_e32 v151, v153
	v_mov_b32_e32 v153, v148
	v_pk_add_f32 v[150:151], v[174:175], v[150:151]
	v_pk_add_f32 v[146:147], v[152:153], v[146:147]
	v_mov_b32_e32 v149, v150
	v_mov_b32_e32 v148, v146
	v_mov_b32_e32 v150, v147
	v_pk_add_f32 v[146:147], v[148:149], v[150:151]
	ds_bpermute_b32 v149, v171, v147
	ds_bpermute_b32 v148, v171, v146
	v_mov_b32_e32 v150, v143
	v_mov_b32_e32 v151, v144
	v_mov_b32_e32 v143, v145
	v_mov_b32_e32 v144, v139
	v_mov_b32_e32 v145, v140
	v_mov_b32_e32 v139, v141
	v_pk_add_f32 v[142:143], v[150:151], v[142:143]
	v_pk_add_f32 v[138:139], v[144:145], v[138:139]
	s_waitcnt lgkmcnt(0)
	v_pk_add_f32 v[146:147], v[146:147], v[148:149]
	v_mov_b32_e32 v140, v138
	v_mov_b32_e32 v141, v142
	v_mov_b32_e32 v142, v139
	ds_bpermute_b32 v149, v169, v147
	ds_bpermute_b32 v148, v169, v146
	v_pk_add_f32 v[138:139], v[140:141], v[142:143]
	ds_bpermute_b32 v141, v171, v139
	ds_bpermute_b32 v140, v171, v138
	v_pk_mul_f32 v[230:231], v[106:107], v[170:171] op_sel_hi:[1,0]
	s_waitcnt lgkmcnt(2)
	v_pk_add_f32 v[146:147], v[146:147], v[148:149]
	v_pk_mul_f32 v[220:221], v[114:115], v[168:169] op_sel_hi:[1,0]
	v_pk_fma_f32 v[146:147], v[146:147], s[2:3], v[172:173] op_sel_hi:[1,0,0]
	s_waitcnt lgkmcnt(0)
	v_pk_add_f32 v[138:139], v[138:139], v[140:141]
	v_mul_f32_e32 v148, 0x4b800000, v147
	v_cmp_gt_f32_e64 s[8:9], s46, v147
	ds_bpermute_b32 v141, v169, v139
	ds_bpermute_b32 v140, v169, v138
	v_cndmask_b32_e64 v147, v147, v148, s[8:9]
	v_rsq_f32_e32 v147, v147
	v_cmp_gt_f32_e32 vcc, s46, v146
	v_pk_mul_f32 v[214:215], v[96:97], v[168:169] op_sel_hi:[1,0]
	s_waitcnt lgkmcnt(0)
	v_pk_add_f32 v[138:139], v[138:139], v[140:141]
	v_mul_f32_e32 v148, 0x45800000, v147
	v_pk_fma_f32 v[138:139], v[138:139], s[2:3], v[172:173] op_sel_hi:[1,0,0]
	v_cndmask_b32_e64 v148, v147, v148, s[8:9]
	v_mul_f32_e32 v147, 0x4b800000, v146
	v_mul_f32_e32 v140, 0x4b800000, v139
	v_cmp_gt_f32_e64 s[8:9], s46, v139
	v_cndmask_b32_e32 v146, v146, v147, vcc
	v_rsq_f32_e32 v146, v146
	v_cndmask_b32_e64 v139, v139, v140, s[8:9]
	v_rsq_f32_e32 v139, v139
	v_pk_mul_f32 v[202:203], v[98:99], v[148:149] op_sel_hi:[1,0]
	v_mul_f32_e32 v147, 0x45800000, v146
	v_cndmask_b32_e32 v146, v146, v147, vcc
	v_mul_f32_e32 v140, 0x45800000, v139
	v_cmp_gt_f32_e32 vcc, s46, v138
	v_cndmask_b32_e64 v184, v139, v140, s[8:9]
	v_mul_f32_e32 v139, 0x4b800000, v138
	v_cndmask_b32_e32 v138, v138, v139, vcc
	v_rsq_f32_e32 v138, v138
	v_pk_mul_f32 v[174:175], v[84:85], v[146:147] op_sel_hi:[1,0]
	v_pk_mul_f32 v[204:205], v[104:105], v[148:149] op_sel_hi:[1,0]
	v_pk_mul_f32 v[206:207], v[102:103], v[148:149] op_sel_hi:[1,0]
	v_mul_f32_e32 v139, 0x45800000, v138
	v_cndmask_b32_e32 v186, v138, v139, vcc
	v_mov_b32_e32 v138, v135
	v_mov_b32_e32 v139, v136
	v_mov_b32_e32 v135, v137
	v_mov_b32_e32 v136, v131
	v_mov_b32_e32 v137, v132
	v_mov_b32_e32 v131, v133
	v_pk_add_f32 v[134:135], v[138:139], v[134:135]
	v_pk_add_f32 v[130:131], v[136:137], v[130:131]
	v_mov_b32_e32 v133, v134
	v_mov_b32_e32 v132, v130
	v_mov_b32_e32 v134, v131
	v_pk_add_f32 v[130:131], v[132:133], v[134:135]
	ds_bpermute_b32 v133, v171, v131
	ds_bpermute_b32 v132, v171, v130
	v_pk_mul_f32 v[200:201], v[100:101], v[148:149] op_sel_hi:[1,0]
	v_pk_mul_f32 v[176:177], v[82:83], v[146:147] op_sel_hi:[1,0]
	v_pk_mul_f32 v[192:193], v[76:77], v[148:149] op_sel_hi:[1,0]
	v_pk_mul_f32 v[194:195], v[74:75], v[148:149] op_sel_hi:[1,0]
	s_waitcnt lgkmcnt(0)
;     __device__ __forceinline__ void operator()(f32x4 (&acc)[2][2][4][2], const Unit& u, int wr, int wc, int fr, int fq) const {
;     ...
;         { float rsv[8]; rows_rstd(ssq_in, u.pm * BM + wr * 64 + fr, fr, fq, rsv);
; #pragma unroll
;             for (int r = 0; r < 8; ++r)
; #pragma unroll
;                 for (int c = 0; c < 4; ++c) acc[r >> 2][c >> 1][r & 3][c & 1] = acc[r >> 2][c >> 1][r & 3][c & 1] * rsv[r]; }
;         f32x4 cur[2][4], nxt[2][4]; u32x2 pcur[4], pnxt[4];
; #pragma unroll
;         for (int q = 0; q < 2; ++q)
; #pragma unroll
;             for (int c = 0; c < 4; ++c) cur[q][c] = *(const f32x4*)(h + (size_t)EPI_ROW(q) * D + col0 + (c >> 1) * HALF + (c & 1) * 4);
; #pragma unroll
;         for (int c = 0; c < 4; ++c) pcur[c] = *(const u32x2*)(pp + (size_t)EPI_ROW(0) * D + col0 + (c >> 1) * HALF + (c & 1) * 4);
; #pragma unroll
;         for (int k = 0; k < 4; ++k) {
;             if (k < 3) {
; #pragma unroll
;                 for (int q = 0; q < 2; ++q)
; #pragma unroll
;                     for (int c = 0; c < 4; ++c) nxt[q][c] = *(const f32x4*)(h + (size_t)EPI_ROW(2 * k + 2 + q) * D + col0 + (c >> 1) * HALF + (c & 1) * 4);
	v_pk_add_f32 v[130:131], v[130:131], v[132:133]
	ds_bpermute_b32 v133, v169, v131
	ds_bpermute_b32 v132, v169, v130
	v_pk_mul_f32 v[150:151], v[68:69], v[146:147] op_sel_hi:[1,0]
	v_pk_mul_f32 v[152:153], v[66:67], v[146:147] op_sel_hi:[1,0]
	v_pk_mul_f32 v[216:217], v[94:95], v[168:169] op_sel_hi:[1,0]
	v_pk_mul_f32 v[210:211], v[92:93], v[168:169] op_sel_hi:[1,0]
	s_waitcnt lgkmcnt(0)
	v_pk_add_f32 v[130:131], v[130:131], v[132:133]
	v_pk_mul_f32 v[212:213], v[90:91], v[168:169] op_sel_hi:[1,0]
	v_pk_fma_f32 v[130:131], v[130:131], s[2:3], v[172:173] op_sel_hi:[1,0,0]
	s_lshl_b32 s3, s33, 8
	v_mul_f32_e32 v132, 0x4b800000, v131
	v_cmp_gt_f32_e64 s[8:9], s46, v131
	v_cmp_gt_f32_e32 vcc, s46, v130
	v_pk_mul_f32 v[188:189], v[88:89], v[146:147] op_sel_hi:[1,0]
	v_cndmask_b32_e64 v131, v131, v132, s[8:9]
	v_rsq_f32_e32 v131, v131
	v_pk_mul_f32 v[190:191], v[86:87], v[146:147] op_sel_hi:[1,0]
	v_pk_mul_f32 v[244:245], v[128:129], v[170:171] op_sel_hi:[1,0]
	v_pk_mul_f32 v[246:247], v[126:127], v[170:171] op_sel_hi:[1,0]
	v_mul_f32_e32 v132, 0x45800000, v131
	v_cndmask_b32_e64 v172, v131, v132, s[8:9]
	v_mul_f32_e32 v131, 0x4b800000, v130
	v_cndmask_b32_e32 v130, v130, v131, vcc
	v_rsq_f32_e32 v130, v130
	v_pk_mul_f32 v[110:111], v[38:39], v[172:173] op_sel_hi:[1,0]
	v_or_b32_e32 v38, 16, v166
	v_pk_mul_f32 v[112:113], v[48:49], v[172:173] op_sel_hi:[1,0]
	v_mul_f32_e32 v131, 0x45800000, v130
	v_cndmask_b32_e32 v208, v130, v131, vcc
	v_pk_mul_f32 v[84:85], v[2:3], v[208:209] op_sel_hi:[1,0]
	v_lshl_or_b32 v2, v178, 3, s3
	v_or_b32_e32 v2, s44, v2
	v_ashrrev_i32_e32 v3, 31, v2
	v_lshlrev_b64 v[98:99], 2, v[2:3]
	v_pk_mul_f32 v[114:115], v[46:47], v[172:173] op_sel_hi:[1,0]
	v_pk_mul_f32 v[108:109], v[40:41], v[172:173] op_sel_hi:[1,0]
	v_pk_mul_f32 v[104:105], v[16:17], v[172:173] op_sel_hi:[1,0]
	v_pk_mul_f32 v[106:107], v[14:15], v[172:173] op_sel_hi:[1,0]
	v_pk_mul_f32 v[100:101], v[12:13], v[172:173] op_sel_hi:[1,0]
	v_pk_mul_f32 v[102:103], v[10:11], v[172:173] op_sel_hi:[1,0]
	v_lshl_add_u64 v[172:173], s[36:37], 0, v[98:99]
	v_lshlrev_b64 v[178:179], 13, v[166:167]
	v_ashrrev_i32_e32 v39, 31, v38
	v_pk_mul_f32 v[82:83], v[4:5], v[208:209] op_sel_hi:[1,0]
	v_lshl_add_u64 v[4:5], v[172:173], 0, v[178:179]
	v_lshlrev_b64 v[232:233], 13, v[38:39]
	v_pk_mul_f32 v[130:131], v[56:57], v[186:187] op_sel_hi:[1,0]
	v_pk_mul_f32 v[132:133], v[54:55], v[186:187] op_sel_hi:[1,0]
	global_load_dwordx4 v[66:69], v[4:5], off offset:16
	global_load_dwordx4 v[74:77], v[4:5], off
	global_load_dwordx4 v[46:49], v[4:5], off offset:528
	global_load_dwordx4 v[54:57], v[4:5], off offset:512
	v_lshl_add_u64 v[4:5], v[172:173], 0, v[232:233]
	v_pk_mul_f32 v[94:95], v[32:33], v[208:209] op_sel_hi:[1,0]
	v_pk_mul_f32 v[96:97], v[30:31], v[208:209] op_sel_hi:[1,0]
	v_pk_mul_f32 v[90:91], v[24:25], v[208:209] op_sel_hi:[1,0]
	v_pk_mul_f32 v[92:93], v[22:23], v[208:209] op_sel_hi:[1,0]
	v_pk_mul_f32 v[86:87], v[8:9], v[208:209] op_sel_hi:[1,0]
	v_pk_mul_f32 v[88:89], v[6:7], v[208:209] op_sel_hi:[1,0]
	global_load_dwordx4 v[22:25], v[4:5], off offset:16
	global_load_dwordx4 v[30:33], v[4:5], off
	global_load_dwordx4 v[6:9], v[4:5], off offset:528
	global_load_dwordx4 v[14:17], v[4:5], off offset:512
	v_lshlrev_b64 v[4:5], 12, v[166:167]
	v_lshl_add_u64 v[4:5], s[56:57], 0, v[4:5]
	v_lshlrev_b64 v[128:129], 1, v[2:3]
	v_lshl_add_u64 v[2:3], v[4:5], 0, v[128:129]
	v_pk_mul_f32 v[240:241], v[124:125], v[170:171] op_sel_hi:[1,0]
	v_pk_mul_f32 v[242:243], v[122:123], v[170:171] op_sel_hi:[1,0]
	v_pk_mul_f32 v[222:223], v[120:121], v[168:169] op_sel_hi:[1,0]
	v_pk_mul_f32 v[226:227], v[118:119], v[168:169] op_sel_hi:[1,0]
	v_pk_mul_f32 v[218:219], v[116:117], v[168:169] op_sel_hi:[1,0]
	v_pk_mul_f32 v[196:197], v[80:81], v[148:149] op_sel_hi:[1,0]
	v_pk_mul_f32 v[198:199], v[78:79], v[148:149] op_sel_hi:[1,0]
	v_pk_mul_f32 v[168:169], v[72:73], v[146:147] op_sel_hi:[1,0]
	v_pk_mul_f32 v[170:171], v[70:71], v[146:147] op_sel_hi:[1,0]
	global_load_dwordx4 v[70:73], v[2:3], off
	global_load_dwordx4 v[78:81], v[2:3], off offset:256
	v_mul_f32_e32 v167, 0xbfb8aa3b, v246
	v_exp_f32_e32 v167, v167
	v_pk_mul_f32 v[146:147], v[64:65], v[184:185] op_sel_hi:[1,0]
	v_pk_mul_f32 v[148:149], v[62:63], v[184:185] op_sel_hi:[1,0]
	v_pk_mul_f32 v[142:143], v[60:61], v[184:185] op_sel_hi:[1,0]
	v_add_f32_e32 v167, 1.0, v167
	v_pk_mul_f32 v[144:145], v[58:59], v[184:185] op_sel_hi:[1,0]
	v_pk_mul_f32 v[138:139], v[44:45], v[184:185] op_sel_hi:[1,0]
	v_pk_mul_f32 v[140:141], v[42:43], v[184:185] op_sel_hi:[1,0]
	v_pk_mul_f32 v[134:135], v[36:37], v[184:185] op_sel_hi:[1,0]
	v_pk_mul_f32 v[136:137], v[34:35], v[184:185] op_sel_hi:[1,0]
	v_rcp_f32_e32 v184, v167
	v_mul_f32_e32 v167, 0xbfb8aa3b, v247
	v_exp_f32_e32 v167, v167
	v_pk_mul_f32 v[124:125], v[52:53], v[186:187] op_sel_hi:[1,0]
	v_pk_mul_f32 v[126:127], v[50:51], v[186:187] op_sel_hi:[1,0]
	v_pk_mul_f32 v[120:121], v[28:29], v[186:187] op_sel_hi:[1,0]
	v_pk_mul_f32 v[122:123], v[26:27], v[186:187] op_sel_hi:[1,0]
	v_pk_mul_f32 v[116:117], v[20:21], v[186:187] op_sel_hi:[1,0]
	v_pk_mul_f32 v[118:119], v[18:19], v[186:187] op_sel_hi:[1,0]
	v_add_f32_e32 v167, 1.0, v167
	v_rcp_f32_e32 v185, v167
	v_lshlrev_b64 v[38:39], 12, v[38:39]
	v_lshlrev_b64 v[208:209], 13, v[238:239]
	v_lshl_add_u64 v[38:39], s[56:57], 0, v[38:39]
	v_lshl_add_u64 v[2:3], v[172:173], 0, v[224:225]
	v_lshl_add_u64 v[10:11], v[172:173], 0, v[208:209]
	v_lshl_add_u64 v[38:39], v[38:39], 0, v[128:129]
	global_load_dwordx4 v[50:53], v[2:3], off offset:16
	global_load_dwordx4 v[58:61], v[2:3], off
	global_load_dwordx4 v[34:37], v[2:3], off offset:528
	global_load_dwordx4 v[42:45], v[2:3], off offset:512
	global_load_dwordx4 v[18:21], v[10:11], off offset:16
	global_load_dwordx4 v[26:29], v[10:11], off
	s_nop 0
	global_load_dwordx4 v[2:5], v[10:11], off offset:528
	s_nop 0
	global_load_dwordx4 v[10:13], v[10:11], off offset:512
	s_nop 0
	global_load_dwordx4 v[62:65], v[38:39], off
	s_nop 0
	global_load_dwordx4 v[38:41], v[38:39], off offset:256
	v_mul_f32_e32 v167, 0xbfb8aa3b, v206
	v_exp_f32_e32 v167, v167
	v_mul_f32_e32 v148, 0xbfb8aa3b, v148
	v_mul_f32_e32 v149, 0xbfb8aa3b, v149
	v_exp_f32_e32 v148, v148
	v_add_f32_e32 v167, 1.0, v167
	v_exp_f32_e32 v149, v149
	s_mov_b64 s[8:9], -1
	v_add_f32_e32 v148, 1.0, v148
	v_rcp_f32_e32 v148, v148
	v_add_f32_e32 v149, 1.0, v149
	v_rcp_f32_e32 v149, v149
	s_andn2_b64 vcc, exec, s[6:7]
	s_waitcnt vmcnt(11)
; __device__ __forceinline__ float sigmoidf_(float x) { return __builtin_amdgcn_rcpf(1.0f + __expf(-x)); }
; __device__ __forceinline__ float ssq4(const f32x4 o) { return (o[0] * o[0] + o[1] * o[1]) + (o[2] * o[2] + o[3] * o[3]); }
;     __device__ __forceinline__ void operator()(f32x4 (&acc)[2][2][4][2], const Unit& u, int wr, int wc, int fr, int fq) const {
;     ...
;         for (int k = 0; k < 4; ++k) {
;             if (k < 3) {
; #pragma unroll
;                 for (int q = 0; q < 2; ++q)
; #pragma unroll
;                     for (int c = 0; c < 4; ++c) nxt[q][c] = *(const f32x4*)(h + (size_t)EPI_ROW(2 * k + 2 + q) * D + col0 + (c >> 1) * HALF + (c & 1) * 4);
;             }
; #pragma unroll
;             for (int q = 0; q < 2; ++q) { const int r = 2 * k + q, ai = r >> 2, m = r & 3; const size_t off = (size_t)EPI_ROW(r) * D + col0; float sr = 0.f;
;                 if (r < 7) {
; #pragma unroll
;                     for (int c = 0; c < 4; ++c) pnxt[c] = *(const u32x2*)(pp + (size_t)EPI_ROW(r + 1) * D + col0 + (c >> 1) * HALF + (c & 1) * 4);
;                 }
;                 asm volatile("" ::: "memory");
; #pragma unroll
;                 for (int bj = 0; bj < 2; ++bj) { f32x4 o2[2];
; #pragma unroll
;                     for (int n = 0; n < 2; ++n) { const f32x4 b = cur[q][2 * bj + n]; const u32x2 qw = pcur[2 * bj + n];
;                         const f32x4 pq = (f32x4){bflo(qw.x), bfhi(qw.x), bflo(qw.y), bfhi(qw.y)}; const f32x4 a = acc[ai][bj][m][n];
; #pragma unroll
;                         for (int j = 0; j < 4; ++j) o2[n][j] = b[j] + pq[j] * sigmoidf_(a[j]); }
;                     *(f32x4*)(h + off + bj * HALF) = o2[0]; *(f32x4*)(h + off + bj * HALF + 4) = o2[1];
;                     if (!LAST) { u32x4 w; w.x = cvt_pk_bf16(o2[0][0], o2[0][1]); w.y = cvt_pk_bf16(o2[0][2], o2[0][3]); w.z = cvt_pk_bf16(o2[1][0], o2[1][1]); w.w = cvt_pk_bf16(o2[1][2], o2[1][3]);
;                         *(u32x4*)(hb + off + bj * HALF) = w; sr += ssq4(o2[0]) + ssq4(o2[1]); } }
	v_lshlrev_b32_e32 v186, 16, v70
	v_and_b32_e32 v187, 0xffff0000, v70
	v_mul_f32_e32 v70, 0xbfb8aa3b, v244
	v_exp_f32_e32 v70, v70
	v_pk_fma_f32 v[74:75], v[184:185], v[186:187], v[74:75]
	v_add_f32_e32 v70, 1.0, v70
	v_rcp_f32_e32 v184, v70
	v_mul_f32_e32 v70, 0xbfb8aa3b, v245
	v_exp_f32_e32 v70, v70
	s_nop 0
	v_add_f32_e32 v70, 1.0, v70
	v_rcp_f32_e32 v185, v70
	v_lshlrev_b32_e32 v70, 16, v71
	v_and_b32_e32 v71, 0xffff0000, v71
	v_pk_fma_f32 v[76:77], v[184:185], v[70:71], v[76:77]
	v_mul_f32_e32 v70, 0xbfb8aa3b, v242
	v_mul_f32_e32 v71, 0xbfb8aa3b, v243
	v_exp_f32_e32 v70, v70
	v_exp_f32_e32 v71, v71
	v_lshlrev_b32_e32 v184, 16, v72
	v_and_b32_e32 v185, 0xffff0000, v72
	v_add_f32_e32 v70, 1.0, v70
	v_add_f32_e32 v71, 1.0, v71
	v_rcp_f32_e32 v70, v70
	v_rcp_f32_e32 v71, v71
	v_lshlrev_b32_e32 v72, 16, v73
	v_and_b32_e32 v73, 0xffff0000, v73
	v_pk_fma_f32 v[66:67], v[70:71], v[184:185], v[66:67]
	v_mul_f32_e32 v70, 0xbfb8aa3b, v240
	v_mul_f32_e32 v71, 0xbfb8aa3b, v241
	v_exp_f32_e32 v70, v70
	v_exp_f32_e32 v71, v71
	v_rcp_f32_e32 v184, v167
	v_mul_f32_e32 v167, 0xbfb8aa3b, v207
	v_add_f32_e32 v70, 1.0, v70
	v_add_f32_e32 v71, 1.0, v71
	v_rcp_f32_e32 v70, v70
	v_rcp_f32_e32 v71, v71
	v_exp_f32_e32 v167, v167
	v_pk_fma_f32 v[68:69], v[70:71], v[72:73], v[68:69]
	v_lshl_add_u64 v[70:71], s[36:37], 0, v[178:179]
	v_lshl_add_u64 v[70:71], v[70:71], 0, v[98:99]
	global_store_dwordx4 v[70:71], v[74:77], off nt
	global_store_dwordx4 v[70:71], v[66:69], off offset:16 nt
	v_add_f32_e32 v167, 1.0, v167
	v_rcp_f32_e32 v185, v167
	v_mul_f32_e32 v66, 0xbfb8aa3b, v236
	v_mul_f32_e32 v67, 0xbfb8aa3b, v237
	v_exp_f32_e32 v66, v66
	v_exp_f32_e32 v67, v67
	s_waitcnt vmcnt(12)
	v_lshlrev_b32_e32 v68, 16, v78
	v_and_b32_e32 v69, 0xffff0000, v78
	v_add_f32_e32 v66, 1.0, v66
	v_add_f32_e32 v67, 1.0, v67
	v_rcp_f32_e32 v66, v66
	v_rcp_f32_e32 v67, v67
	v_add_u32_e32 v178, 0x80, v166
	v_ashrrev_i32_e32 v179, 31, v178
	v_pk_fma_f32 v[54:55], v[66:67], v[68:69], v[54:55]
	v_mul_f32_e32 v66, 0xbfb8aa3b, v234
	v_mul_f32_e32 v67, 0xbfb8aa3b, v235
	v_exp_f32_e32 v66, v66
	v_exp_f32_e32 v67, v67
	v_lshlrev_b32_e32 v68, 16, v79
	v_and_b32_e32 v69, 0xffff0000, v79
	v_add_f32_e32 v66, 1.0, v66
	v_add_f32_e32 v67, 1.0, v67
	v_rcp_f32_e32 v66, v66
	v_rcp_f32_e32 v67, v67
	s_nop 0
	v_pk_fma_f32 v[56:57], v[66:67], v[68:69], v[56:57]
	v_mul_f32_e32 v66, 0xbfb8aa3b, v230
	v_mul_f32_e32 v67, 0xbfb8aa3b, v231
	v_exp_f32_e32 v66, v66
	v_exp_f32_e32 v67, v67
	v_lshlrev_b32_e32 v68, 16, v80
	v_and_b32_e32 v69, 0xffff0000, v80
	v_add_f32_e32 v66, 1.0, v66
	v_add_f32_e32 v67, 1.0, v67
	v_rcp_f32_e32 v66, v66
	v_rcp_f32_e32 v67, v67
	s_nop 0
	v_pk_fma_f32 v[46:47], v[66:67], v[68:69], v[46:47]
	v_mul_f32_e32 v66, 0xbfb8aa3b, v228
	v_mul_f32_e32 v67, 0xbfb8aa3b, v229
	v_exp_f32_e32 v66, v66
	v_exp_f32_e32 v67, v67
	v_lshlrev_b32_e32 v68, 16, v81
	v_and_b32_e32 v69, 0xffff0000, v81
	v_add_f32_e32 v66, 1.0, v66
	v_add_f32_e32 v67, 1.0, v67
	v_rcp_f32_e32 v66, v66
	v_rcp_f32_e32 v67, v67
	s_nop 0
	v_pk_fma_f32 v[48:49], v[66:67], v[68:69], v[48:49]
	global_store_dwordx4 v[70:71], v[54:57], off offset:512 nt
	global_store_dwordx4 v[70:71], v[46:49], off offset:528 nt
	v_lshlrev_b64 v[70:71], 12, v[238:239]
	v_lshl_add_u64 v[70:71], s[56:57], 0, v[70:71]
	v_lshlrev_b64 v[46:47], 12, v[248:249]
	v_lshl_add_u64 v[46:47], s[56:57], 0, v[46:47]
	v_lshl_add_u64 v[46:47], v[46:47], 0, v[128:129]
	global_load_dwordx4 v[74:77], v[46:47], off
	global_load_dwordx4 v[66:69], v[46:47], off offset:256
	v_mul_f32_e32 v46, 0xbfb8aa3b, v226
	v_mul_f32_e32 v47, 0xbfb8aa3b, v227
	v_exp_f32_e32 v46, v46
	v_exp_f32_e32 v47, v47
	s_waitcnt vmcnt(7)
	v_lshlrev_b32_e32 v48, 16, v62
	v_and_b32_e32 v49, 0xffff0000, v62
	v_add_f32_e32 v46, 1.0, v46
	v_add_f32_e32 v47, 1.0, v47
	v_rcp_f32_e32 v46, v46
	v_rcp_f32_e32 v47, v47
	v_lshl_add_u64 v[70:71], v[70:71], 0, v[128:129]
	v_pk_fma_f32 v[30:31], v[46:47], v[48:49], v[30:31]
	v_mul_f32_e32 v46, 0xbfb8aa3b, v222
	v_mul_f32_e32 v47, 0xbfb8aa3b, v223
	v_exp_f32_e32 v46, v46
	v_exp_f32_e32 v47, v47
	v_lshlrev_b32_e32 v48, 16, v63
	v_and_b32_e32 v49, 0xffff0000, v63
	v_add_f32_e32 v46, 1.0, v46
	v_add_f32_e32 v47, 1.0, v47
	v_rcp_f32_e32 v46, v46
	v_rcp_f32_e32 v47, v47
	s_waitcnt vmcnt(1)
; __device__ __forceinline__ float sigmoidf_(float x) { return __builtin_amdgcn_rcpf(1.0f + __expf(-x)); }
; __device__ __forceinline__ float ssq4(const f32x4 o) { return (o[0] * o[0] + o[1] * o[1]) + (o[2] * o[2] + o[3] * o[3]); }
;     __device__ __forceinline__ void operator()(f32x4 (&acc)[2][2][4][2], const Unit& u, int wr, int wc, int fr, int fq) const {
;     ...
;         for (int k = 0; k < 4; ++k) {
;             if (k < 3) {
; #pragma unroll
;                 for (int q = 0; q < 2; ++q)
; #pragma unroll
;                     for (int c = 0; c < 4; ++c) nxt[q][c] = *(const f32x4*)(h + (size_t)EPI_ROW(2 * k + 2 + q) * D + col0 + (c >> 1) * HALF + (c & 1) * 4);
;             }
; #pragma unroll
;             for (int q = 0; q < 2; ++q) { const int r = 2 * k + q, ai = r >> 2, m = r & 3; const size_t off = (size_t)EPI_ROW(r) * D + col0; float sr = 0.f;
;                 if (r < 7) {
; #pragma unroll
;                     for (int c = 0; c < 4; ++c) pnxt[c] = *(const u32x2*)(pp + (size_t)EPI_ROW(r + 1) * D + col0 + (c >> 1) * HALF + (c & 1) * 4);
;                 }
;                 asm volatile("" ::: "memory");
; #pragma unroll
;                 for (int bj = 0; bj < 2; ++bj) { f32x4 o2[2];
; #pragma unroll
;                     for (int n = 0; n < 2; ++n) { const f32x4 b = cur[q][2 * bj + n]; const u32x2 qw = pcur[2 * bj + n];
;                         const f32x4 pq = (f32x4){bflo(qw.x), bfhi(qw.x), bflo(qw.y), bfhi(qw.y)}; const f32x4 a = acc[ai][bj][m][n];
; #pragma unroll
;                         for (int j = 0; j < 4; ++j) o2[n][j] = b[j] + pq[j] * sigmoidf_(a[j]); }
;                     *(f32x4*)(h + off + bj * HALF) = o2[0]; *(f32x4*)(h + off + bj * HALF + 4) = o2[1];
;                     if (!LAST) { u32x4 w; w.x = cvt_pk_bf16(o2[0][0], o2[0][1]); w.y = cvt_pk_bf16(o2[0][2], o2[0][3]); w.z = cvt_pk_bf16(o2[1][0], o2[1][1]); w.w = cvt_pk_bf16(o2[1][2], o2[1][3]);
;                         *(u32x4*)(hb + off + bj * HALF) = w; sr += ssq4(o2[0]) + ssq4(o2[1]); } }
	v_lshlrev_b32_e32 v186, 16, v74
	v_pk_fma_f32 v[32:33], v[46:47], v[48:49], v[32:33]
	v_mul_f32_e32 v46, 0xbfb8aa3b, v220
	v_mul_f32_e32 v47, 0xbfb8aa3b, v221
	v_exp_f32_e32 v46, v46
	v_exp_f32_e32 v47, v47
	v_lshlrev_b32_e32 v48, 16, v64
	v_and_b32_e32 v49, 0xffff0000, v64
	v_add_f32_e32 v46, 1.0, v46
	v_add_f32_e32 v47, 1.0, v47
	v_rcp_f32_e32 v46, v46
	v_rcp_f32_e32 v47, v47
	v_and_b32_e32 v187, 0xffff0000, v74
	v_mul_f32_e32 v74, 0xbfb8aa3b, v204
	v_exp_f32_e32 v74, v74
	v_pk_fma_f32 v[22:23], v[46:47], v[48:49], v[22:23]
	v_mul_f32_e32 v46, 0xbfb8aa3b, v218
	v_mul_f32_e32 v47, 0xbfb8aa3b, v219
	v_exp_f32_e32 v46, v46
	v_exp_f32_e32 v47, v47
	v_lshlrev_b32_e32 v48, 16, v65
	v_and_b32_e32 v49, 0xffff0000, v65
	v_add_f32_e32 v46, 1.0, v46
	v_add_f32_e32 v47, 1.0, v47
	v_rcp_f32_e32 v46, v46
	v_rcp_f32_e32 v47, v47
	v_add_f32_e32 v74, 1.0, v74
	v_pk_fma_f32 v[58:59], v[184:185], v[186:187], v[58:59]
	v_rcp_f32_e32 v184, v74
	v_pk_fma_f32 v[24:25], v[46:47], v[48:49], v[24:25]
	v_lshl_add_u64 v[46:47], s[36:37], 0, v[232:233]
	v_lshl_add_u64 v[46:47], v[46:47], 0, v[98:99]
	global_store_dwordx4 v[46:47], v[30:33], off nt
	global_store_dwordx4 v[46:47], v[22:25], off offset:16 nt
	v_mul_f32_e32 v74, 0xbfb8aa3b, v205
	v_exp_f32_e32 v74, v74
	v_mul_f32_e32 v22, 0xbfb8aa3b, v216
	v_mul_f32_e32 v23, 0xbfb8aa3b, v217
	v_exp_f32_e32 v22, v22
	v_exp_f32_e32 v23, v23
	v_lshlrev_b32_e32 v24, 16, v38
	v_and_b32_e32 v25, 0xffff0000, v38
	v_add_f32_e32 v22, 1.0, v22
	v_add_f32_e32 v23, 1.0, v23
	v_rcp_f32_e32 v22, v22
	v_rcp_f32_e32 v23, v23
	v_add_f32_e32 v74, 1.0, v74
	v_rcp_f32_e32 v185, v74
	v_lshlrev_b32_e32 v74, 16, v75
	v_pk_fma_f32 v[14:15], v[22:23], v[24:25], v[14:15]
	v_mul_f32_e32 v22, 0xbfb8aa3b, v214
	v_mul_f32_e32 v23, 0xbfb8aa3b, v215
	v_exp_f32_e32 v22, v22
	v_exp_f32_e32 v23, v23
	v_lshlrev_b32_e32 v24, 16, v39
	v_and_b32_e32 v25, 0xffff0000, v39
	v_add_f32_e32 v22, 1.0, v22
	v_add_f32_e32 v23, 1.0, v23
	v_rcp_f32_e32 v22, v22
	v_rcp_f32_e32 v23, v23
	v_add_u32_e32 v214, 0x90, v166
	v_ashrrev_i32_e32 v215, 31, v214
	v_and_b32_e32 v75, 0xffff0000, v75
	v_pk_fma_f32 v[16:17], v[22:23], v[24:25], v[16:17]
	v_mul_f32_e32 v22, 0xbfb8aa3b, v212
	v_mul_f32_e32 v23, 0xbfb8aa3b, v213
	v_exp_f32_e32 v22, v22
	v_exp_f32_e32 v23, v23
	v_lshlrev_b32_e32 v24, 16, v40
	v_and_b32_e32 v25, 0xffff0000, v40
	v_add_f32_e32 v22, 1.0, v22
	v_add_f32_e32 v23, 1.0, v23
	v_rcp_f32_e32 v22, v22
	v_rcp_f32_e32 v23, v23
	v_lshlrev_b64 v[212:213], 13, v[178:179]
	v_pk_fma_f32 v[60:61], v[184:185], v[74:75], v[60:61]
	v_mul_f32_e32 v74, 0xbfb8aa3b, v202
	v_pk_fma_f32 v[6:7], v[22:23], v[24:25], v[6:7]
	v_mul_f32_e32 v22, 0xbfb8aa3b, v210
	v_mul_f32_e32 v23, 0xbfb8aa3b, v211
	v_exp_f32_e32 v22, v22
	v_exp_f32_e32 v23, v23
	v_lshlrev_b32_e32 v24, 16, v41
	v_and_b32_e32 v25, 0xffff0000, v41
	v_add_f32_e32 v22, 1.0, v22
	v_add_f32_e32 v23, 1.0, v23
	v_rcp_f32_e32 v22, v22
	v_rcp_f32_e32 v23, v23
	v_lshlrev_b64 v[210:211], 13, v[214:215]
	v_mul_f32_e32 v75, 0xbfb8aa3b, v203
	v_exp_f32_e32 v74, v74
	v_pk_fma_f32 v[8:9], v[22:23], v[24:25], v[8:9]
	global_store_dwordx4 v[46:47], v[14:17], off offset:512 nt
	global_store_dwordx4 v[46:47], v[6:9], off offset:528 nt
	v_exp_f32_e32 v75, v75
	v_lshl_add_u64 v[14:15], v[172:173], 0, v[210:211]
	v_lshl_add_u64 v[6:7], v[172:173], 0, v[212:213]
	global_load_dwordx4 v[54:57], v[6:7], off offset:16
	global_load_dwordx4 v[62:65], v[6:7], off
	global_load_dwordx4 v[38:41], v[6:7], off offset:528
	global_load_dwordx4 v[46:49], v[6:7], off offset:512
	global_load_dwordx4 v[22:25], v[14:15], off offset:16
	global_load_dwordx4 v[30:33], v[14:15], off
	s_nop 0
	global_load_dwordx4 v[6:9], v[14:15], off offset:528
	s_nop 0
	global_load_dwordx4 v[14:17], v[14:15], off offset:512
	s_nop 0
	global_load_dwordx4 v[78:81], v[70:71], off
	s_nop 0
	global_load_dwordx4 v[70:73], v[70:71], off offset:256
	v_add_f32_e32 v74, 1.0, v74
	v_add_f32_e32 v75, 1.0, v75
	v_rcp_f32_e32 v74, v74
	v_rcp_f32_e32 v75, v75
	v_lshlrev_b32_e32 v184, 16, v76
	v_and_b32_e32 v185, 0xffff0000, v76
	v_lshlrev_b32_e32 v76, 16, v77
	v_pk_fma_f32 v[50:51], v[74:75], v[184:185], v[50:51]
	v_mul_f32_e32 v74, 0xbfb8aa3b, v200
	v_mul_f32_e32 v75, 0xbfb8aa3b, v201
	v_exp_f32_e32 v74, v74
	v_exp_f32_e32 v75, v75
	v_and_b32_e32 v77, 0xffff0000, v77
	v_add_f32_e32 v74, 1.0, v74
	v_add_f32_e32 v75, 1.0, v75
	v_rcp_f32_e32 v74, v74
	v_rcp_f32_e32 v75, v75
	s_nop 0
	v_pk_fma_f32 v[52:53], v[74:75], v[76:77], v[52:53]
	v_lshl_add_u64 v[74:75], s[36:37], 0, v[224:225]
	v_lshl_add_u64 v[74:75], v[74:75], 0, v[98:99]
	global_store_dwordx4 v[74:75], v[58:61], off nt
	global_store_dwordx4 v[74:75], v[50:53], off offset:16 nt
	s_nop 1
	v_mul_f32_e32 v50, 0xbfb8aa3b, v198
	v_mul_f32_e32 v51, 0xbfb8aa3b, v199
	v_exp_f32_e32 v50, v50
	v_exp_f32_e32 v51, v51
	s_waitcnt vmcnt(16)
; __device__ __forceinline__ float sigmoidf_(float x) { return __builtin_amdgcn_rcpf(1.0f + __expf(-x)); }
; __device__ __forceinline__ float ssq4(const f32x4 o) { return (o[0] * o[0] + o[1] * o[1]) + (o[2] * o[2] + o[3] * o[3]); }
;     __device__ __forceinline__ void operator()(f32x4 (&acc)[2][2][4][2], const Unit& u, int wr, int wc, int fr, int fq) const {
;     ...
;         for (int k = 0; k < 4; ++k) {
;             if (k < 3) {
; #pragma unroll
;                 for (int q = 0; q < 2; ++q)
; #pragma unroll
;                     for (int c = 0; c < 4; ++c) nxt[q][c] = *(const f32x4*)(h + (size_t)EPI_ROW(2 * k + 2 + q) * D + col0 + (c >> 1) * HALF + (c & 1) * 4);
;             }
; #pragma unroll
;             for (int q = 0; q < 2; ++q) { const int r = 2 * k + q, ai = r >> 2, m = r & 3; const size_t off = (size_t)EPI_ROW(r) * D + col0; float sr = 0.f;
;                 if (r < 7) {
; #pragma unroll
;                     for (int c = 0; c < 4; ++c) pnxt[c] = *(const u32x2*)(pp + (size_t)EPI_ROW(r + 1) * D + col0 + (c >> 1) * HALF + (c & 1) * 4);
;                 }
;                 asm volatile("" ::: "memory");
; #pragma unroll
;                 for (int bj = 0; bj < 2; ++bj) { f32x4 o2[2];
; #pragma unroll
;                     for (int n = 0; n < 2; ++n) { const f32x4 b = cur[q][2 * bj + n]; const u32x2 qw = pcur[2 * bj + n];
;                         const f32x4 pq = (f32x4){bflo(qw.x), bfhi(qw.x), bflo(qw.y), bfhi(qw.y)}; const f32x4 a = acc[ai][bj][m][n];
; #pragma unroll
;                         for (int j = 0; j < 4; ++j) o2[n][j] = b[j] + pq[j] * sigmoidf_(a[j]); }
;                     *(f32x4*)(h + off + bj * HALF) = o2[0]; *(f32x4*)(h + off + bj * HALF + 4) = o2[1];
;                     if (!LAST) { u32x4 w; w.x = cvt_pk_bf16(o2[0][0], o2[0][1]); w.y = cvt_pk_bf16(o2[0][2], o2[0][3]); w.z = cvt_pk_bf16(o2[1][0], o2[1][1]); w.w = cvt_pk_bf16(o2[1][2], o2[1][3]);
;                         *(u32x4*)(hb + off + bj * HALF) = w; sr += ssq4(o2[0]) + ssq4(o2[1]); } }
	v_lshlrev_b32_e32 v52, 16, v66
	v_and_b32_e32 v53, 0xffff0000, v66
	v_add_f32_e32 v50, 1.0, v50
	v_add_f32_e32 v51, 1.0, v51
	v_rcp_f32_e32 v50, v50
	v_rcp_f32_e32 v51, v51
	s_nop 0
	v_pk_fma_f32 v[42:43], v[50:51], v[52:53], v[42:43]
	v_mul_f32_e32 v50, 0xbfb8aa3b, v196
	v_mul_f32_e32 v51, 0xbfb8aa3b, v197
	v_exp_f32_e32 v50, v50
	v_exp_f32_e32 v51, v51
	v_lshlrev_b32_e32 v52, 16, v67
	v_and_b32_e32 v53, 0xffff0000, v67
	v_add_f32_e32 v50, 1.0, v50
	v_add_f32_e32 v51, 1.0, v51
	v_rcp_f32_e32 v50, v50
	v_rcp_f32_e32 v51, v51
	s_nop 0
	v_pk_fma_f32 v[44:45], v[50:51], v[52:53], v[44:45]
	v_mul_f32_e32 v50, 0xbfb8aa3b, v194
	v_mul_f32_e32 v51, 0xbfb8aa3b, v195
	v_exp_f32_e32 v50, v50
	v_exp_f32_e32 v51, v51
	v_lshlrev_b32_e32 v52, 16, v68
	v_and_b32_e32 v53, 0xffff0000, v68
	v_add_f32_e32 v50, 1.0, v50
	v_add_f32_e32 v51, 1.0, v51
	v_rcp_f32_e32 v50, v50
	v_rcp_f32_e32 v51, v51
	s_nop 0
	v_pk_fma_f32 v[34:35], v[50:51], v[52:53], v[34:35]
	v_mul_f32_e32 v50, 0xbfb8aa3b, v192
	v_mul_f32_e32 v51, 0xbfb8aa3b, v193
	v_exp_f32_e32 v50, v50
	v_exp_f32_e32 v51, v51
	v_lshlrev_b32_e32 v52, 16, v69
	v_and_b32_e32 v53, 0xffff0000, v69
	v_add_f32_e32 v50, 1.0, v50
	v_add_f32_e32 v51, 1.0, v51
	v_rcp_f32_e32 v50, v50
	v_rcp_f32_e32 v51, v51
	s_nop 0
	v_pk_fma_f32 v[36:37], v[50:51], v[52:53], v[36:37]
	global_store_dwordx4 v[74:75], v[42:45], off offset:512 nt
	global_store_dwordx4 v[74:75], v[34:37], off offset:528 nt
	s_nop 1
	v_lshlrev_b64 v[34:35], 12, v[178:179]
	v_lshl_add_u64 v[34:35], s[56:57], 0, v[34:35]
	v_lshl_add_u64 v[34:35], v[34:35], 0, v[128:129]
	global_load_dwordx4 v[74:77], v[34:35], off
	global_load_dwordx4 v[66:69], v[34:35], off offset:256
	v_mul_f32_e32 v34, 0xbfb8aa3b, v190
	v_mul_f32_e32 v35, 0xbfb8aa3b, v191
	v_exp_f32_e32 v34, v34
	v_exp_f32_e32 v35, v35
	s_waitcnt vmcnt(7)
	v_lshlrev_b32_e32 v36, 16, v78
	v_and_b32_e32 v37, 0xffff0000, v78
	v_add_f32_e32 v34, 1.0, v34
	v_add_f32_e32 v35, 1.0, v35
	v_rcp_f32_e32 v34, v34
	v_rcp_f32_e32 v35, v35
	s_nop 0
	v_pk_fma_f32 v[26:27], v[34:35], v[36:37], v[26:27]
	v_mul_f32_e32 v34, 0xbfb8aa3b, v188
	v_mul_f32_e32 v35, 0xbfb8aa3b, v189
	v_exp_f32_e32 v34, v34
	v_exp_f32_e32 v35, v35
	v_lshlrev_b32_e32 v36, 16, v79
	v_and_b32_e32 v37, 0xffff0000, v79
	v_add_f32_e32 v34, 1.0, v34
	v_add_f32_e32 v35, 1.0, v35
	v_rcp_f32_e32 v34, v34
	v_rcp_f32_e32 v35, v35
	s_nop 0
	v_pk_fma_f32 v[28:29], v[34:35], v[36:37], v[28:29]
	v_mul_f32_e32 v34, 0xbfb8aa3b, v176
	v_mul_f32_e32 v35, 0xbfb8aa3b, v177
	v_exp_f32_e32 v34, v34
	v_exp_f32_e32 v35, v35
	v_lshlrev_b32_e32 v36, 16, v80
	v_and_b32_e32 v37, 0xffff0000, v80
	v_add_f32_e32 v34, 1.0, v34
	v_add_f32_e32 v35, 1.0, v35
	v_rcp_f32_e32 v34, v34
	v_rcp_f32_e32 v35, v35
	s_nop 0
	v_pk_fma_f32 v[18:19], v[34:35], v[36:37], v[18:19]
	v_mul_f32_e32 v34, 0xbfb8aa3b, v174
	v_mul_f32_e32 v35, 0xbfb8aa3b, v175
	v_exp_f32_e32 v34, v34
	v_exp_f32_e32 v35, v35
	v_lshlrev_b32_e32 v36, 16, v81
	v_and_b32_e32 v37, 0xffff0000, v81
	v_add_f32_e32 v34, 1.0, v34
	v_add_f32_e32 v35, 1.0, v35
	v_rcp_f32_e32 v34, v34
	v_rcp_f32_e32 v35, v35
	s_nop 0
	v_pk_fma_f32 v[20:21], v[34:35], v[36:37], v[20:21]
	v_lshl_add_u64 v[34:35], s[36:37], 0, v[208:209]
	v_lshl_add_u64 v[34:35], v[34:35], 0, v[98:99]
	global_store_dwordx4 v[34:35], v[26:29], off nt
	global_store_dwordx4 v[34:35], v[18:21], off offset:16 nt
	s_nop 1
	v_mul_f32_e32 v18, 0xbfb8aa3b, v170
	v_mul_f32_e32 v19, 0xbfb8aa3b, v171
	v_exp_f32_e32 v18, v18
	v_exp_f32_e32 v19, v19
	s_waitcnt vmcnt(8)
	v_lshlrev_b32_e32 v20, 16, v70
	v_and_b32_e32 v21, 0xffff0000, v70
	v_add_f32_e32 v18, 1.0, v18
	v_add_f32_e32 v19, 1.0, v19
	v_rcp_f32_e32 v18, v18
	v_rcp_f32_e32 v19, v19
	s_waitcnt vmcnt(3)
	v_lshlrev_b32_e32 v170, 16, v74
	v_pk_fma_f32 v[10:11], v[18:19], v[20:21], v[10:11]
	v_mul_f32_e32 v18, 0xbfb8aa3b, v168
	v_mul_f32_e32 v19, 0xbfb8aa3b, v169
	v_exp_f32_e32 v18, v18
	v_exp_f32_e32 v19, v19
	v_lshlrev_b32_e32 v20, 16, v71
	v_and_b32_e32 v21, 0xffff0000, v71
	v_add_f32_e32 v18, 1.0, v18
	v_add_f32_e32 v19, 1.0, v19
	v_rcp_f32_e32 v18, v18
	v_rcp_f32_e32 v19, v19
	v_and_b32_e32 v171, 0xffff0000, v74
	v_mul_f32_e32 v74, 0xbfb8aa3b, v146
	v_exp_f32_e32 v74, v74
	v_pk_fma_f32 v[12:13], v[18:19], v[20:21], v[12:13]
	v_mul_f32_e32 v18, 0xbfb8aa3b, v152
	v_mul_f32_e32 v19, 0xbfb8aa3b, v153
	v_exp_f32_e32 v18, v18
	v_exp_f32_e32 v19, v19
	v_lshlrev_b32_e32 v20, 16, v72
	v_and_b32_e32 v21, 0xffff0000, v72
	v_add_f32_e32 v18, 1.0, v18
	v_add_f32_e32 v19, 1.0, v19
	v_rcp_f32_e32 v18, v18
	v_rcp_f32_e32 v19, v19
	v_add_u32_e32 v168, 0xa0, v166
	v_add_u32_e32 v166, 0xb0, v166
	v_ashrrev_i32_e32 v169, 31, v168
	v_pk_fma_f32 v[2:3], v[18:19], v[20:21], v[2:3]
	v_mul_f32_e32 v18, 0xbfb8aa3b, v150
	v_mul_f32_e32 v19, 0xbfb8aa3b, v151
	v_exp_f32_e32 v18, v18
	v_exp_f32_e32 v19, v19
	v_lshlrev_b32_e32 v20, 16, v73
	v_and_b32_e32 v21, 0xffff0000, v73
	v_add_f32_e32 v18, 1.0, v18
	v_add_f32_e32 v19, 1.0, v19
	v_rcp_f32_e32 v18, v18
	v_rcp_f32_e32 v19, v19
	v_ashrrev_i32_e32 v167, 31, v166
	v_lshlrev_b64 v[70:71], 12, v[214:215]
	v_add_f32_e32 v74, 1.0, v74
	v_pk_fma_f32 v[4:5], v[18:19], v[20:21], v[4:5]
	global_store_dwordx4 v[34:35], v[10:13], off offset:512 nt
	global_store_dwordx4 v[34:35], v[2:5], off offset:528 nt
	v_lshlrev_b64 v[152:153], 13, v[168:169]
	v_lshlrev_b64 v[150:151], 13, v[166:167]
	v_lshl_add_u64 v[70:71], s[56:57], 0, v[70:71]
	v_rcp_f32_e32 v146, v74
	v_mul_f32_e32 v74, 0xbfb8aa3b, v147
	v_lshl_add_u64 v[2:3], v[172:173], 0, v[152:153]
	v_lshl_add_u64 v[10:11], v[172:173], 0, v[150:151]
	v_lshl_add_u64 v[70:71], v[70:71], 0, v[128:129]
	v_exp_f32_e32 v74, v74
	global_load_dwordx4 v[50:53], v[2:3], off offset:16
; __device__ __forceinline__ float sigmoidf_(float x) { return __builtin_amdgcn_rcpf(1.0f + __expf(-x)); }
; __device__ __forceinline__ float ssq4(const f32x4 o) { return (o[0] * o[0] + o[1] * o[1]) + (o[2] * o[2] + o[3] * o[3]); }
;     __device__ __forceinline__ void operator()(f32x4 (&acc)[2][2][4][2], const Unit& u, int wr, int wc, int fr, int fq) const {
;     ...
;         for (int k = 0; k < 4; ++k) {
;             if (k < 3) {
; #pragma unroll
;                 for (int q = 0; q < 2; ++q)
; #pragma unroll
;                     for (int c = 0; c < 4; ++c) nxt[q][c] = *(const f32x4*)(h + (size_t)EPI_ROW(2 * k + 2 + q) * D + col0 + (c >> 1) * HALF + (c & 1) * 4);
;             }
; #pragma unroll
;             for (int q = 0; q < 2; ++q) { const int r = 2 * k + q, ai = r >> 2, m = r & 3; const size_t off = (size_t)EPI_ROW(r) * D + col0; float sr = 0.f;
;                 if (r < 7) {
; #pragma unroll
;                     for (int c = 0; c < 4; ++c) pnxt[c] = *(const u32x2*)(pp + (size_t)EPI_ROW(r + 1) * D + col0 + (c >> 1) * HALF + (c & 1) * 4);
;                 }
;                 asm volatile("" ::: "memory");
; #pragma unroll
;                 for (int bj = 0; bj < 2; ++bj) { f32x4 o2[2];
; #pragma unroll
;                     for (int n = 0; n < 2; ++n) { const f32x4 b = cur[q][2 * bj + n]; const u32x2 qw = pcur[2 * bj + n];
;                         const f32x4 pq = (f32x4){bflo(qw.x), bfhi(qw.x), bflo(qw.y), bfhi(qw.y)}; const f32x4 a = acc[ai][bj][m][n];
; #pragma unroll
;                         for (int j = 0; j < 4; ++j) o2[n][j] = b[j] + pq[j] * sigmoidf_(a[j]); }
;                     *(f32x4*)(h + off + bj * HALF) = o2[0]; *(f32x4*)(h + off + bj * HALF + 4) = o2[1];
;                     if (!LAST) { u32x4 w; w.x = cvt_pk_bf16(o2[0][0], o2[0][1]); w.y = cvt_pk_bf16(o2[0][2], o2[0][3]); w.z = cvt_pk_bf16(o2[1][0], o2[1][1]); w.w = cvt_pk_bf16(o2[1][2], o2[1][3]);
;                         *(u32x4*)(hb + off + bj * HALF) = w; sr += ssq4(o2[0]) + ssq4(o2[1]); } }
	global_load_dwordx4 v[58:61], v[2:3], off
	global_load_dwordx4 v[34:37], v[2:3], off offset:528
	global_load_dwordx4 v[42:45], v[2:3], off offset:512
	global_load_dwordx4 v[18:21], v[10:11], off offset:16
	global_load_dwordx4 v[26:29], v[10:11], off
	s_nop 0
	global_load_dwordx4 v[2:5], v[10:11], off offset:528
	s_nop 0
	global_load_dwordx4 v[10:13], v[10:11], off offset:512
	s_nop 0
	global_load_dwordx4 v[78:81], v[70:71], off
	s_nop 0
	global_load_dwordx4 v[70:73], v[70:71], off offset:256
	v_add_f32_e32 v74, 1.0, v74
	v_rcp_f32_e32 v147, v74
	v_lshlrev_b32_e32 v74, 16, v75
	v_and_b32_e32 v75, 0xffff0000, v75
	v_pk_fma_f32 v[62:63], v[148:149], v[170:171], v[62:63]
	v_pk_fma_f32 v[64:65], v[146:147], v[74:75], v[64:65]
	v_mul_f32_e32 v74, 0xbfb8aa3b, v144
	v_mul_f32_e32 v75, 0xbfb8aa3b, v145
	v_exp_f32_e32 v74, v74
	v_exp_f32_e32 v75, v75
	v_lshlrev_b32_e32 v144, 16, v76
	v_and_b32_e32 v145, 0xffff0000, v76
	v_add_f32_e32 v74, 1.0, v74
	v_add_f32_e32 v75, 1.0, v75
	v_rcp_f32_e32 v74, v74
	v_rcp_f32_e32 v75, v75
	v_lshlrev_b32_e32 v76, 16, v77
	v_and_b32_e32 v77, 0xffff0000, v77
	v_pk_fma_f32 v[54:55], v[74:75], v[144:145], v[54:55]
	v_mul_f32_e32 v74, 0xbfb8aa3b, v142
	v_mul_f32_e32 v75, 0xbfb8aa3b, v143
	v_exp_f32_e32 v74, v74
	v_exp_f32_e32 v75, v75
	v_add_f32_e32 v74, 1.0, v74
	v_add_f32_e32 v75, 1.0, v75
	v_rcp_f32_e32 v74, v74
	v_rcp_f32_e32 v75, v75
	s_nop 0
	v_pk_fma_f32 v[56:57], v[74:75], v[76:77], v[56:57]
	v_lshl_add_u64 v[74:75], s[36:37], 0, v[212:213]
	v_lshl_add_u64 v[74:75], v[74:75], 0, v[98:99]
	global_store_dwordx4 v[74:75], v[62:65], off nt
	global_store_dwordx4 v[74:75], v[54:57], off offset:16 nt
	s_nop 1
	v_mul_f32_e32 v54, 0xbfb8aa3b, v140
	v_mul_f32_e32 v55, 0xbfb8aa3b, v141
	v_exp_f32_e32 v54, v54
	v_exp_f32_e32 v55, v55
	s_waitcnt vmcnt(16)
	v_lshlrev_b32_e32 v56, 16, v66
	v_and_b32_e32 v57, 0xffff0000, v66
	v_add_f32_e32 v54, 1.0, v54
	v_add_f32_e32 v55, 1.0, v55
	v_rcp_f32_e32 v54, v54
	v_rcp_f32_e32 v55, v55
	s_nop 0
	v_pk_fma_f32 v[46:47], v[54:55], v[56:57], v[46:47]
	v_mul_f32_e32 v54, 0xbfb8aa3b, v138
	v_mul_f32_e32 v55, 0xbfb8aa3b, v139
	v_exp_f32_e32 v54, v54
	v_exp_f32_e32 v55, v55
	v_lshlrev_b32_e32 v56, 16, v67
	v_and_b32_e32 v57, 0xffff0000, v67
	v_add_f32_e32 v54, 1.0, v54
	v_add_f32_e32 v55, 1.0, v55
	v_rcp_f32_e32 v54, v54
	v_rcp_f32_e32 v55, v55
	s_nop 0
	v_pk_fma_f32 v[48:49], v[54:55], v[56:57], v[48:49]
	v_mul_f32_e32 v54, 0xbfb8aa3b, v136
	v_mul_f32_e32 v55, 0xbfb8aa3b, v137
	v_exp_f32_e32 v54, v54
	v_exp_f32_e32 v55, v55
	v_lshlrev_b32_e32 v56, 16, v68
	v_and_b32_e32 v57, 0xffff0000, v68
	v_add_f32_e32 v54, 1.0, v54
	v_add_f32_e32 v55, 1.0, v55
	v_rcp_f32_e32 v54, v54
	v_rcp_f32_e32 v55, v55
	s_nop 0
	v_pk_fma_f32 v[38:39], v[54:55], v[56:57], v[38:39]
	v_mul_f32_e32 v54, 0xbfb8aa3b, v134
	v_mul_f32_e32 v55, 0xbfb8aa3b, v135
	v_exp_f32_e32 v54, v54
	v_exp_f32_e32 v55, v55
	v_lshlrev_b32_e32 v56, 16, v69
	v_and_b32_e32 v57, 0xffff0000, v69
	v_add_f32_e32 v54, 1.0, v54
	v_add_f32_e32 v55, 1.0, v55
	v_rcp_f32_e32 v54, v54
	v_rcp_f32_e32 v55, v55
	s_nop 0
	v_pk_fma_f32 v[40:41], v[54:55], v[56:57], v[40:41]
	v_mul_f32_e32 v54, 0xbfb8aa3b, v132
	v_mul_f32_e32 v55, 0xbfb8aa3b, v133
	v_exp_f32_e32 v54, v54
	v_exp_f32_e32 v55, v55
	global_store_dwordx4 v[74:75], v[46:49], off offset:512 nt
	global_store_dwordx4 v[74:75], v[38:41], off offset:528 nt
	s_waitcnt vmcnt(5)
	v_lshlrev_b32_e32 v56, 16, v78
	v_add_f32_e32 v54, 1.0, v54
	v_add_f32_e32 v55, 1.0, v55
	v_rcp_f32_e32 v54, v54
	v_rcp_f32_e32 v55, v55
	v_lshlrev_b64 v[38:39], 12, v[168:169]
	v_and_b32_e32 v57, 0xffff0000, v78
	v_lshl_add_u64 v[38:39], s[56:57], 0, v[38:39]
	v_pk_fma_f32 v[30:31], v[54:55], v[56:57], v[30:31]
	v_mul_f32_e32 v54, 0xbfb8aa3b, v130
	v_mul_f32_e32 v55, 0xbfb8aa3b, v131
	v_lshl_add_u64 v[38:39], v[38:39], 0, v[128:129]
	v_exp_f32_e32 v54, v54
	v_exp_f32_e32 v55, v55
	global_load_dwordx4 v[46:49], v[38:39], off
	s_nop 0
	global_load_dwordx4 v[38:41], v[38:39], off offset:256
	v_lshlrev_b32_e32 v56, 16, v79
	v_add_f32_e32 v54, 1.0, v54
	v_add_f32_e32 v55, 1.0, v55
	v_rcp_f32_e32 v54, v54
	v_rcp_f32_e32 v55, v55
	v_and_b32_e32 v57, 0xffff0000, v79
	v_pk_fma_f32 v[32:33], v[54:55], v[56:57], v[32:33]
	v_mul_f32_e32 v54, 0xbfb8aa3b, v126
	v_mul_f32_e32 v55, 0xbfb8aa3b, v127
	v_exp_f32_e32 v54, v54
	v_exp_f32_e32 v55, v55
	v_lshlrev_b32_e32 v56, 16, v80
	v_and_b32_e32 v57, 0xffff0000, v80
	v_add_f32_e32 v54, 1.0, v54
	v_add_f32_e32 v55, 1.0, v55
	v_rcp_f32_e32 v54, v54
	v_rcp_f32_e32 v55, v55
	s_nop 0
	v_pk_fma_f32 v[22:23], v[54:55], v[56:57], v[22:23]
	v_mul_f32_e32 v54, 0xbfb8aa3b, v124
	v_mul_f32_e32 v55, 0xbfb8aa3b, v125
	v_exp_f32_e32 v54, v54
	v_exp_f32_e32 v55, v55
	v_lshlrev_b32_e32 v56, 16, v81
	v_and_b32_e32 v57, 0xffff0000, v81
	v_add_f32_e32 v54, 1.0, v54
	v_add_f32_e32 v55, 1.0, v55
	v_rcp_f32_e32 v54, v54
	v_rcp_f32_e32 v55, v55
	s_nop 0
	v_pk_fma_f32 v[24:25], v[54:55], v[56:57], v[24:25]
	v_lshl_add_u64 v[54:55], s[36:37], 0, v[210:211]
	v_lshl_add_u64 v[54:55], v[54:55], 0, v[98:99]
	global_store_dwordx4 v[54:55], v[30:33], off nt
	global_store_dwordx4 v[54:55], v[22:25], off offset:16 nt
	s_waitcnt vmcnt(3)
; __device__ __forceinline__ float sigmoidf_(float x) { return __builtin_amdgcn_rcpf(1.0f + __expf(-x)); }
; __device__ __forceinline__ float ssq4(const f32x4 o) { return (o[0] * o[0] + o[1] * o[1]) + (o[2] * o[2] + o[3] * o[3]); }
;     __device__ __forceinline__ void operator()(f32x4 (&acc)[2][2][4][2], const Unit& u, int wr, int wc, int fr, int fq) const {
;     ...
;         for (int k = 0; k < 4; ++k) {
;             if (k < 3) {
; #pragma unroll
;                 for (int q = 0; q < 2; ++q)
; #pragma unroll
;                     for (int c = 0; c < 4; ++c) nxt[q][c] = *(const f32x4*)(h + (size_t)EPI_ROW(2 * k + 2 + q) * D + col0 + (c >> 1) * HALF + (c & 1) * 4);
;             }
; #pragma unroll
;             for (int q = 0; q < 2; ++q) { const int r = 2 * k + q, ai = r >> 2, m = r & 3; const size_t off = (size_t)EPI_ROW(r) * D + col0; float sr = 0.f;
;                 if (r < 7) {
; #pragma unroll
;                     for (int c = 0; c < 4; ++c) pnxt[c] = *(const u32x2*)(pp + (size_t)EPI_ROW(r + 1) * D + col0 + (c >> 1) * HALF + (c & 1) * 4);
;                 }
;                 asm volatile("" ::: "memory");
; #pragma unroll
;                 for (int bj = 0; bj < 2; ++bj) { f32x4 o2[2];
; #pragma unroll
;                     for (int n = 0; n < 2; ++n) { const f32x4 b = cur[q][2 * bj + n]; const u32x2 qw = pcur[2 * bj + n];
;                         const f32x4 pq = (f32x4){bflo(qw.x), bfhi(qw.x), bflo(qw.y), bfhi(qw.y)}; const f32x4 a = acc[ai][bj][m][n];
; #pragma unroll
;                         for (int j = 0; j < 4; ++j) o2[n][j] = b[j] + pq[j] * sigmoidf_(a[j]); }
;                     *(f32x4*)(h + off + bj * HALF) = o2[0]; *(f32x4*)(h + off + bj * HALF + 4) = o2[1];
;                     if (!LAST) { u32x4 w; w.x = cvt_pk_bf16(o2[0][0], o2[0][1]); w.y = cvt_pk_bf16(o2[0][2], o2[0][3]); w.z = cvt_pk_bf16(o2[1][0], o2[1][1]); w.w = cvt_pk_bf16(o2[1][2], o2[1][3]);
;                         *(u32x4*)(hb + off + bj * HALF) = w; sr += ssq4(o2[0]) + ssq4(o2[1]); } }
	v_lshlrev_b32_e32 v30, 16, v47
	v_mul_f32_e32 v22, 0xbfb8aa3b, v122
	v_mul_f32_e32 v23, 0xbfb8aa3b, v123
	v_exp_f32_e32 v22, v22
	v_exp_f32_e32 v23, v23
	v_lshlrev_b32_e32 v24, 16, v70
	v_and_b32_e32 v25, 0xffff0000, v70
	v_add_f32_e32 v22, 1.0, v22
	v_add_f32_e32 v23, 1.0, v23
	v_rcp_f32_e32 v22, v22
	v_rcp_f32_e32 v23, v23
	v_and_b32_e32 v31, 0xffff0000, v47
	v_lshlrev_b32_e32 v32, 16, v48
	v_and_b32_e32 v33, 0xffff0000, v48
	v_pk_fma_f32 v[14:15], v[22:23], v[24:25], v[14:15]
	v_mul_f32_e32 v22, 0xbfb8aa3b, v120
	v_mul_f32_e32 v23, 0xbfb8aa3b, v121
	v_exp_f32_e32 v22, v22
	v_exp_f32_e32 v23, v23
	v_lshlrev_b32_e32 v24, 16, v71
	v_and_b32_e32 v25, 0xffff0000, v71
	v_add_f32_e32 v22, 1.0, v22
	v_add_f32_e32 v23, 1.0, v23
	v_rcp_f32_e32 v22, v22
	v_rcp_f32_e32 v23, v23
	v_and_b32_e32 v47, 0xffff0000, v49
	v_pk_fma_f32 v[16:17], v[22:23], v[24:25], v[16:17]
	v_mul_f32_e32 v22, 0xbfb8aa3b, v118
	v_mul_f32_e32 v23, 0xbfb8aa3b, v119
	v_exp_f32_e32 v22, v22
	v_exp_f32_e32 v23, v23
	v_lshlrev_b32_e32 v24, 16, v72
	v_and_b32_e32 v25, 0xffff0000, v72
	v_add_f32_e32 v22, 1.0, v22
	v_add_f32_e32 v23, 1.0, v23
	v_rcp_f32_e32 v22, v22
	v_rcp_f32_e32 v23, v23
	s_nop 0
	v_pk_fma_f32 v[6:7], v[22:23], v[24:25], v[6:7]
	v_mul_f32_e32 v22, 0xbfb8aa3b, v116
	v_mul_f32_e32 v23, 0xbfb8aa3b, v117
	v_exp_f32_e32 v22, v22
	v_exp_f32_e32 v23, v23
	v_lshlrev_b32_e32 v24, 16, v73
	v_and_b32_e32 v25, 0xffff0000, v73
	v_add_f32_e32 v22, 1.0, v22
	v_add_f32_e32 v23, 1.0, v23
	v_rcp_f32_e32 v22, v22
	v_rcp_f32_e32 v23, v23
	s_nop 0
	v_pk_fma_f32 v[8:9], v[22:23], v[24:25], v[8:9]
	v_mul_f32_e32 v22, 0xbfb8aa3b, v114
	v_mul_f32_e32 v23, 0xbfb8aa3b, v115
	v_exp_f32_e32 v22, v22
	v_exp_f32_e32 v23, v23
	global_store_dwordx4 v[54:55], v[14:17], off offset:512 nt
	global_store_dwordx4 v[54:55], v[6:9], off offset:528 nt
	v_add_f32_e32 v22, 1.0, v22
	v_add_f32_e32 v23, 1.0, v23
	v_lshlrev_b64 v[6:7], 12, v[166:167]
	v_lshl_add_u64 v[6:7], s[56:57], 0, v[6:7]
	v_lshl_add_u64 v[6:7], v[6:7], 0, v[128:129]
	v_rcp_f32_e32 v22, v22
	v_rcp_f32_e32 v23, v23
	global_load_dwordx4 v[14:17], v[6:7], off
	s_nop 0
	global_load_dwordx4 v[6:9], v[6:7], off offset:256
	v_lshlrev_b32_e32 v24, 16, v46
	v_and_b32_e32 v25, 0xffff0000, v46
	v_pk_fma_f32 v[22:23], v[22:23], v[24:25], v[58:59]
	v_mul_f32_e32 v24, 0xbfb8aa3b, v112
	v_mul_f32_e32 v25, 0xbfb8aa3b, v113
	v_exp_f32_e32 v24, v24
	v_exp_f32_e32 v25, v25
	v_lshlrev_b32_e32 v46, 16, v49
	v_add_f32_e32 v24, 1.0, v24
	v_add_f32_e32 v25, 1.0, v25
	v_rcp_f32_e32 v24, v24
	v_rcp_f32_e32 v25, v25
	s_nop 0
	v_pk_fma_f32 v[24:25], v[24:25], v[30:31], v[60:61]
	v_mul_f32_e32 v30, 0xbfb8aa3b, v110
	v_mul_f32_e32 v31, 0xbfb8aa3b, v111
	v_exp_f32_e32 v30, v30
	v_exp_f32_e32 v31, v31
	v_add_f32_e32 v30, 1.0, v30
	v_add_f32_e32 v31, 1.0, v31
	v_rcp_f32_e32 v30, v30
	v_rcp_f32_e32 v31, v31
	s_nop 0
	v_pk_fma_f32 v[30:31], v[30:31], v[32:33], v[50:51]
	v_mul_f32_e32 v32, 0xbfb8aa3b, v108
	v_mul_f32_e32 v33, 0xbfb8aa3b, v109
	v_exp_f32_e32 v32, v32
	v_exp_f32_e32 v33, v33
	v_add_f32_e32 v32, 1.0, v32
	v_add_f32_e32 v33, 1.0, v33
	v_rcp_f32_e32 v32, v32
	v_rcp_f32_e32 v33, v33
	s_nop 0
	v_pk_fma_f32 v[32:33], v[32:33], v[46:47], v[52:53]
	v_lshl_add_u64 v[46:47], s[36:37], 0, v[152:153]
	v_lshl_add_u64 v[46:47], v[46:47], 0, v[98:99]
	global_store_dwordx4 v[46:47], v[22:25], off nt
	global_store_dwordx4 v[46:47], v[30:33], off offset:16 nt
	s_nop 0
	v_mul_f32_e32 v22, 0xbfb8aa3b, v106
	v_mul_f32_e32 v23, 0xbfb8aa3b, v107
	v_exp_f32_e32 v22, v22
	v_exp_f32_e32 v23, v23
	s_waitcnt vmcnt(8)
; __device__ __forceinline__ float sigmoidf_(float x) { return __builtin_amdgcn_rcpf(1.0f + __expf(-x)); }
; __device__ __forceinline__ float ssq4(const f32x4 o) { return (o[0] * o[0] + o[1] * o[1]) + (o[2] * o[2] + o[3] * o[3]); }
; #define PG8_BAR __builtin_amdgcn_s_barrier()
;     __device__ __forceinline__ void operator()(f32x4 (&acc)[2][2][4][2], const Unit& u, int wr, int wc, int fr, int fq) const {
;     ...
;             for (int q = 0; q < 2; ++q) { const int r = 2 * k + q, ai = r >> 2, m = r & 3; const size_t off = (size_t)EPI_ROW(r) * D + col0; float sr = 0.f;
;                 if (r < 7) {
; #pragma unroll
;                     for (int c = 0; c < 4; ++c) pnxt[c] = *(const u32x2*)(pp + (size_t)EPI_ROW(r + 1) * D + col0 + (c >> 1) * HALF + (c & 1) * 4);
;                 }
;                 asm volatile("" ::: "memory");
; #pragma unroll
;                 for (int bj = 0; bj < 2; ++bj) { f32x4 o2[2];
; #pragma unroll
;                     for (int n = 0; n < 2; ++n) { const f32x4 b = cur[q][2 * bj + n]; const u32x2 qw = pcur[2 * bj + n];
;                         const f32x4 pq = (f32x4){bflo(qw.x), bfhi(qw.x), bflo(qw.y), bfhi(qw.y)}; const f32x4 a = acc[ai][bj][m][n];
; #pragma unroll
;                         for (int j = 0; j < 4; ++j) o2[n][j] = b[j] + pq[j] * sigmoidf_(a[j]); }
;                     *(f32x4*)(h + off + bj * HALF) = o2[0]; *(f32x4*)(h + off + bj * HALF + 4) = o2[1];
;                     if (!LAST) { u32x4 w; w.x = cvt_pk_bf16(o2[0][0], o2[0][1]); w.y = cvt_pk_bf16(o2[0][2], o2[0][3]); w.z = cvt_pk_bf16(o2[1][0], o2[1][1]); w.w = cvt_pk_bf16(o2[1][2], o2[1][3]);
;                         *(u32x4*)(hb + off + bj * HALF) = w; sr += ssq4(o2[0]) + ssq4(o2[1]); } }
; template <class Epi>
; __device__ __forceinline__ void gemm_phase(LAS unsigned char* lds, const Gemm g, const StaticOrder& S, const Epi& E) {
;     ...
;         if (!has_next) break;
; #pragma unroll
;         for (int a = 0; a < 2; ++a)
; #pragma unroll
;             for (int b = 0; b < 2; ++b)
; #pragma unroll
;                 for (int m = 0; m < 4; ++m)
; #pragma unroll
;                     for (int n = 0; n < 2; ++n) acc[a][b][m][n] = (f32x4){0.f, 0.f, 0.f, 0.f};
;         cur = nxt; cA = nA; cB = nB; ++ui;
;         if (wr == 1) PG8_BAR;
	v_lshlrev_b32_e32 v24, 16, v38
	v_and_b32_e32 v25, 0xffff0000, v38
	v_add_f32_e32 v22, 1.0, v22
	v_add_f32_e32 v23, 1.0, v23
	v_rcp_f32_e32 v22, v22
	v_rcp_f32_e32 v23, v23
	v_lshlrev_b32_e32 v30, 16, v39
	v_and_b32_e32 v31, 0xffff0000, v39
	v_lshlrev_b32_e32 v32, 16, v40
	v_pk_fma_f32 v[22:23], v[22:23], v[24:25], v[42:43]
	v_mul_f32_e32 v24, 0xbfb8aa3b, v104
	v_mul_f32_e32 v25, 0xbfb8aa3b, v105
	v_exp_f32_e32 v24, v24
	v_exp_f32_e32 v25, v25
	v_and_b32_e32 v33, 0xffff0000, v40
	v_add_f32_e32 v24, 1.0, v24
	v_add_f32_e32 v25, 1.0, v25
	v_rcp_f32_e32 v24, v24
	v_rcp_f32_e32 v25, v25
	s_nop 0
	v_pk_fma_f32 v[24:25], v[24:25], v[30:31], v[44:45]
	v_mul_f32_e32 v30, 0xbfb8aa3b, v102
	v_mul_f32_e32 v31, 0xbfb8aa3b, v103
	v_exp_f32_e32 v30, v30
	v_exp_f32_e32 v31, v31
	v_add_f32_e32 v30, 1.0, v30
	v_add_f32_e32 v31, 1.0, v31
	v_rcp_f32_e32 v30, v30
	v_rcp_f32_e32 v31, v31
	s_nop 0
	v_pk_fma_f32 v[30:31], v[30:31], v[32:33], v[34:35]
	v_mul_f32_e32 v32, 0xbfb8aa3b, v100
	v_mul_f32_e32 v33, 0xbfb8aa3b, v101
	v_exp_f32_e32 v32, v32
	v_exp_f32_e32 v33, v33
	v_lshlrev_b32_e32 v34, 16, v41
	v_and_b32_e32 v35, 0xffff0000, v41
	v_add_f32_e32 v32, 1.0, v32
	v_add_f32_e32 v33, 1.0, v33
	v_rcp_f32_e32 v32, v32
	v_rcp_f32_e32 v33, v33
	s_nop 0
	v_pk_fma_f32 v[32:33], v[32:33], v[34:35], v[36:37]
	global_store_dwordx4 v[46:47], v[22:25], off offset:512 nt
	global_store_dwordx4 v[46:47], v[30:33], off offset:528 nt
	s_nop 0
	v_mul_f32_e32 v22, 0xbfb8aa3b, v96
	v_mul_f32_e32 v23, 0xbfb8aa3b, v97
	v_exp_f32_e32 v22, v22
	v_exp_f32_e32 v23, v23
	s_waitcnt vmcnt(5)
	v_lshlrev_b32_e32 v24, 16, v14
	v_and_b32_e32 v25, 0xffff0000, v14
	v_mul_f32_e32 v14, 0xbfb8aa3b, v94
	v_add_f32_e32 v22, 1.0, v22
	v_add_f32_e32 v23, 1.0, v23
	v_exp_f32_e32 v14, v14
	v_rcp_f32_e32 v22, v22
	v_rcp_f32_e32 v23, v23
	v_add_f32_e32 v14, 1.0, v14
	v_pk_fma_f32 v[22:23], v[22:23], v[24:25], v[26:27]
	v_rcp_f32_e32 v24, v14
	v_mul_f32_e32 v14, 0xbfb8aa3b, v95
	v_exp_f32_e32 v14, v14
	v_lshlrev_b32_e32 v26, 16, v16
	v_and_b32_e32 v27, 0xffff0000, v16
	v_mul_f32_e32 v16, 0xbfb8aa3b, v90
	v_add_f32_e32 v14, 1.0, v14
	v_rcp_f32_e32 v25, v14
	v_lshlrev_b32_e32 v14, 16, v15
	v_and_b32_e32 v15, 0xffff0000, v15
	v_exp_f32_e32 v16, v16
	v_pk_fma_f32 v[24:25], v[24:25], v[14:15], v[28:29]
	v_mul_f32_e32 v14, 0xbfb8aa3b, v92
	v_mul_f32_e32 v15, 0xbfb8aa3b, v93
	v_exp_f32_e32 v14, v14
	v_exp_f32_e32 v15, v15
	v_add_f32_e32 v16, 1.0, v16
	v_add_f32_e32 v14, 1.0, v14
	v_add_f32_e32 v15, 1.0, v15
	v_rcp_f32_e32 v14, v14
	v_rcp_f32_e32 v15, v15
	s_nop 0
	v_pk_fma_f32 v[14:15], v[14:15], v[26:27], v[18:19]
	v_rcp_f32_e32 v18, v16
	v_mul_f32_e32 v16, 0xbfb8aa3b, v91
	v_exp_f32_e32 v16, v16
	s_nop 0
	v_add_f32_e32 v16, 1.0, v16
	v_rcp_f32_e32 v19, v16
	v_lshlrev_b32_e32 v16, 16, v17
	v_and_b32_e32 v17, 0xffff0000, v17
	v_pk_fma_f32 v[16:17], v[18:19], v[16:17], v[20:21]
	v_lshl_add_u64 v[18:19], s[36:37], 0, v[150:151]
	v_lshl_add_u64 v[18:19], v[18:19], 0, v[98:99]
	global_store_dwordx4 v[18:19], v[22:25], off nt
	global_store_dwordx4 v[18:19], v[14:17], off offset:16 nt
	s_nop 1
	v_mul_f32_e32 v14, 0xbfb8aa3b, v88
	v_mul_f32_e32 v15, 0xbfb8aa3b, v89
	v_exp_f32_e32 v14, v14
	v_exp_f32_e32 v15, v15
	s_waitcnt vmcnt(6)
	v_lshlrev_b32_e32 v16, 16, v6
	v_and_b32_e32 v17, 0xffff0000, v6
	v_mul_f32_e32 v6, 0xbfb8aa3b, v86
	v_add_f32_e32 v14, 1.0, v14
	v_add_f32_e32 v15, 1.0, v15
	v_exp_f32_e32 v6, v6
	v_rcp_f32_e32 v14, v14
	v_rcp_f32_e32 v15, v15
	v_add_f32_e32 v6, 1.0, v6
	v_pk_fma_f32 v[10:11], v[14:15], v[16:17], v[10:11]
	v_rcp_f32_e32 v14, v6
	v_mul_f32_e32 v6, 0xbfb8aa3b, v87
	v_exp_f32_e32 v6, v6
	s_nop 0
	v_add_f32_e32 v6, 1.0, v6
	v_rcp_f32_e32 v15, v6
	v_lshlrev_b32_e32 v6, 16, v7
	v_and_b32_e32 v7, 0xffff0000, v7
	v_pk_fma_f32 v[12:13], v[14:15], v[6:7], v[12:13]
	v_mul_f32_e32 v6, 0xbfb8aa3b, v84
	v_mul_f32_e32 v7, 0xbfb8aa3b, v85
	v_exp_f32_e32 v6, v6
	v_exp_f32_e32 v7, v7
	v_lshlrev_b32_e32 v14, 16, v8
	v_and_b32_e32 v15, 0xffff0000, v8
	v_add_f32_e32 v6, 1.0, v6
	v_add_f32_e32 v7, 1.0, v7
	v_rcp_f32_e32 v6, v6
	v_rcp_f32_e32 v7, v7
	v_lshlrev_b32_e32 v8, 16, v9
	v_and_b32_e32 v9, 0xffff0000, v9
	v_pk_fma_f32 v[2:3], v[6:7], v[14:15], v[2:3]
	v_mul_f32_e32 v6, 0xbfb8aa3b, v82
	v_mul_f32_e32 v7, 0xbfb8aa3b, v83
	v_exp_f32_e32 v6, v6
	v_exp_f32_e32 v7, v7
	v_add_f32_e32 v6, 1.0, v6
	v_add_f32_e32 v7, 1.0, v7
	v_rcp_f32_e32 v6, v6
	v_rcp_f32_e32 v7, v7
	s_nop 0
	v_pk_fma_f32 v[4:5], v[6:7], v[8:9], v[4:5]
	global_store_dwordx4 v[18:19], v[10:13], off offset:512 nt
	global_store_dwordx4 v[18:19], v[2:5], off offset:528 nt
	s_cbranch_vccnz .LBB0_2368
	s_andn2_b64 vcc, exec, s[0:1]
	s_cbranch_vccnz .LBB0_2367
	s_barrier
	s_branch .LBB0_2367
